# v17 + per-segment s_setprio flips removed from the eight GEMM K-loops
# speedup vs baseline: 1.0332x; 1.0032x over previous
; #define PG8_STAGE(bufoff, gbase, voff) do { _Pragma("unroll") for (int _i = 0; _i < 2; ++_i) \
;         __builtin_amdgcn_global_load_lds((const unsigned*)((const char*)(gbase) + (voff)[_i]), (PG8_LAS unsigned*)(lds + (bufoff) + ldsw + _i * 8192), 16, 0, 0); } while (0)
; #define PG8_LDA(dst, b, h) do { _Pragma("unroll") for (int m = 0; m < 4; ++m) _Pragma("unroll") for (int k = 0; k < 2; ++k) dst[m][k] = *(const PG8_LAS bf16x8*)(lds + PG8_SA(b, h) + aoff + m * 2048 + k * 1024); } while (0)
; #define PG8_LDB(dst, b, h) do { _Pragma("unroll") for (int n = 0; n < 2; ++n) _Pragma("unroll") for (int k = 0; k < 2; ++k) dst[n][k] = *(const PG8_LAS bf16x8*)(lds + PG8_SB(b, h) + boff + n * 2048 + k * 1024); } while (0)
; #define PG8_MMA(ai, bj, At, Bt) do { __builtin_amdgcn_s_setprio(1); _Pragma("unroll") for (int m = 0; m < 4; ++m) _Pragma("unroll") for (int n = 0; n < 2; ++n) _Pragma("unroll") for (int k = 0; k < 2; ++k) \
;         acc[ai][bj][m][n] = __builtin_amdgcn_mfma_f32_16x16x32_bf16(Bt[n][k], At[m][k], acc[ai][bj][m][n], 0, 0, 0); __builtin_amdgcn_s_setprio(0); } while (0)
; #define PG8_WAIT_V(n) asm volatile("s_waitcnt vmcnt(" #n ")" ::: "memory")
; #define PG8_WAIT_L(n) asm volatile("s_waitcnt lgkmcnt(" #n ")" ::: "memory")
; #define PG8_BAR __builtin_amdgcn_s_barrier()
; #define PG8_SCHED __builtin_amdgcn_sched_barrier(0)
; template <class Epi, class Sched, bool ALIGN_EPI = false, bool SP2 = false>
; __device__ __forceinline__ void gemm_phase(PG8_LAS unsigned char* lds, const Gemm g, const Sched& S, const Epi& E) {
;     ...
;             PG8_LDB(B0, 0, 0); PG8_LDB(B1, 0, 1); PG8_SCHED; PG8_LDA(At, 0, 0); PG8_STAGE(PG8_SA(1, 1), a1 + hstep, voffA);
;             PG8_WAIT_V(8); PG8_WAIT_L(0); PG8_BAR; PG8_MMA(0, 0, At, B0); PG8_MMA(0, 1, At, B1); PG8_BAR; PG8_SCHED;
;             PG8_LDA(At, 0, 1); PG8_STAGE(PG8_SB(0, 0), b2, voffB); PG8_STAGE(PG8_SB(0, 1), b2 + hstep, voffB); PG8_STAGE(PG8_SA(0, 0), a2, voffA);
;             PG8_WAIT_V(8); PG8_WAIT_L(0); PG8_BAR; PG8_MMA(1, 0, At, B0); PG8_MMA(1, 1, At, B1); PG8_BAR; PG8_SCHED;
.LBB0_218:
	s_add_u32 s0, s6, 0xfffc0080
	s_addc_u32 s1, s7, -1
	s_add_i32 s60, 0, 0x10000
	s_cmp_eq_u32 s35, 12
	s_cselect_b32 s25, s15, s1
	s_cselect_b32 s24, s29, s0
	s_cselect_b32 s1, s13, s23
	s_cselect_b32 s0, s63, s22
	s_add_i32 s64, 0, 0x14000
	v_add_u32_e32 v100, s60, v181
	v_add_u32_e32 v186, s64, v181
	ds_read_b128 v[84:87], v100
	ds_read_b128 v[88:91], v100 offset:1024
	ds_read_b128 v[92:95], v100 offset:2048
	ds_read_b128 v[100:103], v100 offset:3072
	ds_read_b128 v[172:175], v186
	ds_read_b128 v[176:179], v186 offset:1024
	ds_read_b128 v[190:193], v186 offset:2048
	ds_read_b128 v[194:197], v186 offset:3072
	v_lshl_add_u64 v[240:241], s[6:7], 0, v[168:169]
	s_add_i32 m0, s54, 0xc000
	ds_read_b128 v[198:201], v183
	ds_read_b128 v[202:205], v183 offset:1024
	ds_read_b128 v[206:209], v183 offset:2048
	ds_read_b128 v[220:223], v183 offset:3072
	ds_read_b128 v[224:227], v183 offset:4096
	ds_read_b128 v[228:231], v183 offset:5120
	ds_read_b128 v[232:235], v183 offset:6144
	ds_read_b128 v[236:239], v183 offset:7168
	global_load_lds_dwordx4 v[240:241], off
	v_lshl_add_u64 v[240:241], s[6:7], 0, v[170:171]
	s_add_i32 m0, s54, 0xe000
	s_nop 0
	global_load_lds_dwordx4 v[240:241], off
	s_waitcnt vmcnt(8)
	s_waitcnt lgkmcnt(0)
	s_barrier
	s_waitcnt lgkmcnt(0)
	v_mfma_f32_16x16x32_bf16 v[160:163], v[84:87], v[198:201], v[160:163]
	v_mfma_f32_16x16x32_bf16 v[156:159], v[92:95], v[198:201], v[156:159]
	v_mfma_f32_16x16x32_bf16 v[144:147], v[84:87], v[206:209], v[144:147]
	v_mfma_f32_16x16x32_bf16 v[140:143], v[92:95], v[206:209], v[140:143]
	v_mfma_f32_16x16x32_bf16 v[128:131], v[84:87], v[224:227], v[128:131]
	v_mfma_f32_16x16x32_bf16 v[124:127], v[92:95], v[224:227], v[124:127]
	v_mfma_f32_16x16x32_bf16 v[112:115], v[84:87], v[232:235], v[112:115]
	v_mfma_f32_16x16x32_bf16 v[108:111], v[92:95], v[232:235], v[108:111]
	v_mfma_f32_16x16x32_bf16 v[160:163], v[88:91], v[202:205], v[160:163]
	v_mfma_f32_16x16x32_bf16 v[156:159], v[100:103], v[202:205], v[156:159]
	v_mfma_f32_16x16x32_bf16 v[144:147], v[88:91], v[220:223], v[144:147]
	v_mfma_f32_16x16x32_bf16 v[140:143], v[100:103], v[220:223], v[140:143]
	v_mfma_f32_16x16x32_bf16 v[128:131], v[88:91], v[228:231], v[128:131]
	v_mfma_f32_16x16x32_bf16 v[124:127], v[100:103], v[228:231], v[124:127]
	v_mfma_f32_16x16x32_bf16 v[112:115], v[88:91], v[236:239], v[112:115]
	v_mfma_f32_16x16x32_bf16 v[108:111], v[100:103], v[236:239], v[108:111]
	v_mfma_f32_16x16x32_bf16 v[152:155], v[172:175], v[198:201], v[152:155]
	v_mfma_f32_16x16x32_bf16 v[148:151], v[190:193], v[198:201], v[148:151]
	v_mfma_f32_16x16x32_bf16 v[136:139], v[172:175], v[206:209], v[136:139]
	v_mfma_f32_16x16x32_bf16 v[132:135], v[190:193], v[206:209], v[132:135]
	v_mfma_f32_16x16x32_bf16 v[120:123], v[172:175], v[224:227], v[120:123]
	v_mfma_f32_16x16x32_bf16 v[116:119], v[190:193], v[224:227], v[116:119]
	v_mfma_f32_16x16x32_bf16 v[104:107], v[172:175], v[232:235], v[104:107]
	v_mfma_f32_16x16x32_bf16 v[96:99], v[190:193], v[232:235], v[96:99]
	v_mfma_f32_16x16x32_bf16 v[152:155], v[176:179], v[202:205], v[152:155]
	v_mfma_f32_16x16x32_bf16 v[148:151], v[194:197], v[202:205], v[148:151]
	v_mfma_f32_16x16x32_bf16 v[136:139], v[176:179], v[220:223], v[136:139]
	v_mfma_f32_16x16x32_bf16 v[132:135], v[194:197], v[220:223], v[132:135]
	v_mfma_f32_16x16x32_bf16 v[120:123], v[176:179], v[228:231], v[120:123]
	v_mfma_f32_16x16x32_bf16 v[116:119], v[194:197], v[228:231], v[116:119]
	v_mfma_f32_16x16x32_bf16 v[104:107], v[176:179], v[236:239], v[104:107]
	v_mfma_f32_16x16x32_bf16 v[96:99], v[194:197], v[236:239], v[96:99]
	s_barrier
	s_add_i32 s60, s60, s26
	v_lshl_add_u64 v[240:241], s[0:1], 0, v[0:1]
	s_mov_b32 m0, s60
	ds_read_b128 v[198:201], v183 offset:16384
	ds_read_b128 v[202:205], v183 offset:17408
	ds_read_b128 v[206:209], v183 offset:18432
	ds_read_b128 v[220:223], v183 offset:19456
	ds_read_b128 v[224:227], v183 offset:20480
	ds_read_b128 v[228:231], v183 offset:21504
	ds_read_b128 v[232:235], v183 offset:22528
	ds_read_b128 v[236:239], v183 offset:23552
	global_load_lds_dwordx4 v[240:241], off
	s_add_i32 m0, s60, 0x2000
	s_add_u32 s60, s0, 0x40000
	v_lshl_add_u64 v[242:243], s[0:1], 0, v[2:3]
	s_addc_u32 s61, s1, 0
	s_add_i32 s64, s64, s26
	global_load_lds_dwordx4 v[242:243], off
	v_lshl_add_u64 v[244:245], s[60:61], 0, v[0:1]
	s_mov_b32 m0, s64
	v_lshl_add_u64 v[246:247], s[24:25], 0, v[164:165]
	global_load_lds_dwordx4 v[244:245], off
	v_lshl_add_u64 v[244:245], s[60:61], 0, v[2:3]
	s_add_i32 m0, s64, 0x2000
	s_nop 0
	global_load_lds_dwordx4 v[244:245], off
	v_lshl_add_u64 v[244:245], s[24:25], 0, v[166:167]
	s_mov_b32 m0, s54
	s_nop 0
	global_load_lds_dwordx4 v[244:245], off
	s_mov_b32 m0, s55
	s_nop 0
	global_load_lds_dwordx4 v[246:247], off
	s_waitcnt vmcnt(8)
	s_waitcnt lgkmcnt(0)
	s_barrier
; #define PG8_STAGE(bufoff, gbase, voff) do { _Pragma("unroll") for (int _i = 0; _i < 2; ++_i) \
;         __builtin_amdgcn_global_load_lds((const unsigned*)((const char*)(gbase) + (voff)[_i]), (PG8_LAS unsigned*)(lds + (bufoff) + ldsw + _i * 8192), 16, 0, 0); } while (0)
; #define PG8_LDA(dst, b, h) do { _Pragma("unroll") for (int m = 0; m < 4; ++m) _Pragma("unroll") for (int k = 0; k < 2; ++k) dst[m][k] = *(const PG8_LAS bf16x8*)(lds + PG8_SA(b, h) + aoff + m * 2048 + k * 1024); } while (0)
; #define PG8_LDB(dst, b, h) do { _Pragma("unroll") for (int n = 0; n < 2; ++n) _Pragma("unroll") for (int k = 0; k < 2; ++k) dst[n][k] = *(const PG8_LAS bf16x8*)(lds + PG8_SB(b, h) + boff + n * 2048 + k * 1024); } while (0)
; #define PG8_MMA(ai, bj, At, Bt) do { __builtin_amdgcn_s_setprio(1); _Pragma("unroll") for (int m = 0; m < 4; ++m) _Pragma("unroll") for (int n = 0; n < 2; ++n) _Pragma("unroll") for (int k = 0; k < 2; ++k) \
;         acc[ai][bj][m][n] = __builtin_amdgcn_mfma_f32_16x16x32_bf16(Bt[n][k], At[m][k], acc[ai][bj][m][n], 0, 0, 0); __builtin_amdgcn_s_setprio(0); } while (0)
; #define PG8_WAIT_V(n) asm volatile("s_waitcnt vmcnt(" #n ")" ::: "memory")
; #define PG8_WAIT_L(n) asm volatile("s_waitcnt lgkmcnt(" #n ")" ::: "memory")
; #define PG8_BAR __builtin_amdgcn_s_barrier()
; #define PG8_SCHED __builtin_amdgcn_sched_barrier(0)
; template <class Epi, class Sched, bool ALIGN_EPI = false, bool SP2 = false>
; __device__ __forceinline__ void gemm_phase(PG8_LAS unsigned char* lds, const Gemm g, const Sched& S, const Epi& E) {
;     ...
;             PG8_WAIT_V(8); PG8_WAIT_L(0); PG8_BAR; PG8_MMA(1, 0, At, B0); PG8_MMA(1, 1, At, B1); PG8_BAR; PG8_SCHED;
;             PG8_LDB(B0, 1, 0); PG8_LDB(B1, 1, 1); PG8_SCHED; PG8_LDA(At, 1, 0); PG8_STAGE(PG8_SA(0, 1), a2 + hstep, voffA);
;             PG8_WAIT_V(8); PG8_WAIT_L(0); PG8_BAR; PG8_MMA(0, 0, At, B0); PG8_MMA(0, 1, At, B1); PG8_BAR; PG8_SCHED;
	s_waitcnt lgkmcnt(0)
	v_mfma_f32_16x16x32_bf16 v[80:83], v[84:87], v[198:201], v[80:83]
	v_mfma_f32_16x16x32_bf16 v[76:79], v[92:95], v[198:201], v[76:79]
	v_mfma_f32_16x16x32_bf16 v[64:67], v[84:87], v[206:209], v[64:67]
	v_mfma_f32_16x16x32_bf16 v[60:63], v[92:95], v[206:209], v[60:63]
	v_mfma_f32_16x16x32_bf16 v[48:51], v[84:87], v[224:227], v[48:51]
	v_mfma_f32_16x16x32_bf16 v[44:47], v[92:95], v[224:227], v[44:47]
	v_mfma_f32_16x16x32_bf16 v[32:35], v[84:87], v[232:235], v[32:35]
	v_mfma_f32_16x16x32_bf16 v[28:31], v[92:95], v[232:235], v[28:31]
	v_mfma_f32_16x16x32_bf16 v[80:83], v[88:91], v[202:205], v[80:83]
	v_mfma_f32_16x16x32_bf16 v[76:79], v[100:103], v[202:205], v[76:79]
	v_mfma_f32_16x16x32_bf16 v[64:67], v[88:91], v[220:223], v[64:67]
	v_mfma_f32_16x16x32_bf16 v[60:63], v[100:103], v[220:223], v[60:63]
	v_mfma_f32_16x16x32_bf16 v[48:51], v[88:91], v[228:231], v[48:51]
	v_mfma_f32_16x16x32_bf16 v[44:47], v[100:103], v[228:231], v[44:47]
	v_mfma_f32_16x16x32_bf16 v[32:35], v[88:91], v[236:239], v[32:35]
	v_mfma_f32_16x16x32_bf16 v[28:31], v[100:103], v[236:239], v[28:31]
	v_mfma_f32_16x16x32_bf16 v[72:75], v[172:175], v[198:201], v[72:75]
	v_mfma_f32_16x16x32_bf16 v[68:71], v[190:193], v[198:201], v[68:71]
	v_mfma_f32_16x16x32_bf16 v[56:59], v[172:175], v[206:209], v[56:59]
	v_mfma_f32_16x16x32_bf16 v[52:55], v[190:193], v[206:209], v[52:55]
	v_mfma_f32_16x16x32_bf16 v[40:43], v[172:175], v[224:227], v[40:43]
	v_mfma_f32_16x16x32_bf16 v[36:39], v[190:193], v[224:227], v[36:39]
	v_mfma_f32_16x16x32_bf16 v[24:27], v[172:175], v[232:235], v[24:27]
	v_mfma_f32_16x16x32_bf16 v[20:23], v[190:193], v[232:235], v[20:23]
	v_mfma_f32_16x16x32_bf16 v[72:75], v[176:179], v[202:205], v[72:75]
	v_mfma_f32_16x16x32_bf16 v[68:71], v[194:197], v[202:205], v[68:71]
	v_mfma_f32_16x16x32_bf16 v[56:59], v[176:179], v[220:223], v[56:59]
	v_mfma_f32_16x16x32_bf16 v[52:55], v[194:197], v[220:223], v[52:55]
	v_mfma_f32_16x16x32_bf16 v[40:43], v[176:179], v[228:231], v[40:43]
	v_mfma_f32_16x16x32_bf16 v[36:39], v[194:197], v[228:231], v[36:39]
	v_mfma_f32_16x16x32_bf16 v[24:27], v[176:179], v[236:239], v[24:27]
	v_mfma_f32_16x16x32_bf16 v[20:23], v[194:197], v[236:239], v[20:23]
	s_barrier
	s_add_i32 s60, 0, 0x18000
	s_add_i32 s61, 0, 0x1c000
	v_add_u32_e32 v100, s60, v181
	v_add_u32_e32 v186, s61, v181
	ds_read_b128 v[84:87], v100
	ds_read_b128 v[88:91], v100 offset:1024
	ds_read_b128 v[92:95], v100 offset:2048
	ds_read_b128 v[100:103], v100 offset:3072
	ds_read_b128 v[172:175], v186
	ds_read_b128 v[176:179], v186 offset:1024
	ds_read_b128 v[190:193], v186 offset:2048
	ds_read_b128 v[194:197], v186 offset:3072
	s_add_u32 s24, s24, 0x40000
	s_addc_u32 s25, s25, 0
	s_mov_b32 m0, s58
	v_lshl_add_u64 v[248:249], s[24:25], 0, v[166:167]
	ds_read_b128 v[198:201], v183 offset:32768
	ds_read_b128 v[202:205], v183 offset:33792
	ds_read_b128 v[206:209], v183 offset:34816
	ds_read_b128 v[220:223], v183 offset:35840
	ds_read_b128 v[224:227], v183 offset:36864
	ds_read_b128 v[228:231], v183 offset:37888
	ds_read_b128 v[232:235], v183 offset:38912
	ds_read_b128 v[236:239], v183 offset:39936
	global_load_lds_dwordx4 v[248:249], off
	v_lshl_add_u64 v[248:249], s[24:25], 0, v[164:165]
	s_mov_b32 m0, s59
	s_nop 0
	global_load_lds_dwordx4 v[248:249], off
	s_waitcnt vmcnt(8)
	s_waitcnt lgkmcnt(0)
	s_barrier
	s_waitcnt lgkmcnt(0)
	v_mfma_f32_16x16x32_bf16 v[160:163], v[84:87], v[198:201], v[160:163]
	v_mfma_f32_16x16x32_bf16 v[156:159], v[92:95], v[198:201], v[156:159]
	v_mfma_f32_16x16x32_bf16 v[144:147], v[84:87], v[206:209], v[144:147]
	v_mfma_f32_16x16x32_bf16 v[140:143], v[92:95], v[206:209], v[140:143]
	v_mfma_f32_16x16x32_bf16 v[128:131], v[84:87], v[224:227], v[128:131]
	v_mfma_f32_16x16x32_bf16 v[124:127], v[92:95], v[224:227], v[124:127]
	v_mfma_f32_16x16x32_bf16 v[112:115], v[84:87], v[232:235], v[112:115]
	v_mfma_f32_16x16x32_bf16 v[108:111], v[92:95], v[232:235], v[108:111]
	v_mfma_f32_16x16x32_bf16 v[160:163], v[88:91], v[202:205], v[160:163]
	v_mfma_f32_16x16x32_bf16 v[156:159], v[100:103], v[202:205], v[156:159]
	v_mfma_f32_16x16x32_bf16 v[144:147], v[88:91], v[220:223], v[144:147]
	v_mfma_f32_16x16x32_bf16 v[140:143], v[100:103], v[220:223], v[140:143]
	v_mfma_f32_16x16x32_bf16 v[128:131], v[88:91], v[228:231], v[128:131]
	v_mfma_f32_16x16x32_bf16 v[124:127], v[100:103], v[228:231], v[124:127]
	v_mfma_f32_16x16x32_bf16 v[112:115], v[88:91], v[236:239], v[112:115]
	v_mfma_f32_16x16x32_bf16 v[108:111], v[100:103], v[236:239], v[108:111]
	v_mfma_f32_16x16x32_bf16 v[152:155], v[172:175], v[198:201], v[152:155]
	v_mfma_f32_16x16x32_bf16 v[148:151], v[190:193], v[198:201], v[148:151]
	v_mfma_f32_16x16x32_bf16 v[136:139], v[172:175], v[206:209], v[136:139]
	v_mfma_f32_16x16x32_bf16 v[132:135], v[190:193], v[206:209], v[132:135]
	v_mfma_f32_16x16x32_bf16 v[120:123], v[172:175], v[224:227], v[120:123]
	v_mfma_f32_16x16x32_bf16 v[116:119], v[190:193], v[224:227], v[116:119]
	v_mfma_f32_16x16x32_bf16 v[104:107], v[172:175], v[232:235], v[104:107]
	v_mfma_f32_16x16x32_bf16 v[96:99], v[190:193], v[232:235], v[96:99]
	v_mfma_f32_16x16x32_bf16 v[152:155], v[176:179], v[202:205], v[152:155]
	v_mfma_f32_16x16x32_bf16 v[148:151], v[194:197], v[202:205], v[148:151]
	v_mfma_f32_16x16x32_bf16 v[136:139], v[176:179], v[220:223], v[136:139]
	v_mfma_f32_16x16x32_bf16 v[132:135], v[194:197], v[220:223], v[132:135]
	v_mfma_f32_16x16x32_bf16 v[120:123], v[176:179], v[228:231], v[120:123]
	v_mfma_f32_16x16x32_bf16 v[116:119], v[194:197], v[228:231], v[116:119]
	v_mfma_f32_16x16x32_bf16 v[104:107], v[176:179], v[236:239], v[104:107]
	v_mfma_f32_16x16x32_bf16 v[96:99], v[194:197], v[236:239], v[96:99]
	s_barrier
; #define PG8_STAGE(bufoff, gbase, voff) do { _Pragma("unroll") for (int _i = 0; _i < 2; ++_i) \
;         __builtin_amdgcn_global_load_lds((const unsigned*)((const char*)(gbase) + (voff)[_i]), (PG8_LAS unsigned*)(lds + (bufoff) + ldsw + _i * 8192), 16, 0, 0); } while (0)
; #define PG8_LDA(dst, b, h) do { _Pragma("unroll") for (int m = 0; m < 4; ++m) _Pragma("unroll") for (int k = 0; k < 2; ++k) dst[m][k] = *(const PG8_LAS bf16x8*)(lds + PG8_SA(b, h) + aoff + m * 2048 + k * 1024); } while (0)
; #define PG8_MMA(ai, bj, At, Bt) do { __builtin_amdgcn_s_setprio(1); _Pragma("unroll") for (int m = 0; m < 4; ++m) _Pragma("unroll") for (int n = 0; n < 2; ++n) _Pragma("unroll") for (int k = 0; k < 2; ++k) \
;         acc[ai][bj][m][n] = __builtin_amdgcn_mfma_f32_16x16x32_bf16(Bt[n][k], At[m][k], acc[ai][bj][m][n], 0, 0, 0); __builtin_amdgcn_s_setprio(0); } while (0)
; #define PG8_WAIT_V(n) asm volatile("s_waitcnt vmcnt(" #n ")" ::: "memory")
; #define PG8_WAIT_L(n) asm volatile("s_waitcnt lgkmcnt(" #n ")" ::: "memory")
; #define PG8_BAR __builtin_amdgcn_s_barrier()
; #define PG8_SCHED __builtin_amdgcn_sched_barrier(0)
; template <class Epi, class Sched, bool ALIGN_EPI = false, bool SP2 = false>
; __device__ __forceinline__ void gemm_phase(PG8_LAS unsigned char* lds, const Gemm g, const Sched& S, const Epi& E) {
;     ...
;             PG8_LDA(At, 1, 1); PG8_STAGE(PG8_SB(1, 0), b3, voffB); PG8_STAGE(PG8_SB(1, 1), b3 + hstep, voffB); PG8_STAGE(PG8_SA(1, 0), a3, voffA);
;             PG8_WAIT_V(8); PG8_WAIT_L(0); PG8_BAR; PG8_MMA(1, 0, At, B0); PG8_MMA(1, 1, At, B1); PG8_BAR; PG8_SCHED;
	s_add_i32 s24, s60, s26
	v_lshl_add_u64 v[240:241], v[240:241], 0, s[20:21]
	s_mov_b32 m0, s24
	ds_read_b128 v[198:201], v183 offset:49152
	ds_read_b128 v[202:205], v183 offset:50176
	ds_read_b128 v[206:209], v183 offset:51200
	ds_read_b128 v[220:223], v183 offset:52224
	ds_read_b128 v[224:227], v183 offset:53248
	ds_read_b128 v[228:231], v183 offset:54272
	ds_read_b128 v[232:235], v183 offset:55296
	ds_read_b128 v[236:239], v183 offset:56320
	global_load_lds_dwordx4 v[240:241], off
	s_add_i32 m0, s24, 0x2000
	s_add_u32 s0, s0, 0x40080
	v_lshl_add_u64 v[240:241], v[242:243], 0, s[20:21]
	s_addc_u32 s1, s1, 0
	s_add_i32 s24, s61, s26
	global_load_lds_dwordx4 v[240:241], off
	v_lshl_add_u64 v[240:241], s[0:1], 0, v[0:1]
	s_mov_b32 m0, s24
	s_nop 0
	global_load_lds_dwordx4 v[240:241], off
	v_lshl_add_u64 v[240:241], s[0:1], 0, v[2:3]
	s_add_i32 m0, s24, 0x2000
	s_nop 0
	global_load_lds_dwordx4 v[240:241], off
	v_lshl_add_u64 v[240:241], v[244:245], 0, s[20:21]
	s_mov_b32 m0, s66
	s_nop 0
	global_load_lds_dwordx4 v[240:241], off
	v_lshl_add_u64 v[240:241], v[246:247], 0, s[20:21]
	s_mov_b32 m0, s67
	s_nop 0
	global_load_lds_dwordx4 v[240:241], off
	s_waitcnt vmcnt(8)
	s_waitcnt lgkmcnt(0)
	s_barrier
	s_waitcnt lgkmcnt(0)
	v_mfma_f32_16x16x32_bf16 v[80:83], v[84:87], v[198:201], v[80:83]
	v_mfma_f32_16x16x32_bf16 v[76:79], v[92:95], v[198:201], v[76:79]
	v_mfma_f32_16x16x32_bf16 v[64:67], v[84:87], v[206:209], v[64:67]
	v_mfma_f32_16x16x32_bf16 v[60:63], v[92:95], v[206:209], v[60:63]
	v_mfma_f32_16x16x32_bf16 v[48:51], v[84:87], v[224:227], v[48:51]
	v_mfma_f32_16x16x32_bf16 v[44:47], v[92:95], v[224:227], v[44:47]
	v_mfma_f32_16x16x32_bf16 v[32:35], v[84:87], v[232:235], v[32:35]
	v_mfma_f32_16x16x32_bf16 v[28:31], v[92:95], v[232:235], v[28:31]
	v_mfma_f32_16x16x32_bf16 v[80:83], v[88:91], v[202:205], v[80:83]
	v_mfma_f32_16x16x32_bf16 v[76:79], v[100:103], v[202:205], v[76:79]
	v_mfma_f32_16x16x32_bf16 v[64:67], v[88:91], v[220:223], v[64:67]
	v_mfma_f32_16x16x32_bf16 v[60:63], v[100:103], v[220:223], v[60:63]
	v_mfma_f32_16x16x32_bf16 v[48:51], v[88:91], v[228:231], v[48:51]
	v_mfma_f32_16x16x32_bf16 v[44:47], v[100:103], v[228:231], v[44:47]
	v_mfma_f32_16x16x32_bf16 v[32:35], v[88:91], v[236:239], v[32:35]
	v_mfma_f32_16x16x32_bf16 v[28:31], v[100:103], v[236:239], v[28:31]
	v_mfma_f32_16x16x32_bf16 v[72:75], v[172:175], v[198:201], v[72:75]
	v_mfma_f32_16x16x32_bf16 v[68:71], v[190:193], v[198:201], v[68:71]
	v_mfma_f32_16x16x32_bf16 v[56:59], v[172:175], v[206:209], v[56:59]
	v_mfma_f32_16x16x32_bf16 v[52:55], v[190:193], v[206:209], v[52:55]
	v_mfma_f32_16x16x32_bf16 v[40:43], v[172:175], v[224:227], v[40:43]
	v_mfma_f32_16x16x32_bf16 v[36:39], v[190:193], v[224:227], v[36:39]
	v_mfma_f32_16x16x32_bf16 v[24:27], v[172:175], v[232:235], v[24:27]
	v_mfma_f32_16x16x32_bf16 v[20:23], v[190:193], v[232:235], v[20:23]
	v_mfma_f32_16x16x32_bf16 v[72:75], v[176:179], v[202:205], v[72:75]
	v_mfma_f32_16x16x32_bf16 v[68:71], v[194:197], v[202:205], v[68:71]
	v_mfma_f32_16x16x32_bf16 v[56:59], v[176:179], v[220:223], v[56:59]
	v_mfma_f32_16x16x32_bf16 v[52:55], v[194:197], v[220:223], v[52:55]
	v_mfma_f32_16x16x32_bf16 v[40:43], v[176:179], v[228:231], v[40:43]
	v_mfma_f32_16x16x32_bf16 v[36:39], v[194:197], v[228:231], v[36:39]
	v_mfma_f32_16x16x32_bf16 v[24:27], v[176:179], v[236:239], v[24:27]
	v_mfma_f32_16x16x32_bf16 v[20:23], v[194:197], v[236:239], v[20:23]
	s_barrier
	s_add_i32 s35, s35, 2
	s_add_u32 s6, s6, 0x100
	s_addc_u32 s7, s7, 0
	s_add_u32 s22, s22, 0x100
	s_addc_u32 s23, s23, 0
	s_cmp_gt_u32 s35, 13
	s_cbranch_scc0 .LBB0_218
	s_and_b64 vcc, exec, s[10:11]
	s_cbranch_vccz .LBB0_221
	s_barrier

; #define PG8_STAGE(bufoff, gbase, voff) do { _Pragma("unroll") for (int _i = 0; _i < 2; ++_i) \
;         __builtin_amdgcn_global_load_lds((const unsigned*)((const char*)(gbase) + (voff)[_i]), (PG8_LAS unsigned*)(lds + (bufoff) + ldsw + _i * 8192), 16, 0, 0); } while (0)
; #define PG8_LDA(dst, b, h) do { _Pragma("unroll") for (int m = 0; m < 4; ++m) _Pragma("unroll") for (int k = 0; k < 2; ++k) dst[m][k] = *(const PG8_LAS bf16x8*)(lds + PG8_SA(b, h) + aoff + m * 2048 + k * 1024); } while (0)
; #define PG8_LDB(dst, b, h) do { _Pragma("unroll") for (int n = 0; n < 2; ++n) _Pragma("unroll") for (int k = 0; k < 2; ++k) dst[n][k] = *(const PG8_LAS bf16x8*)(lds + PG8_SB(b, h) + boff + n * 2048 + k * 1024); } while (0)
; #define PG8_MMA(ai, bj, At, Bt) do { __builtin_amdgcn_s_setprio(1); _Pragma("unroll") for (int m = 0; m < 4; ++m) _Pragma("unroll") for (int n = 0; n < 2; ++n) _Pragma("unroll") for (int k = 0; k < 2; ++k) \
;         acc[ai][bj][m][n] = __builtin_amdgcn_mfma_f32_16x16x32_bf16(Bt[n][k], At[m][k], acc[ai][bj][m][n], 0, 0, 0); __builtin_amdgcn_s_setprio(0); } while (0)
; #define PG8_WAIT_V(n) asm volatile("s_waitcnt vmcnt(" #n ")" ::: "memory")
; #define PG8_WAIT_L(n) asm volatile("s_waitcnt lgkmcnt(" #n ")" ::: "memory")
; #define PG8_BAR __builtin_amdgcn_s_barrier()
; #define PG8_SCHED __builtin_amdgcn_sched_barrier(0)
; template <class Epi, class Sched, bool ALIGN_EPI = false, bool SP2 = false>
; __device__ __forceinline__ void gemm_phase(PG8_LAS unsigned char* lds, const Gemm g, const Sched& S, const Epi& E) {
;     ...
;             PG8_LDB(B0, 0, 0); PG8_LDB(B1, 0, 1); PG8_SCHED; PG8_LDA(At, 0, 0); PG8_STAGE(PG8_SA(1, 1), a1 + hstep, voffA);
;             PG8_WAIT_V(8); PG8_WAIT_L(0); PG8_BAR; PG8_MMA(0, 0, At, B0); PG8_MMA(0, 1, At, B1); PG8_BAR; PG8_SCHED;
;             PG8_LDA(At, 0, 1); PG8_STAGE(PG8_SB(0, 0), b2, voffB); PG8_STAGE(PG8_SB(0, 1), b2 + hstep, voffB); PG8_STAGE(PG8_SA(0, 0), a2, voffA);
;             PG8_WAIT_V(8); PG8_WAIT_L(0); PG8_BAR; PG8_MMA(1, 0, At, B0); PG8_MMA(1, 1, At, B1); PG8_BAR; PG8_SCHED;
.LBB0_559:
	s_add_u32 s0, s54, 0xfffe0080
	s_addc_u32 s1, s55, -1
	s_add_i32 s60, 0, 0x10000
	s_cmp_eq_u32 s35, 4
	s_cselect_b32 s67, s17, s1
	s_cselect_b32 s66, s29, s0
	s_cselect_b32 s1, s15, s23
	s_cselect_b32 s0, vcc_lo, s22
	s_add_i32 s64, 0, 0x14000
	v_add_u32_e32 v112, s60, v221
	v_add_u32_e32 v176, s64, v221
	ds_read_b128 v[92:95], v112
	ds_read_b128 v[96:99], v112 offset:1024
	ds_read_b128 v[108:111], v112 offset:2048
	ds_read_b128 v[112:115], v112 offset:3072
	ds_read_b128 v[164:167], v176
	ds_read_b128 v[168:171], v176 offset:1024
	ds_read_b128 v[172:175], v176 offset:2048
	ds_read_b128 v[176:179], v176 offset:3072
	v_lshl_add_u64 v[240:241], s[54:55], 0, v[194:195]
	s_add_i32 m0, s73, 0xc000
	ds_read_b128 v[180:183], v223
	ds_read_b128 v[198:201], v223 offset:1024
	ds_read_b128 v[202:205], v223 offset:2048
	ds_read_b128 v[206:209], v223 offset:3072
	ds_read_b128 v[224:227], v223 offset:4096
	ds_read_b128 v[228:231], v223 offset:5120
	ds_read_b128 v[232:235], v223 offset:6144
	ds_read_b128 v[236:239], v223 offset:7168
	global_load_lds_dwordx4 v[240:241], off
	v_lshl_add_u64 v[240:241], s[54:55], 0, v[196:197]
	s_add_i32 m0, s73, 0xe000
	s_nop 0
	global_load_lds_dwordx4 v[240:241], off
	s_waitcnt vmcnt(8)
	s_waitcnt lgkmcnt(0)
	s_barrier
	s_waitcnt lgkmcnt(0)
	v_mfma_f32_16x16x32_bf16 v[160:163], v[92:95], v[180:183], v[160:163]
	v_mfma_f32_16x16x32_bf16 v[156:159], v[108:111], v[180:183], v[156:159]
	v_mfma_f32_16x16x32_bf16 v[144:147], v[92:95], v[202:205], v[144:147]
	v_mfma_f32_16x16x32_bf16 v[140:143], v[108:111], v[202:205], v[140:143]
	v_mfma_f32_16x16x32_bf16 v[128:131], v[92:95], v[224:227], v[128:131]
	v_mfma_f32_16x16x32_bf16 v[124:127], v[108:111], v[224:227], v[124:127]
	v_mfma_f32_16x16x32_bf16 v[104:107], v[92:95], v[232:235], v[104:107]
	v_mfma_f32_16x16x32_bf16 v[100:103], v[108:111], v[232:235], v[100:103]
	v_mfma_f32_16x16x32_bf16 v[160:163], v[96:99], v[198:201], v[160:163]
	v_mfma_f32_16x16x32_bf16 v[156:159], v[112:115], v[198:201], v[156:159]
	v_mfma_f32_16x16x32_bf16 v[144:147], v[96:99], v[206:209], v[144:147]
	v_mfma_f32_16x16x32_bf16 v[140:143], v[112:115], v[206:209], v[140:143]
	v_mfma_f32_16x16x32_bf16 v[128:131], v[96:99], v[228:231], v[128:131]
	v_mfma_f32_16x16x32_bf16 v[124:127], v[112:115], v[228:231], v[124:127]
	v_mfma_f32_16x16x32_bf16 v[104:107], v[96:99], v[236:239], v[104:107]
	v_mfma_f32_16x16x32_bf16 v[100:103], v[112:115], v[236:239], v[100:103]
	v_mfma_f32_16x16x32_bf16 v[152:155], v[164:167], v[180:183], v[152:155]
	v_mfma_f32_16x16x32_bf16 v[148:151], v[172:175], v[180:183], v[148:151]
	v_mfma_f32_16x16x32_bf16 v[136:139], v[164:167], v[202:205], v[136:139]
	v_mfma_f32_16x16x32_bf16 v[132:135], v[172:175], v[202:205], v[132:135]
	v_mfma_f32_16x16x32_bf16 v[120:123], v[164:167], v[224:227], v[120:123]
	v_mfma_f32_16x16x32_bf16 v[116:119], v[172:175], v[224:227], v[116:119]
	v_mfma_f32_16x16x32_bf16 v[88:91], v[164:167], v[232:235], v[88:91]
	v_mfma_f32_16x16x32_bf16 v[84:87], v[172:175], v[232:235], v[84:87]
	v_mfma_f32_16x16x32_bf16 v[152:155], v[168:171], v[198:201], v[152:155]
	v_mfma_f32_16x16x32_bf16 v[148:151], v[176:179], v[198:201], v[148:151]
	v_mfma_f32_16x16x32_bf16 v[136:139], v[168:171], v[206:209], v[136:139]
	v_mfma_f32_16x16x32_bf16 v[132:135], v[176:179], v[206:209], v[132:135]
	v_mfma_f32_16x16x32_bf16 v[120:123], v[168:171], v[228:231], v[120:123]
	v_mfma_f32_16x16x32_bf16 v[116:119], v[176:179], v[228:231], v[116:119]
	v_mfma_f32_16x16x32_bf16 v[88:91], v[168:171], v[236:239], v[88:91]
	v_mfma_f32_16x16x32_bf16 v[84:87], v[176:179], v[236:239], v[84:87]
	s_barrier
	s_add_i32 s60, s60, s72
	v_lshl_add_u64 v[240:241], s[0:1], 0, v[0:1]
	s_mov_b32 m0, s60
	ds_read_b128 v[180:183], v223 offset:16384
	ds_read_b128 v[198:201], v223 offset:17408
	ds_read_b128 v[202:205], v223 offset:18432
	ds_read_b128 v[206:209], v223 offset:19456
	ds_read_b128 v[224:227], v223 offset:20480
	ds_read_b128 v[228:231], v223 offset:21504
	ds_read_b128 v[232:235], v223 offset:22528
	ds_read_b128 v[236:239], v223 offset:23552
	global_load_lds_dwordx4 v[240:241], off
	s_add_i32 m0, s60, 0x2000
	s_add_u32 s60, s0, 0x20000
	v_lshl_add_u64 v[242:243], s[0:1], 0, v[2:3]
	s_addc_u32 s61, s1, 0
	s_add_i32 s64, s64, s72
	global_load_lds_dwordx4 v[242:243], off
	v_lshl_add_u64 v[244:245], s[60:61], 0, v[0:1]
	s_mov_b32 m0, s64
	v_lshl_add_u64 v[246:247], s[66:67], 0, v[190:191]
	global_load_lds_dwordx4 v[244:245], off
	v_lshl_add_u64 v[244:245], s[60:61], 0, v[2:3]
	s_add_i32 m0, s64, 0x2000
	s_nop 0
	global_load_lds_dwordx4 v[244:245], off
	v_lshl_add_u64 v[244:245], s[66:67], 0, v[192:193]
	s_mov_b32 m0, s73
	s_nop 0
	global_load_lds_dwordx4 v[244:245], off
	s_mov_b32 m0, s75
	s_nop 0
	global_load_lds_dwordx4 v[246:247], off
	s_waitcnt vmcnt(8)
	s_waitcnt lgkmcnt(0)
	s_barrier
; #define PG8_STAGE(bufoff, gbase, voff) do { _Pragma("unroll") for (int _i = 0; _i < 2; ++_i) \
;         __builtin_amdgcn_global_load_lds((const unsigned*)((const char*)(gbase) + (voff)[_i]), (PG8_LAS unsigned*)(lds + (bufoff) + ldsw + _i * 8192), 16, 0, 0); } while (0)
; #define PG8_LDA(dst, b, h) do { _Pragma("unroll") for (int m = 0; m < 4; ++m) _Pragma("unroll") for (int k = 0; k < 2; ++k) dst[m][k] = *(const PG8_LAS bf16x8*)(lds + PG8_SA(b, h) + aoff + m * 2048 + k * 1024); } while (0)
; #define PG8_LDB(dst, b, h) do { _Pragma("unroll") for (int n = 0; n < 2; ++n) _Pragma("unroll") for (int k = 0; k < 2; ++k) dst[n][k] = *(const PG8_LAS bf16x8*)(lds + PG8_SB(b, h) + boff + n * 2048 + k * 1024); } while (0)
; #define PG8_MMA(ai, bj, At, Bt) do { __builtin_amdgcn_s_setprio(1); _Pragma("unroll") for (int m = 0; m < 4; ++m) _Pragma("unroll") for (int n = 0; n < 2; ++n) _Pragma("unroll") for (int k = 0; k < 2; ++k) \
;         acc[ai][bj][m][n] = __builtin_amdgcn_mfma_f32_16x16x32_bf16(Bt[n][k], At[m][k], acc[ai][bj][m][n], 0, 0, 0); __builtin_amdgcn_s_setprio(0); } while (0)
; #define PG8_WAIT_V(n) asm volatile("s_waitcnt vmcnt(" #n ")" ::: "memory")
; #define PG8_WAIT_L(n) asm volatile("s_waitcnt lgkmcnt(" #n ")" ::: "memory")
; #define PG8_BAR __builtin_amdgcn_s_barrier()
; #define PG8_SCHED __builtin_amdgcn_sched_barrier(0)
; template <class Epi, class Sched, bool ALIGN_EPI = false, bool SP2 = false>
; __device__ __forceinline__ void gemm_phase(PG8_LAS unsigned char* lds, const Gemm g, const Sched& S, const Epi& E) {
;     ...
;             PG8_WAIT_V(8); PG8_WAIT_L(0); PG8_BAR; PG8_MMA(1, 0, At, B0); PG8_MMA(1, 1, At, B1); PG8_BAR; PG8_SCHED;
;             PG8_LDB(B0, 1, 0); PG8_LDB(B1, 1, 1); PG8_SCHED; PG8_LDA(At, 1, 0); PG8_STAGE(PG8_SA(0, 1), a2 + hstep, voffA);
;             PG8_WAIT_V(8); PG8_WAIT_L(0); PG8_BAR; PG8_MMA(0, 0, At, B0); PG8_MMA(0, 1, At, B1); PG8_BAR; PG8_SCHED;
	s_waitcnt lgkmcnt(0)
	v_mfma_f32_16x16x32_bf16 v[80:83], v[92:95], v[180:183], v[80:83]
	v_mfma_f32_16x16x32_bf16 v[76:79], v[108:111], v[180:183], v[76:79]
	v_mfma_f32_16x16x32_bf16 v[64:67], v[92:95], v[202:205], v[64:67]
	v_mfma_f32_16x16x32_bf16 v[60:63], v[108:111], v[202:205], v[60:63]
	v_mfma_f32_16x16x32_bf16 v[48:51], v[92:95], v[224:227], v[48:51]
	v_mfma_f32_16x16x32_bf16 v[44:47], v[108:111], v[224:227], v[44:47]
	v_mfma_f32_16x16x32_bf16 v[32:35], v[92:95], v[232:235], v[32:35]
	v_mfma_f32_16x16x32_bf16 v[28:31], v[108:111], v[232:235], v[28:31]
	v_mfma_f32_16x16x32_bf16 v[80:83], v[96:99], v[198:201], v[80:83]
	v_mfma_f32_16x16x32_bf16 v[76:79], v[112:115], v[198:201], v[76:79]
	v_mfma_f32_16x16x32_bf16 v[64:67], v[96:99], v[206:209], v[64:67]
	v_mfma_f32_16x16x32_bf16 v[60:63], v[112:115], v[206:209], v[60:63]
	v_mfma_f32_16x16x32_bf16 v[48:51], v[96:99], v[228:231], v[48:51]
	v_mfma_f32_16x16x32_bf16 v[44:47], v[112:115], v[228:231], v[44:47]
	v_mfma_f32_16x16x32_bf16 v[32:35], v[96:99], v[236:239], v[32:35]
	v_mfma_f32_16x16x32_bf16 v[28:31], v[112:115], v[236:239], v[28:31]
	v_mfma_f32_16x16x32_bf16 v[72:75], v[164:167], v[180:183], v[72:75]
	v_mfma_f32_16x16x32_bf16 v[68:71], v[172:175], v[180:183], v[68:71]
	v_mfma_f32_16x16x32_bf16 v[56:59], v[164:167], v[202:205], v[56:59]
	v_mfma_f32_16x16x32_bf16 v[52:55], v[172:175], v[202:205], v[52:55]
	v_mfma_f32_16x16x32_bf16 v[40:43], v[164:167], v[224:227], v[40:43]
	v_mfma_f32_16x16x32_bf16 v[36:39], v[172:175], v[224:227], v[36:39]
	v_mfma_f32_16x16x32_bf16 v[24:27], v[164:167], v[232:235], v[24:27]
	v_mfma_f32_16x16x32_bf16 v[20:23], v[172:175], v[232:235], v[20:23]
	v_mfma_f32_16x16x32_bf16 v[72:75], v[168:171], v[198:201], v[72:75]
	v_mfma_f32_16x16x32_bf16 v[68:71], v[176:179], v[198:201], v[68:71]
	v_mfma_f32_16x16x32_bf16 v[56:59], v[168:171], v[206:209], v[56:59]
	v_mfma_f32_16x16x32_bf16 v[52:55], v[176:179], v[206:209], v[52:55]
	v_mfma_f32_16x16x32_bf16 v[40:43], v[168:171], v[228:231], v[40:43]
	v_mfma_f32_16x16x32_bf16 v[36:39], v[176:179], v[228:231], v[36:39]
	v_mfma_f32_16x16x32_bf16 v[24:27], v[168:171], v[236:239], v[24:27]
	v_mfma_f32_16x16x32_bf16 v[20:23], v[176:179], v[236:239], v[20:23]
	s_barrier
	s_add_i32 s64, 0, 0x18000
	s_add_i32 s65, 0, 0x1c000
	v_add_u32_e32 v112, s64, v221
	v_add_u32_e32 v176, s65, v221
	ds_read_b128 v[92:95], v112
	ds_read_b128 v[96:99], v112 offset:1024
	ds_read_b128 v[108:111], v112 offset:2048
	ds_read_b128 v[112:115], v112 offset:3072
	ds_read_b128 v[164:167], v176
	ds_read_b128 v[168:171], v176 offset:1024
	ds_read_b128 v[172:175], v176 offset:2048
	ds_read_b128 v[176:179], v176 offset:3072
	s_add_u32 s60, s66, 0x20000
	s_addc_u32 s61, s67, 0
	s_mov_b32 m0, s94
	v_lshl_add_u64 v[248:249], s[60:61], 0, v[192:193]
	ds_read_b128 v[180:183], v223 offset:32768
	ds_read_b128 v[198:201], v223 offset:33792
	ds_read_b128 v[202:205], v223 offset:34816
	ds_read_b128 v[206:209], v223 offset:35840
	ds_read_b128 v[224:227], v223 offset:36864
	ds_read_b128 v[228:231], v223 offset:37888
	ds_read_b128 v[232:235], v223 offset:38912
	ds_read_b128 v[236:239], v223 offset:39936
	global_load_lds_dwordx4 v[248:249], off
	v_lshl_add_u64 v[248:249], s[60:61], 0, v[190:191]
	s_mov_b32 m0, s95
	s_nop 0
	global_load_lds_dwordx4 v[248:249], off
	s_waitcnt vmcnt(8)
	s_waitcnt lgkmcnt(0)
	s_barrier
	s_waitcnt lgkmcnt(0)
	v_mfma_f32_16x16x32_bf16 v[160:163], v[92:95], v[180:183], v[160:163]
	v_mfma_f32_16x16x32_bf16 v[156:159], v[108:111], v[180:183], v[156:159]
	v_mfma_f32_16x16x32_bf16 v[144:147], v[92:95], v[202:205], v[144:147]
	v_mfma_f32_16x16x32_bf16 v[140:143], v[108:111], v[202:205], v[140:143]
	v_mfma_f32_16x16x32_bf16 v[128:131], v[92:95], v[224:227], v[128:131]
	v_mfma_f32_16x16x32_bf16 v[124:127], v[108:111], v[224:227], v[124:127]
	v_mfma_f32_16x16x32_bf16 v[104:107], v[92:95], v[232:235], v[104:107]
	v_mfma_f32_16x16x32_bf16 v[100:103], v[108:111], v[232:235], v[100:103]
	v_mfma_f32_16x16x32_bf16 v[160:163], v[96:99], v[198:201], v[160:163]
	v_mfma_f32_16x16x32_bf16 v[156:159], v[112:115], v[198:201], v[156:159]
	v_mfma_f32_16x16x32_bf16 v[144:147], v[96:99], v[206:209], v[144:147]
	v_mfma_f32_16x16x32_bf16 v[140:143], v[112:115], v[206:209], v[140:143]
	v_mfma_f32_16x16x32_bf16 v[128:131], v[96:99], v[228:231], v[128:131]
	v_mfma_f32_16x16x32_bf16 v[124:127], v[112:115], v[228:231], v[124:127]
	v_mfma_f32_16x16x32_bf16 v[104:107], v[96:99], v[236:239], v[104:107]
	v_mfma_f32_16x16x32_bf16 v[100:103], v[112:115], v[236:239], v[100:103]
	v_mfma_f32_16x16x32_bf16 v[152:155], v[164:167], v[180:183], v[152:155]
	v_mfma_f32_16x16x32_bf16 v[148:151], v[172:175], v[180:183], v[148:151]
	v_mfma_f32_16x16x32_bf16 v[136:139], v[164:167], v[202:205], v[136:139]
	v_mfma_f32_16x16x32_bf16 v[132:135], v[172:175], v[202:205], v[132:135]
	v_mfma_f32_16x16x32_bf16 v[120:123], v[164:167], v[224:227], v[120:123]
	v_mfma_f32_16x16x32_bf16 v[116:119], v[172:175], v[224:227], v[116:119]
	v_mfma_f32_16x16x32_bf16 v[88:91], v[164:167], v[232:235], v[88:91]
	v_mfma_f32_16x16x32_bf16 v[84:87], v[172:175], v[232:235], v[84:87]
	v_mfma_f32_16x16x32_bf16 v[152:155], v[168:171], v[198:201], v[152:155]
	v_mfma_f32_16x16x32_bf16 v[148:151], v[176:179], v[198:201], v[148:151]
	v_mfma_f32_16x16x32_bf16 v[136:139], v[168:171], v[206:209], v[136:139]
	v_mfma_f32_16x16x32_bf16 v[132:135], v[176:179], v[206:209], v[132:135]
	v_mfma_f32_16x16x32_bf16 v[120:123], v[168:171], v[228:231], v[120:123]
	v_mfma_f32_16x16x32_bf16 v[116:119], v[176:179], v[228:231], v[116:119]
	v_mfma_f32_16x16x32_bf16 v[88:91], v[168:171], v[236:239], v[88:91]
	v_mfma_f32_16x16x32_bf16 v[84:87], v[176:179], v[236:239], v[84:87]
	s_barrier
; #define PG8_STAGE(bufoff, gbase, voff) do { _Pragma("unroll") for (int _i = 0; _i < 2; ++_i) \
;         __builtin_amdgcn_global_load_lds((const unsigned*)((const char*)(gbase) + (voff)[_i]), (PG8_LAS unsigned*)(lds + (bufoff) + ldsw + _i * 8192), 16, 0, 0); } while (0)
; #define PG8_LDA(dst, b, h) do { _Pragma("unroll") for (int m = 0; m < 4; ++m) _Pragma("unroll") for (int k = 0; k < 2; ++k) dst[m][k] = *(const PG8_LAS bf16x8*)(lds + PG8_SA(b, h) + aoff + m * 2048 + k * 1024); } while (0)
; #define PG8_MMA(ai, bj, At, Bt) do { __builtin_amdgcn_s_setprio(1); _Pragma("unroll") for (int m = 0; m < 4; ++m) _Pragma("unroll") for (int n = 0; n < 2; ++n) _Pragma("unroll") for (int k = 0; k < 2; ++k) \
;         acc[ai][bj][m][n] = __builtin_amdgcn_mfma_f32_16x16x32_bf16(Bt[n][k], At[m][k], acc[ai][bj][m][n], 0, 0, 0); __builtin_amdgcn_s_setprio(0); } while (0)
; #define PG8_WAIT_V(n) asm volatile("s_waitcnt vmcnt(" #n ")" ::: "memory")
; #define PG8_WAIT_L(n) asm volatile("s_waitcnt lgkmcnt(" #n ")" ::: "memory")
; #define PG8_BAR __builtin_amdgcn_s_barrier()
; #define PG8_SCHED __builtin_amdgcn_sched_barrier(0)
; template <class Epi, class Sched, bool ALIGN_EPI = false, bool SP2 = false>
; __device__ __forceinline__ void gemm_phase(PG8_LAS unsigned char* lds, const Gemm g, const Sched& S, const Epi& E) {
;     ...
;             PG8_LDA(At, 1, 1); PG8_STAGE(PG8_SB(1, 0), b3, voffB); PG8_STAGE(PG8_SB(1, 1), b3 + hstep, voffB); PG8_STAGE(PG8_SA(1, 0), a3, voffA);
;             PG8_WAIT_V(8); PG8_WAIT_L(0); PG8_BAR; PG8_MMA(1, 0, At, B0); PG8_MMA(1, 1, At, B1); PG8_BAR; PG8_SCHED;
	s_add_i32 s60, s64, s72
	v_lshl_add_u64 v[240:241], v[240:241], 0, s[20:21]
	s_mov_b32 m0, s60
	ds_read_b128 v[180:183], v223 offset:49152
	ds_read_b128 v[198:201], v223 offset:50176
	ds_read_b128 v[202:205], v223 offset:51200
	ds_read_b128 v[206:209], v223 offset:52224
	ds_read_b128 v[224:227], v223 offset:53248
	ds_read_b128 v[228:231], v223 offset:54272
	ds_read_b128 v[232:235], v223 offset:55296
	ds_read_b128 v[236:239], v223 offset:56320
	global_load_lds_dwordx4 v[240:241], off
	s_add_i32 m0, s60, 0x2000
	s_add_u32 s0, s0, 0x20080
	v_lshl_add_u64 v[240:241], v[242:243], 0, s[20:21]
	s_addc_u32 s1, s1, 0
	s_add_i32 s60, s65, s72
	global_load_lds_dwordx4 v[240:241], off
	v_lshl_add_u64 v[240:241], s[0:1], 0, v[0:1]
	s_mov_b32 m0, s60
	s_nop 0
	global_load_lds_dwordx4 v[240:241], off
	v_lshl_add_u64 v[240:241], s[0:1], 0, v[2:3]
	s_add_i32 m0, s60, 0x2000
	s_nop 0
	global_load_lds_dwordx4 v[240:241], off
	v_lshl_add_u64 v[240:241], v[244:245], 0, s[20:21]
	s_mov_b32 m0, s96
	s_nop 0
	global_load_lds_dwordx4 v[240:241], off
	v_lshl_add_u64 v[240:241], v[246:247], 0, s[20:21]
	s_mov_b32 m0, s97
	s_nop 0
	global_load_lds_dwordx4 v[240:241], off
	s_waitcnt vmcnt(8)
	s_waitcnt lgkmcnt(0)
	s_barrier
	s_waitcnt lgkmcnt(0)
	v_mfma_f32_16x16x32_bf16 v[80:83], v[92:95], v[180:183], v[80:83]
	v_mfma_f32_16x16x32_bf16 v[76:79], v[108:111], v[180:183], v[76:79]
	v_mfma_f32_16x16x32_bf16 v[64:67], v[92:95], v[202:205], v[64:67]
	v_mfma_f32_16x16x32_bf16 v[60:63], v[108:111], v[202:205], v[60:63]
	v_mfma_f32_16x16x32_bf16 v[48:51], v[92:95], v[224:227], v[48:51]
	v_mfma_f32_16x16x32_bf16 v[44:47], v[108:111], v[224:227], v[44:47]
	v_mfma_f32_16x16x32_bf16 v[32:35], v[92:95], v[232:235], v[32:35]
	v_mfma_f32_16x16x32_bf16 v[28:31], v[108:111], v[232:235], v[28:31]
	v_mfma_f32_16x16x32_bf16 v[80:83], v[96:99], v[198:201], v[80:83]
	v_mfma_f32_16x16x32_bf16 v[76:79], v[112:115], v[198:201], v[76:79]
	v_mfma_f32_16x16x32_bf16 v[64:67], v[96:99], v[206:209], v[64:67]
	v_mfma_f32_16x16x32_bf16 v[60:63], v[112:115], v[206:209], v[60:63]
	v_mfma_f32_16x16x32_bf16 v[48:51], v[96:99], v[228:231], v[48:51]
	v_mfma_f32_16x16x32_bf16 v[44:47], v[112:115], v[228:231], v[44:47]
	v_mfma_f32_16x16x32_bf16 v[32:35], v[96:99], v[236:239], v[32:35]
	v_mfma_f32_16x16x32_bf16 v[28:31], v[112:115], v[236:239], v[28:31]
	v_mfma_f32_16x16x32_bf16 v[72:75], v[164:167], v[180:183], v[72:75]
	v_mfma_f32_16x16x32_bf16 v[68:71], v[172:175], v[180:183], v[68:71]
	v_mfma_f32_16x16x32_bf16 v[56:59], v[164:167], v[202:205], v[56:59]
	v_mfma_f32_16x16x32_bf16 v[52:55], v[172:175], v[202:205], v[52:55]
	v_mfma_f32_16x16x32_bf16 v[40:43], v[164:167], v[224:227], v[40:43]
	v_mfma_f32_16x16x32_bf16 v[36:39], v[172:175], v[224:227], v[36:39]
	v_mfma_f32_16x16x32_bf16 v[24:27], v[164:167], v[232:235], v[24:27]
	v_mfma_f32_16x16x32_bf16 v[20:23], v[172:175], v[232:235], v[20:23]
	v_mfma_f32_16x16x32_bf16 v[72:75], v[168:171], v[198:201], v[72:75]
	v_mfma_f32_16x16x32_bf16 v[68:71], v[176:179], v[198:201], v[68:71]
	v_mfma_f32_16x16x32_bf16 v[56:59], v[168:171], v[206:209], v[56:59]
	v_mfma_f32_16x16x32_bf16 v[52:55], v[176:179], v[206:209], v[52:55]
	v_mfma_f32_16x16x32_bf16 v[40:43], v[168:171], v[228:231], v[40:43]
	v_mfma_f32_16x16x32_bf16 v[36:39], v[176:179], v[228:231], v[36:39]
	v_mfma_f32_16x16x32_bf16 v[24:27], v[168:171], v[236:239], v[24:27]
	v_mfma_f32_16x16x32_bf16 v[20:23], v[176:179], v[236:239], v[20:23]
	s_barrier
	s_add_i32 s35, s35, 2
	s_add_u32 s54, s54, 0x100
	s_addc_u32 s55, s55, 0
	s_add_u32 s22, s22, 0x100
	s_addc_u32 s23, s23, 0
	s_cmp_gt_u32 s35, 5
	s_cbranch_scc0 .LBB0_559
	s_and_b64 vcc, exec, s[12:13]
	s_cbranch_vccz .LBB0_562
	s_barrier

; #define PG8_STAGE(bufoff, gbase, voff) do { _Pragma("unroll") for (int _i = 0; _i < 2; ++_i) \
;         __builtin_amdgcn_global_load_lds((const unsigned*)((const char*)(gbase) + (voff)[_i]), (PG8_LAS unsigned*)(lds + (bufoff) + ldsw + _i * 8192), 16, 0, 0); } while (0)
; #define PG8_LDA(dst, b, h) do { _Pragma("unroll") for (int m = 0; m < 4; ++m) _Pragma("unroll") for (int k = 0; k < 2; ++k) dst[m][k] = *(const PG8_LAS bf16x8*)(lds + PG8_SA(b, h) + aoff + m * 2048 + k * 1024); } while (0)
; #define PG8_LDB(dst, b, h) do { _Pragma("unroll") for (int n = 0; n < 2; ++n) _Pragma("unroll") for (int k = 0; k < 2; ++k) dst[n][k] = *(const PG8_LAS bf16x8*)(lds + PG8_SB(b, h) + boff + n * 2048 + k * 1024); } while (0)
; #define PG8_MMA(ai, bj, At, Bt) do { __builtin_amdgcn_s_setprio(1); _Pragma("unroll") for (int m = 0; m < 4; ++m) _Pragma("unroll") for (int n = 0; n < 2; ++n) _Pragma("unroll") for (int k = 0; k < 2; ++k) \
;         acc[ai][bj][m][n] = __builtin_amdgcn_mfma_f32_16x16x32_bf16(Bt[n][k], At[m][k], acc[ai][bj][m][n], 0, 0, 0); __builtin_amdgcn_s_setprio(0); } while (0)
; #define PG8_WAIT_V(n) asm volatile("s_waitcnt vmcnt(" #n ")" ::: "memory")
; #define PG8_WAIT_L(n) asm volatile("s_waitcnt lgkmcnt(" #n ")" ::: "memory")
; #define PG8_BAR __builtin_amdgcn_s_barrier()
; #define PG8_SCHED __builtin_amdgcn_sched_barrier(0)
; template <class Epi, class Sched, bool ALIGN_EPI = false, bool SP2 = false>
; __device__ __forceinline__ void gemm_phase(PG8_LAS unsigned char* lds, const Gemm g, const Sched& S, const Epi& E) {
;     ...
;             PG8_LDB(B0, 0, 0); PG8_LDB(B1, 0, 1); PG8_SCHED; PG8_LDA(At, 0, 0); PG8_STAGE(PG8_SA(1, 1), a1 + hstep, voffA);
;             PG8_WAIT_V(8); PG8_WAIT_L(0); PG8_BAR; PG8_MMA(0, 0, At, B0); PG8_MMA(0, 1, At, B1); PG8_BAR; PG8_SCHED;
;             PG8_LDA(At, 0, 1); PG8_STAGE(PG8_SB(0, 0), b2, voffB); PG8_STAGE(PG8_SB(0, 1), b2 + hstep, voffB); PG8_STAGE(PG8_SA(0, 0), a2, voffA);
;             PG8_WAIT_V(8); PG8_WAIT_L(0); PG8_BAR; PG8_MMA(1, 0, At, B0); PG8_MMA(1, 1, At, B1); PG8_BAR; PG8_SCHED;
.LBB0_581:
	s_add_u32 s0, vcc_lo, 0xfffc0080
	s_addc_u32 s1, vcc_hi, -1
	s_add_i32 s61, 0, 0x10000
	s_cmp_eq_u32 s60, 12
	s_cselect_b32 s67, s29, s1
	s_cselect_b32 s66, s73, s0
	v_add_u32_e32 v0, s61, v177
	s_cselect_b32 s1, s17, s35
	s_cselect_b32 s0, s22, s23
	s_add_i32 s84, 0, 0x14000
	ds_read_b128 v[108:111], v0
	ds_read_b128 v[112:115], v0 offset:1024
	ds_read_b128 v[124:127], v0 offset:2048
	ds_read_b128 v[132:135], v0 offset:3072
	v_add_u32_e32 v0, s84, v177
	ds_read_b128 v[180:183], v0
	ds_read_b128 v[190:193], v0 offset:1024
	ds_read_b128 v[194:197], v0 offset:2048
	ds_read_b128 v[198:201], v0 offset:3072
	v_lshl_add_u64 v[174:175], vcc, 0, v[170:171]
	s_add_i32 m0, s19, 0xc000
	ds_read_b128 v[202:205], v179
	ds_read_b128 v[206:209], v179 offset:1024
	ds_read_b128 v[220:223], v179 offset:2048
	ds_read_b128 v[224:227], v179 offset:3072
	ds_read_b128 v[228:231], v179 offset:4096
	ds_read_b128 v[232:235], v179 offset:5120
	ds_read_b128 v[236:239], v179 offset:6144
	ds_read_b128 v[240:243], v179 offset:7168
	global_load_lds_dwordx4 v[174:175], off
	v_lshl_add_u64 v[174:175], vcc, 0, v[172:173]
	s_add_i32 m0, s19, 0xe000
	s_nop 0
	global_load_lds_dwordx4 v[174:175], off
	s_waitcnt vmcnt(8)
	s_waitcnt lgkmcnt(0)
	s_barrier
	s_waitcnt lgkmcnt(0)
	v_mfma_f32_16x16x32_bf16 v[156:159], v[108:111], v[202:205], v[156:159]
	v_mfma_f32_16x16x32_bf16 v[160:163], v[124:127], v[202:205], v[160:163]
	v_mfma_f32_16x16x32_bf16 v[140:143], v[108:111], v[220:223], v[140:143]
	v_mfma_f32_16x16x32_bf16 v[144:147], v[124:127], v[220:223], v[144:147]
	v_mfma_f32_16x16x32_bf16 v[116:119], v[108:111], v[228:231], v[116:119]
	v_mfma_f32_16x16x32_bf16 v[120:123], v[124:127], v[228:231], v[120:123]
	v_mfma_f32_16x16x32_bf16 v[92:95], v[108:111], v[236:239], v[92:95]
	v_mfma_f32_16x16x32_bf16 v[96:99], v[124:127], v[236:239], v[96:99]
	v_mfma_f32_16x16x32_bf16 v[156:159], v[112:115], v[206:209], v[156:159]
	v_mfma_f32_16x16x32_bf16 v[160:163], v[132:135], v[206:209], v[160:163]
	v_mfma_f32_16x16x32_bf16 v[140:143], v[112:115], v[224:227], v[140:143]
	v_mfma_f32_16x16x32_bf16 v[144:147], v[132:135], v[224:227], v[144:147]
	v_mfma_f32_16x16x32_bf16 v[116:119], v[112:115], v[232:235], v[116:119]
	v_mfma_f32_16x16x32_bf16 v[120:123], v[132:135], v[232:235], v[120:123]
	v_mfma_f32_16x16x32_bf16 v[92:95], v[112:115], v[240:243], v[92:95]
	v_mfma_f32_16x16x32_bf16 v[96:99], v[132:135], v[240:243], v[96:99]
	v_mfma_f32_16x16x32_bf16 v[148:151], v[180:183], v[202:205], v[148:151]
	v_mfma_f32_16x16x32_bf16 v[152:155], v[194:197], v[202:205], v[152:155]
	v_mfma_f32_16x16x32_bf16 v[128:131], v[180:183], v[220:223], v[128:131]
	v_mfma_f32_16x16x32_bf16 v[136:139], v[194:197], v[220:223], v[136:139]
	v_mfma_f32_16x16x32_bf16 v[100:103], v[180:183], v[228:231], v[100:103]
	v_mfma_f32_16x16x32_bf16 v[104:107], v[194:197], v[228:231], v[104:107]
	v_mfma_f32_16x16x32_bf16 v[84:87], v[180:183], v[236:239], v[84:87]
	v_mfma_f32_16x16x32_bf16 v[88:91], v[194:197], v[236:239], v[88:91]
	v_mfma_f32_16x16x32_bf16 v[148:151], v[190:193], v[206:209], v[148:151]
	v_mfma_f32_16x16x32_bf16 v[152:155], v[198:201], v[206:209], v[152:155]
	v_mfma_f32_16x16x32_bf16 v[128:131], v[190:193], v[224:227], v[128:131]
	v_mfma_f32_16x16x32_bf16 v[136:139], v[198:201], v[224:227], v[136:139]
	v_mfma_f32_16x16x32_bf16 v[100:103], v[190:193], v[232:235], v[100:103]
	v_mfma_f32_16x16x32_bf16 v[104:107], v[198:201], v[232:235], v[104:107]
	v_mfma_f32_16x16x32_bf16 v[84:87], v[190:193], v[240:243], v[84:87]
	v_mfma_f32_16x16x32_bf16 v[88:91], v[198:201], v[240:243], v[88:91]
	s_barrier
	s_add_i32 s61, s61, s62
	v_lshl_add_u64 v[174:175], s[0:1], 0, v[164:165]
	s_mov_b32 m0, s61
	ds_read_b128 v[202:205], v179 offset:16384
	ds_read_b128 v[206:209], v179 offset:17408
	ds_read_b128 v[220:223], v179 offset:18432
	ds_read_b128 v[224:227], v179 offset:19456
	ds_read_b128 v[228:231], v179 offset:20480
	ds_read_b128 v[232:235], v179 offset:21504
	ds_read_b128 v[236:239], v179 offset:22528
	ds_read_b128 v[240:243], v179 offset:23552
	global_load_lds_dwordx4 v[174:175], off
	s_add_i32 m0, s61, 0x2000
	s_add_u32 s64, s0, 0x40000
	v_lshl_add_u64 v[244:245], s[0:1], 0, v[168:169]
	s_addc_u32 s65, s1, 0
	s_add_i32 s61, s84, s62
	global_load_lds_dwordx4 v[244:245], off
	v_lshl_add_u64 v[246:247], s[64:65], 0, v[164:165]
	s_mov_b32 m0, s61
	v_lshl_add_u64 v[248:249], s[66:67], 0, v[166:167]
	global_load_lds_dwordx4 v[246:247], off
	v_lshl_add_u64 v[246:247], s[64:65], 0, v[168:169]
	s_add_i32 m0, s61, 0x2000
	s_nop 0
	global_load_lds_dwordx4 v[246:247], off
	v_lshl_add_u64 v[246:247], s[66:67], 0, v[2:3]
	s_mov_b32 m0, s19
	s_nop 0
	global_load_lds_dwordx4 v[246:247], off
	s_mov_b32 m0, s63
	s_nop 0
	global_load_lds_dwordx4 v[248:249], off
	s_waitcnt vmcnt(8)
	s_waitcnt lgkmcnt(0)
	s_barrier
; #define PG8_STAGE(bufoff, gbase, voff) do { _Pragma("unroll") for (int _i = 0; _i < 2; ++_i) \
;         __builtin_amdgcn_global_load_lds((const unsigned*)((const char*)(gbase) + (voff)[_i]), (PG8_LAS unsigned*)(lds + (bufoff) + ldsw + _i * 8192), 16, 0, 0); } while (0)
; #define PG8_LDA(dst, b, h) do { _Pragma("unroll") for (int m = 0; m < 4; ++m) _Pragma("unroll") for (int k = 0; k < 2; ++k) dst[m][k] = *(const PG8_LAS bf16x8*)(lds + PG8_SA(b, h) + aoff + m * 2048 + k * 1024); } while (0)
; #define PG8_LDB(dst, b, h) do { _Pragma("unroll") for (int n = 0; n < 2; ++n) _Pragma("unroll") for (int k = 0; k < 2; ++k) dst[n][k] = *(const PG8_LAS bf16x8*)(lds + PG8_SB(b, h) + boff + n * 2048 + k * 1024); } while (0)
; #define PG8_MMA(ai, bj, At, Bt) do { __builtin_amdgcn_s_setprio(1); _Pragma("unroll") for (int m = 0; m < 4; ++m) _Pragma("unroll") for (int n = 0; n < 2; ++n) _Pragma("unroll") for (int k = 0; k < 2; ++k) \
;         acc[ai][bj][m][n] = __builtin_amdgcn_mfma_f32_16x16x32_bf16(Bt[n][k], At[m][k], acc[ai][bj][m][n], 0, 0, 0); __builtin_amdgcn_s_setprio(0); } while (0)
; #define PG8_WAIT_V(n) asm volatile("s_waitcnt vmcnt(" #n ")" ::: "memory")
; #define PG8_WAIT_L(n) asm volatile("s_waitcnt lgkmcnt(" #n ")" ::: "memory")
; #define PG8_BAR __builtin_amdgcn_s_barrier()
; #define PG8_SCHED __builtin_amdgcn_sched_barrier(0)
; template <class Epi, class Sched, bool ALIGN_EPI = false, bool SP2 = false>
; __device__ __forceinline__ void gemm_phase(PG8_LAS unsigned char* lds, const Gemm g, const Sched& S, const Epi& E) {
;     ...
;             PG8_WAIT_V(8); PG8_WAIT_L(0); PG8_BAR; PG8_MMA(1, 0, At, B0); PG8_MMA(1, 1, At, B1); PG8_BAR; PG8_SCHED;
;             PG8_LDB(B0, 1, 0); PG8_LDB(B1, 1, 1); PG8_SCHED; PG8_LDA(At, 1, 0); PG8_STAGE(PG8_SA(0, 1), a2 + hstep, voffA);
;             PG8_WAIT_V(8); PG8_WAIT_L(0); PG8_BAR; PG8_MMA(0, 0, At, B0); PG8_MMA(0, 1, At, B1); PG8_BAR; PG8_SCHED;
	s_waitcnt lgkmcnt(0)
	v_mfma_f32_16x16x32_bf16 v[76:79], v[108:111], v[202:205], v[76:79]
	v_mfma_f32_16x16x32_bf16 v[80:83], v[124:127], v[202:205], v[80:83]
	v_mfma_f32_16x16x32_bf16 v[60:63], v[108:111], v[220:223], v[60:63]
	v_mfma_f32_16x16x32_bf16 v[64:67], v[124:127], v[220:223], v[64:67]
	v_mfma_f32_16x16x32_bf16 v[44:47], v[108:111], v[228:231], v[44:47]
	v_mfma_f32_16x16x32_bf16 v[48:51], v[124:127], v[228:231], v[48:51]
	v_mfma_f32_16x16x32_bf16 v[28:31], v[108:111], v[236:239], v[28:31]
	v_mfma_f32_16x16x32_bf16 v[32:35], v[124:127], v[236:239], v[32:35]
	v_mfma_f32_16x16x32_bf16 v[76:79], v[112:115], v[206:209], v[76:79]
	v_mfma_f32_16x16x32_bf16 v[80:83], v[132:135], v[206:209], v[80:83]
	v_mfma_f32_16x16x32_bf16 v[60:63], v[112:115], v[224:227], v[60:63]
	v_mfma_f32_16x16x32_bf16 v[64:67], v[132:135], v[224:227], v[64:67]
	v_mfma_f32_16x16x32_bf16 v[44:47], v[112:115], v[232:235], v[44:47]
	v_mfma_f32_16x16x32_bf16 v[48:51], v[132:135], v[232:235], v[48:51]
	v_mfma_f32_16x16x32_bf16 v[28:31], v[112:115], v[240:243], v[28:31]
	v_mfma_f32_16x16x32_bf16 v[32:35], v[132:135], v[240:243], v[32:35]
	v_mfma_f32_16x16x32_bf16 v[68:71], v[180:183], v[202:205], v[68:71]
	v_mfma_f32_16x16x32_bf16 v[72:75], v[194:197], v[202:205], v[72:75]
	v_mfma_f32_16x16x32_bf16 v[52:55], v[180:183], v[220:223], v[52:55]
	v_mfma_f32_16x16x32_bf16 v[56:59], v[194:197], v[220:223], v[56:59]
	v_mfma_f32_16x16x32_bf16 v[36:39], v[180:183], v[228:231], v[36:39]
	v_mfma_f32_16x16x32_bf16 v[40:43], v[194:197], v[228:231], v[40:43]
	v_mfma_f32_16x16x32_bf16 v[20:23], v[180:183], v[236:239], v[20:23]
	v_mfma_f32_16x16x32_bf16 v[24:27], v[194:197], v[236:239], v[24:27]
	v_mfma_f32_16x16x32_bf16 v[68:71], v[190:193], v[206:209], v[68:71]
	v_mfma_f32_16x16x32_bf16 v[72:75], v[198:201], v[206:209], v[72:75]
	v_mfma_f32_16x16x32_bf16 v[52:55], v[190:193], v[224:227], v[52:55]
	v_mfma_f32_16x16x32_bf16 v[56:59], v[198:201], v[224:227], v[56:59]
	v_mfma_f32_16x16x32_bf16 v[36:39], v[190:193], v[232:235], v[36:39]
	v_mfma_f32_16x16x32_bf16 v[40:43], v[198:201], v[232:235], v[40:43]
	v_mfma_f32_16x16x32_bf16 v[20:23], v[190:193], v[240:243], v[20:23]
	v_mfma_f32_16x16x32_bf16 v[24:27], v[198:201], v[240:243], v[24:27]
	s_barrier
	s_add_i32 s61, 0, 0x18000
	v_add_u32_e32 v0, s61, v177
	s_add_i32 s84, 0, 0x1c000
	ds_read_b128 v[108:111], v0
	ds_read_b128 v[112:115], v0 offset:1024
	ds_read_b128 v[124:127], v0 offset:2048
	ds_read_b128 v[132:135], v0 offset:3072
	v_add_u32_e32 v0, s84, v177
	ds_read_b128 v[180:183], v0
	ds_read_b128 v[190:193], v0 offset:1024
	ds_read_b128 v[194:197], v0 offset:2048
	ds_read_b128 v[198:201], v0 offset:3072
	s_add_u32 s64, s66, 0x40000
	s_addc_u32 s65, s67, 0
	s_mov_b32 m0, s75
	v_lshl_add_u64 v[250:251], s[64:65], 0, v[2:3]
	ds_read_b128 v[202:205], v179 offset:32768
	ds_read_b128 v[206:209], v179 offset:33792
	ds_read_b128 v[220:223], v179 offset:34816
	ds_read_b128 v[224:227], v179 offset:35840
	ds_read_b128 v[228:231], v179 offset:36864
	ds_read_b128 v[232:235], v179 offset:37888
	ds_read_b128 v[236:239], v179 offset:38912
	ds_read_b128 v[240:243], v179 offset:39936
	global_load_lds_dwordx4 v[250:251], off
	v_lshl_add_u64 v[250:251], s[64:65], 0, v[166:167]
	s_mov_b32 m0, s94
	s_nop 0
	global_load_lds_dwordx4 v[250:251], off
	s_waitcnt vmcnt(8)
	s_waitcnt lgkmcnt(0)
	s_barrier
	s_waitcnt lgkmcnt(0)
	v_mfma_f32_16x16x32_bf16 v[156:159], v[108:111], v[202:205], v[156:159]
	v_mfma_f32_16x16x32_bf16 v[160:163], v[124:127], v[202:205], v[160:163]
	v_mfma_f32_16x16x32_bf16 v[140:143], v[108:111], v[220:223], v[140:143]
	v_mfma_f32_16x16x32_bf16 v[144:147], v[124:127], v[220:223], v[144:147]
	v_mfma_f32_16x16x32_bf16 v[116:119], v[108:111], v[228:231], v[116:119]
	v_mfma_f32_16x16x32_bf16 v[120:123], v[124:127], v[228:231], v[120:123]
	v_mfma_f32_16x16x32_bf16 v[92:95], v[108:111], v[236:239], v[92:95]
	v_mfma_f32_16x16x32_bf16 v[96:99], v[124:127], v[236:239], v[96:99]
	v_mfma_f32_16x16x32_bf16 v[156:159], v[112:115], v[206:209], v[156:159]
	v_mfma_f32_16x16x32_bf16 v[160:163], v[132:135], v[206:209], v[160:163]
	v_mfma_f32_16x16x32_bf16 v[140:143], v[112:115], v[224:227], v[140:143]
	v_mfma_f32_16x16x32_bf16 v[144:147], v[132:135], v[224:227], v[144:147]
	v_mfma_f32_16x16x32_bf16 v[116:119], v[112:115], v[232:235], v[116:119]
	v_mfma_f32_16x16x32_bf16 v[120:123], v[132:135], v[232:235], v[120:123]
	v_mfma_f32_16x16x32_bf16 v[92:95], v[112:115], v[240:243], v[92:95]
	v_mfma_f32_16x16x32_bf16 v[96:99], v[132:135], v[240:243], v[96:99]
	v_mfma_f32_16x16x32_bf16 v[148:151], v[180:183], v[202:205], v[148:151]
	v_mfma_f32_16x16x32_bf16 v[152:155], v[194:197], v[202:205], v[152:155]
	v_mfma_f32_16x16x32_bf16 v[128:131], v[180:183], v[220:223], v[128:131]
	v_mfma_f32_16x16x32_bf16 v[136:139], v[194:197], v[220:223], v[136:139]
	v_mfma_f32_16x16x32_bf16 v[100:103], v[180:183], v[228:231], v[100:103]
	v_mfma_f32_16x16x32_bf16 v[104:107], v[194:197], v[228:231], v[104:107]
	v_mfma_f32_16x16x32_bf16 v[84:87], v[180:183], v[236:239], v[84:87]
	v_mfma_f32_16x16x32_bf16 v[88:91], v[194:197], v[236:239], v[88:91]
	v_mfma_f32_16x16x32_bf16 v[148:151], v[190:193], v[206:209], v[148:151]
	v_mfma_f32_16x16x32_bf16 v[152:155], v[198:201], v[206:209], v[152:155]
	v_mfma_f32_16x16x32_bf16 v[128:131], v[190:193], v[224:227], v[128:131]
	v_mfma_f32_16x16x32_bf16 v[136:139], v[198:201], v[224:227], v[136:139]
	v_mfma_f32_16x16x32_bf16 v[100:103], v[190:193], v[232:235], v[100:103]
	v_mfma_f32_16x16x32_bf16 v[104:107], v[198:201], v[232:235], v[104:107]
	v_mfma_f32_16x16x32_bf16 v[84:87], v[190:193], v[240:243], v[84:87]
	v_mfma_f32_16x16x32_bf16 v[88:91], v[198:201], v[240:243], v[88:91]
	s_barrier
; #define PG8_STAGE(bufoff, gbase, voff) do { _Pragma("unroll") for (int _i = 0; _i < 2; ++_i) \
;         __builtin_amdgcn_global_load_lds((const unsigned*)((const char*)(gbase) + (voff)[_i]), (PG8_LAS unsigned*)(lds + (bufoff) + ldsw + _i * 8192), 16, 0, 0); } while (0)
; #define PG8_LDA(dst, b, h) do { _Pragma("unroll") for (int m = 0; m < 4; ++m) _Pragma("unroll") for (int k = 0; k < 2; ++k) dst[m][k] = *(const PG8_LAS bf16x8*)(lds + PG8_SA(b, h) + aoff + m * 2048 + k * 1024); } while (0)
; #define PG8_MMA(ai, bj, At, Bt) do { __builtin_amdgcn_s_setprio(1); _Pragma("unroll") for (int m = 0; m < 4; ++m) _Pragma("unroll") for (int n = 0; n < 2; ++n) _Pragma("unroll") for (int k = 0; k < 2; ++k) \
;         acc[ai][bj][m][n] = __builtin_amdgcn_mfma_f32_16x16x32_bf16(Bt[n][k], At[m][k], acc[ai][bj][m][n], 0, 0, 0); __builtin_amdgcn_s_setprio(0); } while (0)
; #define PG8_WAIT_V(n) asm volatile("s_waitcnt vmcnt(" #n ")" ::: "memory")
; #define PG8_WAIT_L(n) asm volatile("s_waitcnt lgkmcnt(" #n ")" ::: "memory")
; #define PG8_BAR __builtin_amdgcn_s_barrier()
; #define PG8_SCHED __builtin_amdgcn_sched_barrier(0)
; template <class Epi, class Sched, bool ALIGN_EPI = false, bool SP2 = false>
; __device__ __forceinline__ void gemm_phase(PG8_LAS unsigned char* lds, const Gemm g, const Sched& S, const Epi& E) {
;     ...
;             PG8_LDA(At, 1, 1); PG8_STAGE(PG8_SB(1, 0), b3, voffB); PG8_STAGE(PG8_SB(1, 1), b3 + hstep, voffB); PG8_STAGE(PG8_SA(1, 0), a3, voffA);
;             PG8_WAIT_V(8); PG8_WAIT_L(0); PG8_BAR; PG8_MMA(1, 0, At, B0); PG8_MMA(1, 1, At, B1); PG8_BAR; PG8_SCHED;
	s_add_i32 s61, s61, s62
	v_lshl_add_u64 v[174:175], v[174:175], 0, s[20:21]
	s_mov_b32 m0, s61
	ds_read_b128 v[202:205], v179 offset:49152
	ds_read_b128 v[206:209], v179 offset:50176
	ds_read_b128 v[220:223], v179 offset:51200
	ds_read_b128 v[224:227], v179 offset:52224
	ds_read_b128 v[228:231], v179 offset:53248
	ds_read_b128 v[232:235], v179 offset:54272
	ds_read_b128 v[236:239], v179 offset:55296
	ds_read_b128 v[240:243], v179 offset:56320
	global_load_lds_dwordx4 v[174:175], off
	s_add_i32 m0, s61, 0x2000
	s_add_u32 s0, s0, 0x40080
	v_lshl_add_u64 v[174:175], v[244:245], 0, s[20:21]
	s_addc_u32 s1, s1, 0
	s_add_i32 s61, s84, s62
	global_load_lds_dwordx4 v[174:175], off
	v_lshl_add_u64 v[174:175], s[0:1], 0, v[164:165]
	s_mov_b32 m0, s61
	s_nop 0
	global_load_lds_dwordx4 v[174:175], off
	v_lshl_add_u64 v[174:175], s[0:1], 0, v[168:169]
	s_add_i32 m0, s61, 0x2000
	s_nop 0
	global_load_lds_dwordx4 v[174:175], off
	v_lshl_add_u64 v[174:175], v[246:247], 0, s[20:21]
	s_mov_b32 m0, s95
	s_nop 0
	global_load_lds_dwordx4 v[174:175], off
	v_lshl_add_u64 v[174:175], v[248:249], 0, s[20:21]
	s_mov_b32 m0, s96
	s_nop 0
	global_load_lds_dwordx4 v[174:175], off
	s_waitcnt vmcnt(8)
	s_waitcnt lgkmcnt(0)
	s_barrier
	s_waitcnt lgkmcnt(0)
	v_mfma_f32_16x16x32_bf16 v[76:79], v[108:111], v[202:205], v[76:79]
	v_mfma_f32_16x16x32_bf16 v[80:83], v[124:127], v[202:205], v[80:83]
	v_mfma_f32_16x16x32_bf16 v[60:63], v[108:111], v[220:223], v[60:63]
	v_mfma_f32_16x16x32_bf16 v[64:67], v[124:127], v[220:223], v[64:67]
	v_mfma_f32_16x16x32_bf16 v[44:47], v[108:111], v[228:231], v[44:47]
	v_mfma_f32_16x16x32_bf16 v[48:51], v[124:127], v[228:231], v[48:51]
	v_mfma_f32_16x16x32_bf16 v[28:31], v[108:111], v[236:239], v[28:31]
	v_mfma_f32_16x16x32_bf16 v[32:35], v[124:127], v[236:239], v[32:35]
	v_mfma_f32_16x16x32_bf16 v[76:79], v[112:115], v[206:209], v[76:79]
	v_mfma_f32_16x16x32_bf16 v[80:83], v[132:135], v[206:209], v[80:83]
	v_mfma_f32_16x16x32_bf16 v[60:63], v[112:115], v[224:227], v[60:63]
	v_mfma_f32_16x16x32_bf16 v[64:67], v[132:135], v[224:227], v[64:67]
	v_mfma_f32_16x16x32_bf16 v[44:47], v[112:115], v[232:235], v[44:47]
	v_mfma_f32_16x16x32_bf16 v[48:51], v[132:135], v[232:235], v[48:51]
	v_mfma_f32_16x16x32_bf16 v[28:31], v[112:115], v[240:243], v[28:31]
	v_mfma_f32_16x16x32_bf16 v[32:35], v[132:135], v[240:243], v[32:35]
	v_mfma_f32_16x16x32_bf16 v[68:71], v[180:183], v[202:205], v[68:71]
	v_mfma_f32_16x16x32_bf16 v[72:75], v[194:197], v[202:205], v[72:75]
	v_mfma_f32_16x16x32_bf16 v[52:55], v[180:183], v[220:223], v[52:55]
	v_mfma_f32_16x16x32_bf16 v[56:59], v[194:197], v[220:223], v[56:59]
	v_mfma_f32_16x16x32_bf16 v[36:39], v[180:183], v[228:231], v[36:39]
	v_mfma_f32_16x16x32_bf16 v[40:43], v[194:197], v[228:231], v[40:43]
	v_mfma_f32_16x16x32_bf16 v[20:23], v[180:183], v[236:239], v[20:23]
	v_mfma_f32_16x16x32_bf16 v[24:27], v[194:197], v[236:239], v[24:27]
	v_mfma_f32_16x16x32_bf16 v[68:71], v[190:193], v[206:209], v[68:71]
	v_mfma_f32_16x16x32_bf16 v[72:75], v[198:201], v[206:209], v[72:75]
	v_mfma_f32_16x16x32_bf16 v[52:55], v[190:193], v[224:227], v[52:55]
	v_mfma_f32_16x16x32_bf16 v[56:59], v[198:201], v[224:227], v[56:59]
	v_mfma_f32_16x16x32_bf16 v[36:39], v[190:193], v[232:235], v[36:39]
	v_mfma_f32_16x16x32_bf16 v[40:43], v[198:201], v[232:235], v[40:43]
	v_mfma_f32_16x16x32_bf16 v[20:23], v[190:193], v[240:243], v[20:23]
	v_mfma_f32_16x16x32_bf16 v[24:27], v[198:201], v[240:243], v[24:27]
	s_barrier
	s_add_i32 s60, s60, 2
	s_add_u32 vcc_lo, vcc_lo, 0x100
	s_addc_u32 vcc_hi, vcc_hi, 0
	s_add_u32 s23, s23, 0x100
	s_addc_u32 s35, s35, 0
	s_cmp_gt_u32 s60, 13
	s_cbranch_scc0 .LBB0_581
	s_and_b64 vcc, exec, s[12:13]
	s_mov_b32 s73, 0x10000
	s_cbranch_vccz .LBB0_584
	s_barrier

; #define PG8_STAGE(bufoff, gbase, voff) do { _Pragma("unroll") for (int _i = 0; _i < 2; ++_i) \
;         __builtin_amdgcn_global_load_lds((const unsigned*)((const char*)(gbase) + (voff)[_i]), (PG8_LAS unsigned*)(lds + (bufoff) + ldsw + _i * 8192), 16, 0, 0); } while (0)
; #define PG8_LDA(dst, b, h) do { _Pragma("unroll") for (int m = 0; m < 4; ++m) _Pragma("unroll") for (int k = 0; k < 2; ++k) dst[m][k] = *(const PG8_LAS bf16x8*)(lds + PG8_SA(b, h) + aoff + m * 2048 + k * 1024); } while (0)
; #define PG8_LDB(dst, b, h) do { _Pragma("unroll") for (int n = 0; n < 2; ++n) _Pragma("unroll") for (int k = 0; k < 2; ++k) dst[n][k] = *(const PG8_LAS bf16x8*)(lds + PG8_SB(b, h) + boff + n * 2048 + k * 1024); } while (0)
; #define PG8_MMA(ai, bj, At, Bt) do { __builtin_amdgcn_s_setprio(1); _Pragma("unroll") for (int m = 0; m < 4; ++m) _Pragma("unroll") for (int n = 0; n < 2; ++n) _Pragma("unroll") for (int k = 0; k < 2; ++k) \
;         acc[ai][bj][m][n] = __builtin_amdgcn_mfma_f32_16x16x32_bf16(Bt[n][k], At[m][k], acc[ai][bj][m][n], 0, 0, 0); __builtin_amdgcn_s_setprio(0); } while (0)
; #define PG8_WAIT_V(n) asm volatile("s_waitcnt vmcnt(" #n ")" ::: "memory")
; #define PG8_WAIT_L(n) asm volatile("s_waitcnt lgkmcnt(" #n ")" ::: "memory")
; template <class Epi, class Sched, bool ALIGN_EPI = false, bool SP2 = false>
; __device__ __forceinline__ void gemm_phase(PG8_LAS unsigned char* lds, const Gemm g, const Sched& S, const Epi& E) {
;     ...
;             const bool last = (t == nt - 2);
;             const char* a1 = cA + (size_t)(t + 1) * kstep;
;             const char* a2 = last ? nA : cA + (size_t)(t + 2) * kstep; const char* b2 = last ? nB : cB + (size_t)(t + 2) * kstep;
;             const char* a3 = a2 + kstep; const char* b3 = b2 + kstep;
;             if (last && has_next) S.a_ready(nxt);
;             if constexpr (SP2) {
;             PG8_LDB(B0, 0, 0); PG8_LDB(B1, 0, 1); PG8_SCHED; PG8_LDA(At, 0, 0); PG8_STAGE(PG8_SA(1, 1), a1 + hstep, voffA);
;             PG8_WAIT_V(8); PG8_WAIT_L(0); PG8_BAR; PG8_MMA(0, 0, At, B0); PG8_MMA(0, 1, At, B1); PG8_BAR; PG8_SCHED;
;             PG8_LDA(At, 0, 1); PG8_STAGE(PG8_SB(0, 0), b2, voffB); PG8_STAGE(PG8_SB(0, 1), b2 + hstep, voffB); PG8_STAGE(PG8_SA(0, 0), a2, voffA);
;             PG8_WAIT_V(8); PG8_WAIT_L(0); PG8_BAR; PG8_MMA(1, 0, At, B0); PG8_MMA(1, 1, At, B1); PG8_BAR; PG8_SCHED;
.LBB0_676:
	s_add_u32 s0, s18, 0xfffe0080
	s_addc_u32 s1, s19, -1
	s_add_i32 s61, 0, 0x10000
	s_cmp_eq_u32 s60, 4
	s_cselect_b32 s25, s13, s1
	s_cselect_b32 s24, s67, s0
	v_add_u32_e32 v160, s61, v163
	s_cselect_b32 s1, s11, s35
	s_cselect_b32 s0, s22, s23
	s_add_i32 s72, 0, 0x14000
	ds_read_b128 v[156:159], v160
	ds_read_b128 v[166:169], v160 offset:1024
	ds_read_b128 v[170:173], v160 offset:2048
	ds_read_b128 v[174:177], v160 offset:3072
	v_add_u32_e32 v160, s72, v163
	ds_read_b128 v[178:181], v160
	ds_read_b128 v[190:193], v160 offset:1024
	ds_read_b128 v[194:197], v160 offset:2048
	ds_read_b128 v[198:201], v160 offset:3072
	v_lshl_add_u64 v[160:161], s[18:19], 0, v[152:153]
	s_add_i32 m0, s56, 0xc000
	ds_read_b128 v[202:205], v165
	ds_read_b128 v[206:209], v165 offset:1024
	ds_read_b128 v[220:223], v165 offset:2048
	ds_read_b128 v[224:227], v165 offset:3072
	ds_read_b128 v[228:231], v165 offset:4096
	ds_read_b128 v[232:235], v165 offset:5120
	ds_read_b128 v[236:239], v165 offset:6144
	ds_read_b128 v[240:243], v165 offset:7168
	global_load_lds_dwordx4 v[160:161], off
	v_lshl_add_u64 v[160:161], s[18:19], 0, v[154:155]
	s_add_i32 m0, s56, 0xe000
	s_nop 0
	global_load_lds_dwordx4 v[160:161], off
	s_waitcnt vmcnt(8)
	s_waitcnt lgkmcnt(0)
	s_barrier
	s_waitcnt lgkmcnt(0)
	v_mfma_f32_16x16x32_bf16 v[144:147], v[156:159], v[202:205], v[144:147]
	v_mfma_f32_16x16x32_bf16 v[140:143], v[170:173], v[202:205], v[140:143]
	v_mfma_f32_16x16x32_bf16 v[132:135], v[156:159], v[220:223], v[132:135]
	v_mfma_f32_16x16x32_bf16 v[124:127], v[170:173], v[220:223], v[124:127]
	v_mfma_f32_16x16x32_bf16 v[116:119], v[156:159], v[228:231], v[116:119]
	v_mfma_f32_16x16x32_bf16 v[108:111], v[170:173], v[228:231], v[108:111]
	v_mfma_f32_16x16x32_bf16 v[100:103], v[156:159], v[236:239], v[100:103]
	v_mfma_f32_16x16x32_bf16 v[92:95], v[170:173], v[236:239], v[92:95]
	v_mfma_f32_16x16x32_bf16 v[144:147], v[166:169], v[206:209], v[144:147]
	v_mfma_f32_16x16x32_bf16 v[140:143], v[174:177], v[206:209], v[140:143]
	v_mfma_f32_16x16x32_bf16 v[132:135], v[166:169], v[224:227], v[132:135]
	v_mfma_f32_16x16x32_bf16 v[124:127], v[174:177], v[224:227], v[124:127]
	v_mfma_f32_16x16x32_bf16 v[116:119], v[166:169], v[232:235], v[116:119]
	v_mfma_f32_16x16x32_bf16 v[108:111], v[174:177], v[232:235], v[108:111]
	v_mfma_f32_16x16x32_bf16 v[100:103], v[166:169], v[240:243], v[100:103]
	v_mfma_f32_16x16x32_bf16 v[92:95], v[174:177], v[240:243], v[92:95]
	v_mfma_f32_16x16x32_bf16 v[136:139], v[178:181], v[202:205], v[136:139]
	v_mfma_f32_16x16x32_bf16 v[128:131], v[194:197], v[202:205], v[128:131]
	v_mfma_f32_16x16x32_bf16 v[120:123], v[178:181], v[220:223], v[120:123]
	v_mfma_f32_16x16x32_bf16 v[112:115], v[194:197], v[220:223], v[112:115]
	v_mfma_f32_16x16x32_bf16 v[104:107], v[178:181], v[228:231], v[104:107]
	v_mfma_f32_16x16x32_bf16 v[96:99], v[194:197], v[228:231], v[96:99]
	v_mfma_f32_16x16x32_bf16 v[88:91], v[178:181], v[236:239], v[88:91]
	v_mfma_f32_16x16x32_bf16 v[84:87], v[194:197], v[236:239], v[84:87]
	v_mfma_f32_16x16x32_bf16 v[136:139], v[190:193], v[206:209], v[136:139]
	v_mfma_f32_16x16x32_bf16 v[128:131], v[198:201], v[206:209], v[128:131]
	v_mfma_f32_16x16x32_bf16 v[120:123], v[190:193], v[224:227], v[120:123]
	v_mfma_f32_16x16x32_bf16 v[112:115], v[198:201], v[224:227], v[112:115]
	v_mfma_f32_16x16x32_bf16 v[104:107], v[190:193], v[232:235], v[104:107]
	v_mfma_f32_16x16x32_bf16 v[96:99], v[198:201], v[232:235], v[96:99]
	v_mfma_f32_16x16x32_bf16 v[88:91], v[190:193], v[240:243], v[88:91]
	v_mfma_f32_16x16x32_bf16 v[84:87], v[198:201], v[240:243], v[84:87]
	s_barrier
	s_add_i32 s61, s61, s55
	v_lshl_add_u64 v[160:161], s[0:1], 0, v[0:1]
	s_mov_b32 m0, s61
	ds_read_b128 v[202:205], v165 offset:16384
	ds_read_b128 v[206:209], v165 offset:17408
	ds_read_b128 v[220:223], v165 offset:18432
	ds_read_b128 v[224:227], v165 offset:19456
	ds_read_b128 v[228:231], v165 offset:20480
	ds_read_b128 v[232:235], v165 offset:21504
	ds_read_b128 v[236:239], v165 offset:22528
	ds_read_b128 v[240:243], v165 offset:23552
	global_load_lds_dwordx4 v[160:161], off
	s_add_i32 m0, s61, 0x2000
	s_add_u32 s64, s0, 0x20000
	v_lshl_add_u64 v[182:183], s[0:1], 0, v[2:3]
	s_addc_u32 s65, s1, 0
	s_add_i32 s61, s72, s55
	global_load_lds_dwordx4 v[182:183], off
	v_lshl_add_u64 v[244:245], s[64:65], 0, v[0:1]
	s_mov_b32 m0, s61
	v_lshl_add_u64 v[246:247], s[24:25], 0, v[148:149]
	global_load_lds_dwordx4 v[244:245], off
	v_lshl_add_u64 v[244:245], s[64:65], 0, v[2:3]
	s_add_i32 m0, s61, 0x2000
	s_nop 0
	global_load_lds_dwordx4 v[244:245], off
	v_lshl_add_u64 v[244:245], s[24:25], 0, v[150:151]
	s_mov_b32 m0, s56
	s_nop 0
	global_load_lds_dwordx4 v[244:245], off
	s_mov_b32 m0, s57
	s_nop 0
	global_load_lds_dwordx4 v[246:247], off
	s_waitcnt vmcnt(8)
	s_waitcnt lgkmcnt(0)
	s_barrier
; #define PG8_STAGE(bufoff, gbase, voff) do { _Pragma("unroll") for (int _i = 0; _i < 2; ++_i) \
;         __builtin_amdgcn_global_load_lds((const unsigned*)((const char*)(gbase) + (voff)[_i]), (PG8_LAS unsigned*)(lds + (bufoff) + ldsw + _i * 8192), 16, 0, 0); } while (0)
; #define PG8_LDA(dst, b, h) do { _Pragma("unroll") for (int m = 0; m < 4; ++m) _Pragma("unroll") for (int k = 0; k < 2; ++k) dst[m][k] = *(const PG8_LAS bf16x8*)(lds + PG8_SA(b, h) + aoff + m * 2048 + k * 1024); } while (0)
; #define PG8_LDB(dst, b, h) do { _Pragma("unroll") for (int n = 0; n < 2; ++n) _Pragma("unroll") for (int k = 0; k < 2; ++k) dst[n][k] = *(const PG8_LAS bf16x8*)(lds + PG8_SB(b, h) + boff + n * 2048 + k * 1024); } while (0)
; #define PG8_MMA(ai, bj, At, Bt) do { __builtin_amdgcn_s_setprio(1); _Pragma("unroll") for (int m = 0; m < 4; ++m) _Pragma("unroll") for (int n = 0; n < 2; ++n) _Pragma("unroll") for (int k = 0; k < 2; ++k) \
;         acc[ai][bj][m][n] = __builtin_amdgcn_mfma_f32_16x16x32_bf16(Bt[n][k], At[m][k], acc[ai][bj][m][n], 0, 0, 0); __builtin_amdgcn_s_setprio(0); } while (0)
; #define PG8_WAIT_V(n) asm volatile("s_waitcnt vmcnt(" #n ")" ::: "memory")
; #define PG8_WAIT_L(n) asm volatile("s_waitcnt lgkmcnt(" #n ")" ::: "memory")
; #define PG8_BAR __builtin_amdgcn_s_barrier()
; #define PG8_SCHED __builtin_amdgcn_sched_barrier(0)
; template <class Epi, class Sched, bool ALIGN_EPI = false, bool SP2 = false>
; __device__ __forceinline__ void gemm_phase(PG8_LAS unsigned char* lds, const Gemm g, const Sched& S, const Epi& E) {
;     ...
;             PG8_WAIT_V(8); PG8_WAIT_L(0); PG8_BAR; PG8_MMA(1, 0, At, B0); PG8_MMA(1, 1, At, B1); PG8_BAR; PG8_SCHED;
;             PG8_LDB(B0, 1, 0); PG8_LDB(B1, 1, 1); PG8_SCHED; PG8_LDA(At, 1, 0); PG8_STAGE(PG8_SA(0, 1), a2 + hstep, voffA);
;             PG8_WAIT_V(8); PG8_WAIT_L(0); PG8_BAR; PG8_MMA(0, 0, At, B0); PG8_MMA(0, 1, At, B1); PG8_BAR; PG8_SCHED;
	s_waitcnt lgkmcnt(0)
	v_mfma_f32_16x16x32_bf16 v[80:83], v[156:159], v[202:205], v[80:83]
	v_mfma_f32_16x16x32_bf16 v[76:79], v[170:173], v[202:205], v[76:79]
	v_mfma_f32_16x16x32_bf16 v[68:71], v[156:159], v[220:223], v[68:71]
	v_mfma_f32_16x16x32_bf16 v[60:63], v[170:173], v[220:223], v[60:63]
	v_mfma_f32_16x16x32_bf16 v[52:55], v[156:159], v[228:231], v[52:55]
	v_mfma_f32_16x16x32_bf16 v[44:47], v[170:173], v[228:231], v[44:47]
	v_mfma_f32_16x16x32_bf16 v[36:39], v[156:159], v[236:239], v[36:39]
	v_mfma_f32_16x16x32_bf16 v[28:31], v[170:173], v[236:239], v[28:31]
	v_mfma_f32_16x16x32_bf16 v[80:83], v[166:169], v[206:209], v[80:83]
	v_mfma_f32_16x16x32_bf16 v[76:79], v[174:177], v[206:209], v[76:79]
	v_mfma_f32_16x16x32_bf16 v[68:71], v[166:169], v[224:227], v[68:71]
	v_mfma_f32_16x16x32_bf16 v[60:63], v[174:177], v[224:227], v[60:63]
	v_mfma_f32_16x16x32_bf16 v[52:55], v[166:169], v[232:235], v[52:55]
	v_mfma_f32_16x16x32_bf16 v[44:47], v[174:177], v[232:235], v[44:47]
	v_mfma_f32_16x16x32_bf16 v[36:39], v[166:169], v[240:243], v[36:39]
	v_mfma_f32_16x16x32_bf16 v[28:31], v[174:177], v[240:243], v[28:31]
	v_mfma_f32_16x16x32_bf16 v[72:75], v[178:181], v[202:205], v[72:75]
	v_mfma_f32_16x16x32_bf16 v[64:67], v[194:197], v[202:205], v[64:67]
	v_mfma_f32_16x16x32_bf16 v[56:59], v[178:181], v[220:223], v[56:59]
	v_mfma_f32_16x16x32_bf16 v[48:51], v[194:197], v[220:223], v[48:51]
	v_mfma_f32_16x16x32_bf16 v[40:43], v[178:181], v[228:231], v[40:43]
	v_mfma_f32_16x16x32_bf16 v[32:35], v[194:197], v[228:231], v[32:35]
	v_mfma_f32_16x16x32_bf16 v[24:27], v[178:181], v[236:239], v[24:27]
	v_mfma_f32_16x16x32_bf16 v[20:23], v[194:197], v[236:239], v[20:23]
	v_mfma_f32_16x16x32_bf16 v[72:75], v[190:193], v[206:209], v[72:75]
	v_mfma_f32_16x16x32_bf16 v[64:67], v[198:201], v[206:209], v[64:67]
	v_mfma_f32_16x16x32_bf16 v[56:59], v[190:193], v[224:227], v[56:59]
	v_mfma_f32_16x16x32_bf16 v[48:51], v[198:201], v[224:227], v[48:51]
	v_mfma_f32_16x16x32_bf16 v[40:43], v[190:193], v[232:235], v[40:43]
	v_mfma_f32_16x16x32_bf16 v[32:35], v[198:201], v[232:235], v[32:35]
	v_mfma_f32_16x16x32_bf16 v[24:27], v[190:193], v[240:243], v[24:27]
	v_mfma_f32_16x16x32_bf16 v[20:23], v[198:201], v[240:243], v[20:23]
	s_barrier
	s_add_i32 s61, 0, 0x18000
	s_add_i32 s64, 0, 0x1c000
	v_add_u32_e32 v174, s61, v163
	v_add_u32_e32 v186, s64, v163
	ds_read_b128 v[156:159], v174
	ds_read_b128 v[166:169], v174 offset:1024
	ds_read_b128 v[170:173], v174 offset:2048
	ds_read_b128 v[174:177], v174 offset:3072
	ds_read_b128 v[178:181], v186
	ds_read_b128 v[190:193], v186 offset:1024
	ds_read_b128 v[194:197], v186 offset:2048
	ds_read_b128 v[198:201], v186 offset:3072
	s_add_u32 s24, s24, 0x20000
	s_addc_u32 s25, s25, 0
	s_mov_b32 m0, s58
	v_lshl_add_u64 v[248:249], s[24:25], 0, v[150:151]
	ds_read_b128 v[202:205], v165 offset:32768
	ds_read_b128 v[206:209], v165 offset:33792
	ds_read_b128 v[220:223], v165 offset:34816
	ds_read_b128 v[224:227], v165 offset:35840
	ds_read_b128 v[228:231], v165 offset:36864
	ds_read_b128 v[232:235], v165 offset:37888
	ds_read_b128 v[236:239], v165 offset:38912
	ds_read_b128 v[240:243], v165 offset:39936
	global_load_lds_dwordx4 v[248:249], off
	v_lshl_add_u64 v[248:249], s[24:25], 0, v[148:149]
	s_mov_b32 m0, s59
	s_nop 0
	global_load_lds_dwordx4 v[248:249], off
	s_waitcnt vmcnt(8)
	s_waitcnt lgkmcnt(0)
	s_barrier
	s_waitcnt lgkmcnt(0)
	v_mfma_f32_16x16x32_bf16 v[144:147], v[156:159], v[202:205], v[144:147]
	v_mfma_f32_16x16x32_bf16 v[140:143], v[170:173], v[202:205], v[140:143]
	v_mfma_f32_16x16x32_bf16 v[132:135], v[156:159], v[220:223], v[132:135]
	v_mfma_f32_16x16x32_bf16 v[124:127], v[170:173], v[220:223], v[124:127]
	v_mfma_f32_16x16x32_bf16 v[116:119], v[156:159], v[228:231], v[116:119]
	v_mfma_f32_16x16x32_bf16 v[108:111], v[170:173], v[228:231], v[108:111]
	v_mfma_f32_16x16x32_bf16 v[100:103], v[156:159], v[236:239], v[100:103]
	v_mfma_f32_16x16x32_bf16 v[92:95], v[170:173], v[236:239], v[92:95]
	v_mfma_f32_16x16x32_bf16 v[144:147], v[166:169], v[206:209], v[144:147]
	v_mfma_f32_16x16x32_bf16 v[140:143], v[174:177], v[206:209], v[140:143]
	v_mfma_f32_16x16x32_bf16 v[132:135], v[166:169], v[224:227], v[132:135]
	v_mfma_f32_16x16x32_bf16 v[124:127], v[174:177], v[224:227], v[124:127]
	v_mfma_f32_16x16x32_bf16 v[116:119], v[166:169], v[232:235], v[116:119]
	v_mfma_f32_16x16x32_bf16 v[108:111], v[174:177], v[232:235], v[108:111]
	v_mfma_f32_16x16x32_bf16 v[100:103], v[166:169], v[240:243], v[100:103]
	v_mfma_f32_16x16x32_bf16 v[92:95], v[174:177], v[240:243], v[92:95]
	v_mfma_f32_16x16x32_bf16 v[136:139], v[178:181], v[202:205], v[136:139]
	v_mfma_f32_16x16x32_bf16 v[128:131], v[194:197], v[202:205], v[128:131]
	v_mfma_f32_16x16x32_bf16 v[120:123], v[178:181], v[220:223], v[120:123]
	v_mfma_f32_16x16x32_bf16 v[112:115], v[194:197], v[220:223], v[112:115]
	v_mfma_f32_16x16x32_bf16 v[104:107], v[178:181], v[228:231], v[104:107]
	v_mfma_f32_16x16x32_bf16 v[96:99], v[194:197], v[228:231], v[96:99]
	v_mfma_f32_16x16x32_bf16 v[88:91], v[178:181], v[236:239], v[88:91]
	v_mfma_f32_16x16x32_bf16 v[84:87], v[194:197], v[236:239], v[84:87]
	v_mfma_f32_16x16x32_bf16 v[136:139], v[190:193], v[206:209], v[136:139]
	v_mfma_f32_16x16x32_bf16 v[128:131], v[198:201], v[206:209], v[128:131]
	v_mfma_f32_16x16x32_bf16 v[120:123], v[190:193], v[224:227], v[120:123]
	v_mfma_f32_16x16x32_bf16 v[112:115], v[198:201], v[224:227], v[112:115]
	v_mfma_f32_16x16x32_bf16 v[104:107], v[190:193], v[232:235], v[104:107]
	v_mfma_f32_16x16x32_bf16 v[96:99], v[198:201], v[232:235], v[96:99]
	v_mfma_f32_16x16x32_bf16 v[88:91], v[190:193], v[240:243], v[88:91]
	v_mfma_f32_16x16x32_bf16 v[84:87], v[198:201], v[240:243], v[84:87]
	s_barrier
; #define PG8_STAGE(bufoff, gbase, voff) do { _Pragma("unroll") for (int _i = 0; _i < 2; ++_i) \
;         __builtin_amdgcn_global_load_lds((const unsigned*)((const char*)(gbase) + (voff)[_i]), (PG8_LAS unsigned*)(lds + (bufoff) + ldsw + _i * 8192), 16, 0, 0); } while (0)
; #define PG8_LDA(dst, b, h) do { _Pragma("unroll") for (int m = 0; m < 4; ++m) _Pragma("unroll") for (int k = 0; k < 2; ++k) dst[m][k] = *(const PG8_LAS bf16x8*)(lds + PG8_SA(b, h) + aoff + m * 2048 + k * 1024); } while (0)
; #define PG8_MMA(ai, bj, At, Bt) do { __builtin_amdgcn_s_setprio(1); _Pragma("unroll") for (int m = 0; m < 4; ++m) _Pragma("unroll") for (int n = 0; n < 2; ++n) _Pragma("unroll") for (int k = 0; k < 2; ++k) \
;         acc[ai][bj][m][n] = __builtin_amdgcn_mfma_f32_16x16x32_bf16(Bt[n][k], At[m][k], acc[ai][bj][m][n], 0, 0, 0); __builtin_amdgcn_s_setprio(0); } while (0)
; #define PG8_WAIT_V(n) asm volatile("s_waitcnt vmcnt(" #n ")" ::: "memory")
; #define PG8_WAIT_L(n) asm volatile("s_waitcnt lgkmcnt(" #n ")" ::: "memory")
; #define PG8_BAR __builtin_amdgcn_s_barrier()
; #define PG8_SCHED __builtin_amdgcn_sched_barrier(0)
; template <class Epi, class Sched, bool ALIGN_EPI = false, bool SP2 = false>
; __device__ __forceinline__ void gemm_phase(PG8_LAS unsigned char* lds, const Gemm g, const Sched& S, const Epi& E) {
;     ...
;             PG8_LDA(At, 1, 1); PG8_STAGE(PG8_SB(1, 0), b3, voffB); PG8_STAGE(PG8_SB(1, 1), b3 + hstep, voffB); PG8_STAGE(PG8_SA(1, 0), a3, voffA);
;             PG8_WAIT_V(8); PG8_WAIT_L(0); PG8_BAR; PG8_MMA(1, 0, At, B0); PG8_MMA(1, 1, At, B1); PG8_BAR; PG8_SCHED;
	s_add_i32 s24, s61, s55
	v_lshl_add_u64 v[160:161], v[160:161], 0, s[20:21]
	s_mov_b32 m0, s24
	ds_read_b128 v[202:205], v165 offset:49152
	ds_read_b128 v[206:209], v165 offset:50176
	ds_read_b128 v[220:223], v165 offset:51200
	ds_read_b128 v[224:227], v165 offset:52224
	ds_read_b128 v[228:231], v165 offset:53248
	ds_read_b128 v[232:235], v165 offset:54272
	ds_read_b128 v[236:239], v165 offset:55296
	ds_read_b128 v[240:243], v165 offset:56320
	global_load_lds_dwordx4 v[160:161], off
	s_add_i32 m0, s24, 0x2000
	s_add_u32 s0, s0, 0x20080
	v_lshl_add_u64 v[160:161], v[182:183], 0, s[20:21]
	s_addc_u32 s1, s1, 0
	s_add_i32 s24, s64, s55
	global_load_lds_dwordx4 v[160:161], off
	v_lshl_add_u64 v[160:161], s[0:1], 0, v[0:1]
	s_mov_b32 m0, s24
	s_nop 0
	global_load_lds_dwordx4 v[160:161], off
	v_lshl_add_u64 v[160:161], s[0:1], 0, v[2:3]
	s_add_i32 m0, s24, 0x2000
	s_nop 0
	global_load_lds_dwordx4 v[160:161], off
	v_lshl_add_u64 v[160:161], v[244:245], 0, s[20:21]
	s_mov_b32 m0, s62
	s_nop 0
	global_load_lds_dwordx4 v[160:161], off
	v_lshl_add_u64 v[160:161], v[246:247], 0, s[20:21]
	s_mov_b32 m0, s63
	s_nop 0
	global_load_lds_dwordx4 v[160:161], off
	s_waitcnt vmcnt(8)
	s_waitcnt lgkmcnt(0)
	s_barrier
	s_waitcnt lgkmcnt(0)
	v_mfma_f32_16x16x32_bf16 v[80:83], v[156:159], v[202:205], v[80:83]
	v_mfma_f32_16x16x32_bf16 v[76:79], v[170:173], v[202:205], v[76:79]
	v_mfma_f32_16x16x32_bf16 v[68:71], v[156:159], v[220:223], v[68:71]
	v_mfma_f32_16x16x32_bf16 v[60:63], v[170:173], v[220:223], v[60:63]
	v_mfma_f32_16x16x32_bf16 v[52:55], v[156:159], v[228:231], v[52:55]
	v_mfma_f32_16x16x32_bf16 v[44:47], v[170:173], v[228:231], v[44:47]
	v_mfma_f32_16x16x32_bf16 v[36:39], v[156:159], v[236:239], v[36:39]
	v_mfma_f32_16x16x32_bf16 v[28:31], v[170:173], v[236:239], v[28:31]
	v_mfma_f32_16x16x32_bf16 v[80:83], v[166:169], v[206:209], v[80:83]
	v_mfma_f32_16x16x32_bf16 v[76:79], v[174:177], v[206:209], v[76:79]
	v_mfma_f32_16x16x32_bf16 v[68:71], v[166:169], v[224:227], v[68:71]
	v_mfma_f32_16x16x32_bf16 v[60:63], v[174:177], v[224:227], v[60:63]
	v_mfma_f32_16x16x32_bf16 v[52:55], v[166:169], v[232:235], v[52:55]
	v_mfma_f32_16x16x32_bf16 v[44:47], v[174:177], v[232:235], v[44:47]
	v_mfma_f32_16x16x32_bf16 v[36:39], v[166:169], v[240:243], v[36:39]
	v_mfma_f32_16x16x32_bf16 v[28:31], v[174:177], v[240:243], v[28:31]
	v_mfma_f32_16x16x32_bf16 v[72:75], v[178:181], v[202:205], v[72:75]
	v_mfma_f32_16x16x32_bf16 v[64:67], v[194:197], v[202:205], v[64:67]
	v_mfma_f32_16x16x32_bf16 v[56:59], v[178:181], v[220:223], v[56:59]
	v_mfma_f32_16x16x32_bf16 v[48:51], v[194:197], v[220:223], v[48:51]
	v_mfma_f32_16x16x32_bf16 v[40:43], v[178:181], v[228:231], v[40:43]
	v_mfma_f32_16x16x32_bf16 v[32:35], v[194:197], v[228:231], v[32:35]
	v_mfma_f32_16x16x32_bf16 v[24:27], v[178:181], v[236:239], v[24:27]
	v_mfma_f32_16x16x32_bf16 v[20:23], v[194:197], v[236:239], v[20:23]
	v_mfma_f32_16x16x32_bf16 v[72:75], v[190:193], v[206:209], v[72:75]
	v_mfma_f32_16x16x32_bf16 v[64:67], v[198:201], v[206:209], v[64:67]
	v_mfma_f32_16x16x32_bf16 v[56:59], v[190:193], v[224:227], v[56:59]
	v_mfma_f32_16x16x32_bf16 v[48:51], v[198:201], v[224:227], v[48:51]
	v_mfma_f32_16x16x32_bf16 v[40:43], v[190:193], v[232:235], v[40:43]
	v_mfma_f32_16x16x32_bf16 v[32:35], v[198:201], v[232:235], v[32:35]
	v_mfma_f32_16x16x32_bf16 v[24:27], v[190:193], v[240:243], v[24:27]
	v_mfma_f32_16x16x32_bf16 v[20:23], v[198:201], v[240:243], v[20:23]
	s_barrier
	s_add_i32 s60, s60, 2
	s_add_u32 s18, s18, 0x100
	s_addc_u32 s19, s19, 0
	s_add_u32 s23, s23, 0x100
	s_addc_u32 s35, s35, 0
	s_cmp_gt_u32 s60, 5
	s_cbranch_scc0 .LBB0_676
	s_and_b64 vcc, exec, s[8:9]
	s_cbranch_vccz .LBB0_679
	s_barrier

; #define PG8_STAGE(bufoff, gbase, voff) do { _Pragma("unroll") for (int _i = 0; _i < 2; ++_i) \
;         __builtin_amdgcn_global_load_lds((const unsigned*)((const char*)(gbase) + (voff)[_i]), (PG8_LAS unsigned*)(lds + (bufoff) + ldsw + _i * 8192), 16, 0, 0); } while (0)
; #define PG8_LDA(dst, b, h) do { _Pragma("unroll") for (int m = 0; m < 4; ++m) _Pragma("unroll") for (int k = 0; k < 2; ++k) dst[m][k] = *(const PG8_LAS bf16x8*)(lds + PG8_SA(b, h) + aoff + m * 2048 + k * 1024); } while (0)
; #define PG8_LDB(dst, b, h) do { _Pragma("unroll") for (int n = 0; n < 2; ++n) _Pragma("unroll") for (int k = 0; k < 2; ++k) dst[n][k] = *(const PG8_LAS bf16x8*)(lds + PG8_SB(b, h) + boff + n * 2048 + k * 1024); } while (0)
; #define PG8_MMA(ai, bj, At, Bt) do { __builtin_amdgcn_s_setprio(1); _Pragma("unroll") for (int m = 0; m < 4; ++m) _Pragma("unroll") for (int n = 0; n < 2; ++n) _Pragma("unroll") for (int k = 0; k < 2; ++k) \
;         acc[ai][bj][m][n] = __builtin_amdgcn_mfma_f32_16x16x32_bf16(Bt[n][k], At[m][k], acc[ai][bj][m][n], 0, 0, 0); __builtin_amdgcn_s_setprio(0); } while (0)
; #define PG8_WAIT_V(n) asm volatile("s_waitcnt vmcnt(" #n ")" ::: "memory")
; #define PG8_WAIT_L(n) asm volatile("s_waitcnt lgkmcnt(" #n ")" ::: "memory")
; template <class Epi, class Sched, bool ALIGN_EPI = false, bool SP2 = false>
; __device__ __forceinline__ void gemm_phase(PG8_LAS unsigned char* lds, const Gemm g, const Sched& S, const Epi& E) {
;     ...
;             const bool last = (t == nt - 2);
;             const char* a1 = cA + (size_t)(t + 1) * kstep;
;             const char* a2 = last ? nA : cA + (size_t)(t + 2) * kstep; const char* b2 = last ? nB : cB + (size_t)(t + 2) * kstep;
;             const char* a3 = a2 + kstep; const char* b3 = b2 + kstep;
;             if (last && has_next) S.a_ready(nxt);
;             if constexpr (SP2) {
;             PG8_LDB(B0, 0, 0); PG8_LDB(B1, 0, 1); PG8_SCHED; PG8_LDA(At, 0, 0); PG8_STAGE(PG8_SA(1, 1), a1 + hstep, voffA);
;             PG8_WAIT_V(8); PG8_WAIT_L(0); PG8_BAR; PG8_MMA(0, 0, At, B0); PG8_MMA(0, 1, At, B1); PG8_BAR; PG8_SCHED;
;             PG8_LDA(At, 0, 1); PG8_STAGE(PG8_SB(0, 0), b2, voffB); PG8_STAGE(PG8_SB(0, 1), b2 + hstep, voffB); PG8_STAGE(PG8_SA(0, 0), a2, voffA);
;             PG8_WAIT_V(8); PG8_WAIT_L(0); PG8_BAR; PG8_MMA(1, 0, At, B0); PG8_MMA(1, 1, At, B1); PG8_BAR; PG8_SCHED;
.LBB0_699:
	s_add_u32 s0, s18, 0xfffe0080
	s_addc_u32 s1, s19, -1
	s_add_i32 s61, 0, 0x10000
	s_cmp_eq_u32 s60, 4
	s_cselect_b32 s25, s13, s1
	s_cselect_b32 s24, s67, s0
	s_cselect_b32 s1, s11, s35
	s_cselect_b32 s0, s22, s23
	s_add_i32 s72, 0, 0x14000
	v_add_u32_e32 v160, s61, v183
	v_add_u32_e32 v180, s72, v183
	ds_read_b128 v[148:151], v160
	ds_read_b128 v[152:155], v160 offset:1024
	ds_read_b128 v[156:159], v160 offset:2048
	ds_read_b128 v[160:163], v160 offset:3072
	ds_read_b128 v[172:175], v180
	ds_read_b128 v[176:179], v180 offset:1024
	ds_read_b128 v[192:195], v180 offset:2048
	ds_read_b128 v[196:199], v180 offset:3072
	v_lshl_add_u64 v[180:181], s[18:19], 0, v[168:169]
	s_add_i32 m0, s56, 0xc000
	ds_read_b128 v[200:203], v191
	ds_read_b128 v[204:207], v191 offset:1024
	ds_read_b128 v[220:223], v191 offset:2048
	ds_read_b128 v[224:227], v191 offset:3072
	ds_read_b128 v[228:231], v191 offset:4096
	ds_read_b128 v[232:235], v191 offset:5120
	ds_read_b128 v[236:239], v191 offset:6144
	ds_read_b128 v[240:243], v191 offset:7168
	global_load_lds_dwordx4 v[180:181], off
	v_lshl_add_u64 v[180:181], s[18:19], 0, v[170:171]
	s_add_i32 m0, s56, 0xe000
	s_nop 0
	global_load_lds_dwordx4 v[180:181], off
	s_waitcnt vmcnt(8)
	s_waitcnt lgkmcnt(0)
	s_barrier
	s_waitcnt lgkmcnt(0)
	v_mfma_f32_16x16x32_bf16 v[144:147], v[148:151], v[200:203], v[144:147]
	v_mfma_f32_16x16x32_bf16 v[140:143], v[156:159], v[200:203], v[140:143]
	v_mfma_f32_16x16x32_bf16 v[128:131], v[148:151], v[220:223], v[128:131]
	v_mfma_f32_16x16x32_bf16 v[124:127], v[156:159], v[220:223], v[124:127]
	v_mfma_f32_16x16x32_bf16 v[112:115], v[148:151], v[228:231], v[112:115]
	v_mfma_f32_16x16x32_bf16 v[108:111], v[156:159], v[228:231], v[108:111]
	v_mfma_f32_16x16x32_bf16 v[96:99], v[148:151], v[236:239], v[96:99]
	v_mfma_f32_16x16x32_bf16 v[92:95], v[156:159], v[236:239], v[92:95]
	v_mfma_f32_16x16x32_bf16 v[144:147], v[152:155], v[204:207], v[144:147]
	v_mfma_f32_16x16x32_bf16 v[140:143], v[160:163], v[204:207], v[140:143]
	v_mfma_f32_16x16x32_bf16 v[128:131], v[152:155], v[224:227], v[128:131]
	v_mfma_f32_16x16x32_bf16 v[124:127], v[160:163], v[224:227], v[124:127]
	v_mfma_f32_16x16x32_bf16 v[112:115], v[152:155], v[232:235], v[112:115]
	v_mfma_f32_16x16x32_bf16 v[108:111], v[160:163], v[232:235], v[108:111]
	v_mfma_f32_16x16x32_bf16 v[96:99], v[152:155], v[240:243], v[96:99]
	v_mfma_f32_16x16x32_bf16 v[92:95], v[160:163], v[240:243], v[92:95]
	v_mfma_f32_16x16x32_bf16 v[136:139], v[172:175], v[200:203], v[136:139]
	v_mfma_f32_16x16x32_bf16 v[132:135], v[192:195], v[200:203], v[132:135]
	v_mfma_f32_16x16x32_bf16 v[120:123], v[172:175], v[220:223], v[120:123]
	v_mfma_f32_16x16x32_bf16 v[116:119], v[192:195], v[220:223], v[116:119]
	v_mfma_f32_16x16x32_bf16 v[104:107], v[172:175], v[228:231], v[104:107]
	v_mfma_f32_16x16x32_bf16 v[100:103], v[192:195], v[228:231], v[100:103]
	v_mfma_f32_16x16x32_bf16 v[88:91], v[172:175], v[236:239], v[88:91]
	v_mfma_f32_16x16x32_bf16 v[84:87], v[192:195], v[236:239], v[84:87]
	v_mfma_f32_16x16x32_bf16 v[136:139], v[176:179], v[204:207], v[136:139]
	v_mfma_f32_16x16x32_bf16 v[132:135], v[196:199], v[204:207], v[132:135]
	v_mfma_f32_16x16x32_bf16 v[120:123], v[176:179], v[224:227], v[120:123]
	v_mfma_f32_16x16x32_bf16 v[116:119], v[196:199], v[224:227], v[116:119]
	v_mfma_f32_16x16x32_bf16 v[104:107], v[176:179], v[232:235], v[104:107]
	v_mfma_f32_16x16x32_bf16 v[100:103], v[196:199], v[232:235], v[100:103]
	v_mfma_f32_16x16x32_bf16 v[88:91], v[176:179], v[240:243], v[88:91]
	v_mfma_f32_16x16x32_bf16 v[84:87], v[196:199], v[240:243], v[84:87]
	s_barrier
	s_add_i32 s61, s61, s55
	v_lshl_add_u64 v[180:181], s[0:1], 0, v[0:1]
	s_mov_b32 m0, s61
	ds_read_b128 v[200:203], v191 offset:16384
	ds_read_b128 v[204:207], v191 offset:17408
	ds_read_b128 v[220:223], v191 offset:18432
	ds_read_b128 v[224:227], v191 offset:19456
	ds_read_b128 v[228:231], v191 offset:20480
	ds_read_b128 v[232:235], v191 offset:21504
	ds_read_b128 v[236:239], v191 offset:22528
	ds_read_b128 v[240:243], v191 offset:23552
	global_load_lds_dwordx4 v[180:181], off
	s_add_i32 m0, s61, 0x2000
	s_add_u32 s64, s0, 0x20000
	v_lshl_add_u64 v[208:209], s[0:1], 0, v[2:3]
	s_addc_u32 s65, s1, 0
	s_add_i32 s61, s72, s55
	global_load_lds_dwordx4 v[208:209], off
	v_lshl_add_u64 v[244:245], s[64:65], 0, v[0:1]
	s_mov_b32 m0, s61
	v_lshl_add_u64 v[246:247], s[24:25], 0, v[164:165]
	global_load_lds_dwordx4 v[244:245], off
	v_lshl_add_u64 v[244:245], s[64:65], 0, v[2:3]
	s_add_i32 m0, s61, 0x2000
	s_nop 0
	global_load_lds_dwordx4 v[244:245], off
	v_lshl_add_u64 v[244:245], s[24:25], 0, v[166:167]
	s_mov_b32 m0, s56
	s_nop 0
	global_load_lds_dwordx4 v[244:245], off
	s_mov_b32 m0, s57
	s_nop 0
	global_load_lds_dwordx4 v[246:247], off
	s_waitcnt vmcnt(8)
	s_waitcnt lgkmcnt(0)
	s_barrier
; #define PG8_STAGE(bufoff, gbase, voff) do { _Pragma("unroll") for (int _i = 0; _i < 2; ++_i) \
;         __builtin_amdgcn_global_load_lds((const unsigned*)((const char*)(gbase) + (voff)[_i]), (PG8_LAS unsigned*)(lds + (bufoff) + ldsw + _i * 8192), 16, 0, 0); } while (0)
; #define PG8_LDA(dst, b, h) do { _Pragma("unroll") for (int m = 0; m < 4; ++m) _Pragma("unroll") for (int k = 0; k < 2; ++k) dst[m][k] = *(const PG8_LAS bf16x8*)(lds + PG8_SA(b, h) + aoff + m * 2048 + k * 1024); } while (0)
; #define PG8_LDB(dst, b, h) do { _Pragma("unroll") for (int n = 0; n < 2; ++n) _Pragma("unroll") for (int k = 0; k < 2; ++k) dst[n][k] = *(const PG8_LAS bf16x8*)(lds + PG8_SB(b, h) + boff + n * 2048 + k * 1024); } while (0)
; #define PG8_MMA(ai, bj, At, Bt) do { __builtin_amdgcn_s_setprio(1); _Pragma("unroll") for (int m = 0; m < 4; ++m) _Pragma("unroll") for (int n = 0; n < 2; ++n) _Pragma("unroll") for (int k = 0; k < 2; ++k) \
;         acc[ai][bj][m][n] = __builtin_amdgcn_mfma_f32_16x16x32_bf16(Bt[n][k], At[m][k], acc[ai][bj][m][n], 0, 0, 0); __builtin_amdgcn_s_setprio(0); } while (0)
; #define PG8_WAIT_V(n) asm volatile("s_waitcnt vmcnt(" #n ")" ::: "memory")
; #define PG8_WAIT_L(n) asm volatile("s_waitcnt lgkmcnt(" #n ")" ::: "memory")
; #define PG8_BAR __builtin_amdgcn_s_barrier()
; #define PG8_SCHED __builtin_amdgcn_sched_barrier(0)
; template <class Epi, class Sched, bool ALIGN_EPI = false, bool SP2 = false>
; __device__ __forceinline__ void gemm_phase(PG8_LAS unsigned char* lds, const Gemm g, const Sched& S, const Epi& E) {
;     ...
;             PG8_WAIT_V(8); PG8_WAIT_L(0); PG8_BAR; PG8_MMA(1, 0, At, B0); PG8_MMA(1, 1, At, B1); PG8_BAR; PG8_SCHED;
;             PG8_LDB(B0, 1, 0); PG8_LDB(B1, 1, 1); PG8_SCHED; PG8_LDA(At, 1, 0); PG8_STAGE(PG8_SA(0, 1), a2 + hstep, voffA);
;             PG8_WAIT_V(8); PG8_WAIT_L(0); PG8_BAR; PG8_MMA(0, 0, At, B0); PG8_MMA(0, 1, At, B1); PG8_BAR; PG8_SCHED;
	s_waitcnt lgkmcnt(0)
	v_mfma_f32_16x16x32_bf16 v[80:83], v[148:151], v[200:203], v[80:83]
	v_mfma_f32_16x16x32_bf16 v[76:79], v[156:159], v[200:203], v[76:79]
	v_mfma_f32_16x16x32_bf16 v[64:67], v[148:151], v[220:223], v[64:67]
	v_mfma_f32_16x16x32_bf16 v[60:63], v[156:159], v[220:223], v[60:63]
	v_mfma_f32_16x16x32_bf16 v[48:51], v[148:151], v[228:231], v[48:51]
	v_mfma_f32_16x16x32_bf16 v[44:47], v[156:159], v[228:231], v[44:47]
	v_mfma_f32_16x16x32_bf16 v[32:35], v[148:151], v[236:239], v[32:35]
	v_mfma_f32_16x16x32_bf16 v[28:31], v[156:159], v[236:239], v[28:31]
	v_mfma_f32_16x16x32_bf16 v[80:83], v[152:155], v[204:207], v[80:83]
	v_mfma_f32_16x16x32_bf16 v[76:79], v[160:163], v[204:207], v[76:79]
	v_mfma_f32_16x16x32_bf16 v[64:67], v[152:155], v[224:227], v[64:67]
	v_mfma_f32_16x16x32_bf16 v[60:63], v[160:163], v[224:227], v[60:63]
	v_mfma_f32_16x16x32_bf16 v[48:51], v[152:155], v[232:235], v[48:51]
	v_mfma_f32_16x16x32_bf16 v[44:47], v[160:163], v[232:235], v[44:47]
	v_mfma_f32_16x16x32_bf16 v[32:35], v[152:155], v[240:243], v[32:35]
	v_mfma_f32_16x16x32_bf16 v[28:31], v[160:163], v[240:243], v[28:31]
	v_mfma_f32_16x16x32_bf16 v[72:75], v[172:175], v[200:203], v[72:75]
	v_mfma_f32_16x16x32_bf16 v[68:71], v[192:195], v[200:203], v[68:71]
	v_mfma_f32_16x16x32_bf16 v[56:59], v[172:175], v[220:223], v[56:59]
	v_mfma_f32_16x16x32_bf16 v[52:55], v[192:195], v[220:223], v[52:55]
	v_mfma_f32_16x16x32_bf16 v[40:43], v[172:175], v[228:231], v[40:43]
	v_mfma_f32_16x16x32_bf16 v[36:39], v[192:195], v[228:231], v[36:39]
	v_mfma_f32_16x16x32_bf16 v[24:27], v[172:175], v[236:239], v[24:27]
	v_mfma_f32_16x16x32_bf16 v[20:23], v[192:195], v[236:239], v[20:23]
	v_mfma_f32_16x16x32_bf16 v[72:75], v[176:179], v[204:207], v[72:75]
	v_mfma_f32_16x16x32_bf16 v[68:71], v[196:199], v[204:207], v[68:71]
	v_mfma_f32_16x16x32_bf16 v[56:59], v[176:179], v[224:227], v[56:59]
	v_mfma_f32_16x16x32_bf16 v[52:55], v[196:199], v[224:227], v[52:55]
	v_mfma_f32_16x16x32_bf16 v[40:43], v[176:179], v[232:235], v[40:43]
	v_mfma_f32_16x16x32_bf16 v[36:39], v[196:199], v[232:235], v[36:39]
	v_mfma_f32_16x16x32_bf16 v[24:27], v[176:179], v[240:243], v[24:27]
	v_mfma_f32_16x16x32_bf16 v[20:23], v[196:199], v[240:243], v[20:23]
	s_barrier
	s_add_i32 s61, 0, 0x18000
	s_add_i32 s64, 0, 0x1c000
	v_add_u32_e32 v160, s61, v183
	v_add_u32_e32 v186, s64, v183
	ds_read_b128 v[148:151], v160
	ds_read_b128 v[152:155], v160 offset:1024
	ds_read_b128 v[156:159], v160 offset:2048
	ds_read_b128 v[160:163], v160 offset:3072
	ds_read_b128 v[172:175], v186
	ds_read_b128 v[176:179], v186 offset:1024
	ds_read_b128 v[192:195], v186 offset:2048
	ds_read_b128 v[196:199], v186 offset:3072
	s_add_u32 s24, s24, 0x20000
	s_addc_u32 s25, s25, 0
	s_mov_b32 m0, s58
	v_lshl_add_u64 v[248:249], s[24:25], 0, v[166:167]
	ds_read_b128 v[200:203], v191 offset:32768
	ds_read_b128 v[204:207], v191 offset:33792
	ds_read_b128 v[220:223], v191 offset:34816
	ds_read_b128 v[224:227], v191 offset:35840
	ds_read_b128 v[228:231], v191 offset:36864
	ds_read_b128 v[232:235], v191 offset:37888
	ds_read_b128 v[236:239], v191 offset:38912
	ds_read_b128 v[240:243], v191 offset:39936
	global_load_lds_dwordx4 v[248:249], off
	v_lshl_add_u64 v[248:249], s[24:25], 0, v[164:165]
	s_mov_b32 m0, s59
	s_nop 0
	global_load_lds_dwordx4 v[248:249], off
	s_waitcnt vmcnt(8)
	s_waitcnt lgkmcnt(0)
	s_barrier
	s_waitcnt lgkmcnt(0)
	v_mfma_f32_16x16x32_bf16 v[144:147], v[148:151], v[200:203], v[144:147]
	v_mfma_f32_16x16x32_bf16 v[140:143], v[156:159], v[200:203], v[140:143]
	v_mfma_f32_16x16x32_bf16 v[128:131], v[148:151], v[220:223], v[128:131]
	v_mfma_f32_16x16x32_bf16 v[124:127], v[156:159], v[220:223], v[124:127]
	v_mfma_f32_16x16x32_bf16 v[112:115], v[148:151], v[228:231], v[112:115]
	v_mfma_f32_16x16x32_bf16 v[108:111], v[156:159], v[228:231], v[108:111]
	v_mfma_f32_16x16x32_bf16 v[96:99], v[148:151], v[236:239], v[96:99]
	v_mfma_f32_16x16x32_bf16 v[92:95], v[156:159], v[236:239], v[92:95]
	v_mfma_f32_16x16x32_bf16 v[144:147], v[152:155], v[204:207], v[144:147]
	v_mfma_f32_16x16x32_bf16 v[140:143], v[160:163], v[204:207], v[140:143]
	v_mfma_f32_16x16x32_bf16 v[128:131], v[152:155], v[224:227], v[128:131]
	v_mfma_f32_16x16x32_bf16 v[124:127], v[160:163], v[224:227], v[124:127]
	v_mfma_f32_16x16x32_bf16 v[112:115], v[152:155], v[232:235], v[112:115]
	v_mfma_f32_16x16x32_bf16 v[108:111], v[160:163], v[232:235], v[108:111]
	v_mfma_f32_16x16x32_bf16 v[96:99], v[152:155], v[240:243], v[96:99]
	v_mfma_f32_16x16x32_bf16 v[92:95], v[160:163], v[240:243], v[92:95]
	v_mfma_f32_16x16x32_bf16 v[136:139], v[172:175], v[200:203], v[136:139]
	v_mfma_f32_16x16x32_bf16 v[132:135], v[192:195], v[200:203], v[132:135]
	v_mfma_f32_16x16x32_bf16 v[120:123], v[172:175], v[220:223], v[120:123]
	v_mfma_f32_16x16x32_bf16 v[116:119], v[192:195], v[220:223], v[116:119]
	v_mfma_f32_16x16x32_bf16 v[104:107], v[172:175], v[228:231], v[104:107]
	v_mfma_f32_16x16x32_bf16 v[100:103], v[192:195], v[228:231], v[100:103]
	v_mfma_f32_16x16x32_bf16 v[88:91], v[172:175], v[236:239], v[88:91]
	v_mfma_f32_16x16x32_bf16 v[84:87], v[192:195], v[236:239], v[84:87]
	v_mfma_f32_16x16x32_bf16 v[136:139], v[176:179], v[204:207], v[136:139]
	v_mfma_f32_16x16x32_bf16 v[132:135], v[196:199], v[204:207], v[132:135]
	v_mfma_f32_16x16x32_bf16 v[120:123], v[176:179], v[224:227], v[120:123]
	v_mfma_f32_16x16x32_bf16 v[116:119], v[196:199], v[224:227], v[116:119]
	v_mfma_f32_16x16x32_bf16 v[104:107], v[176:179], v[232:235], v[104:107]
	v_mfma_f32_16x16x32_bf16 v[100:103], v[196:199], v[232:235], v[100:103]
	v_mfma_f32_16x16x32_bf16 v[88:91], v[176:179], v[240:243], v[88:91]
	v_mfma_f32_16x16x32_bf16 v[84:87], v[196:199], v[240:243], v[84:87]
	s_barrier
; #define PG8_STAGE(bufoff, gbase, voff) do { _Pragma("unroll") for (int _i = 0; _i < 2; ++_i) \
;         __builtin_amdgcn_global_load_lds((const unsigned*)((const char*)(gbase) + (voff)[_i]), (PG8_LAS unsigned*)(lds + (bufoff) + ldsw + _i * 8192), 16, 0, 0); } while (0)
; #define PG8_LDA(dst, b, h) do { _Pragma("unroll") for (int m = 0; m < 4; ++m) _Pragma("unroll") for (int k = 0; k < 2; ++k) dst[m][k] = *(const PG8_LAS bf16x8*)(lds + PG8_SA(b, h) + aoff + m * 2048 + k * 1024); } while (0)
; #define PG8_MMA(ai, bj, At, Bt) do { __builtin_amdgcn_s_setprio(1); _Pragma("unroll") for (int m = 0; m < 4; ++m) _Pragma("unroll") for (int n = 0; n < 2; ++n) _Pragma("unroll") for (int k = 0; k < 2; ++k) \
;         acc[ai][bj][m][n] = __builtin_amdgcn_mfma_f32_16x16x32_bf16(Bt[n][k], At[m][k], acc[ai][bj][m][n], 0, 0, 0); __builtin_amdgcn_s_setprio(0); } while (0)
; #define PG8_WAIT_V(n) asm volatile("s_waitcnt vmcnt(" #n ")" ::: "memory")
; #define PG8_WAIT_L(n) asm volatile("s_waitcnt lgkmcnt(" #n ")" ::: "memory")
; #define PG8_BAR __builtin_amdgcn_s_barrier()
; #define PG8_SCHED __builtin_amdgcn_sched_barrier(0)
; template <class Epi, class Sched, bool ALIGN_EPI = false, bool SP2 = false>
; __device__ __forceinline__ void gemm_phase(PG8_LAS unsigned char* lds, const Gemm g, const Sched& S, const Epi& E) {
;     ...
;             PG8_LDA(At, 1, 1); PG8_STAGE(PG8_SB(1, 0), b3, voffB); PG8_STAGE(PG8_SB(1, 1), b3 + hstep, voffB); PG8_STAGE(PG8_SA(1, 0), a3, voffA);
;             PG8_WAIT_V(8); PG8_WAIT_L(0); PG8_BAR; PG8_MMA(1, 0, At, B0); PG8_MMA(1, 1, At, B1); PG8_BAR; PG8_SCHED;
	s_add_i32 s24, s61, s55
	v_lshl_add_u64 v[180:181], v[180:181], 0, s[20:21]
	s_mov_b32 m0, s24
	ds_read_b128 v[200:203], v191 offset:49152
	ds_read_b128 v[204:207], v191 offset:50176
	ds_read_b128 v[220:223], v191 offset:51200
	ds_read_b128 v[224:227], v191 offset:52224
	ds_read_b128 v[228:231], v191 offset:53248
	ds_read_b128 v[232:235], v191 offset:54272
	ds_read_b128 v[236:239], v191 offset:55296
	ds_read_b128 v[240:243], v191 offset:56320
	global_load_lds_dwordx4 v[180:181], off
	s_add_i32 m0, s24, 0x2000
	s_add_u32 s0, s0, 0x20080
	v_lshl_add_u64 v[180:181], v[208:209], 0, s[20:21]
	s_addc_u32 s1, s1, 0
	s_add_i32 s24, s64, s55
	global_load_lds_dwordx4 v[180:181], off
	v_lshl_add_u64 v[180:181], s[0:1], 0, v[0:1]
	s_mov_b32 m0, s24
	s_nop 0
	global_load_lds_dwordx4 v[180:181], off
	v_lshl_add_u64 v[180:181], s[0:1], 0, v[2:3]
	s_add_i32 m0, s24, 0x2000
	s_nop 0
	global_load_lds_dwordx4 v[180:181], off
	v_lshl_add_u64 v[180:181], v[244:245], 0, s[20:21]
	s_mov_b32 m0, s62
	s_nop 0
	global_load_lds_dwordx4 v[180:181], off
	v_lshl_add_u64 v[180:181], v[246:247], 0, s[20:21]
	s_mov_b32 m0, s63
	s_nop 0
	global_load_lds_dwordx4 v[180:181], off
	s_waitcnt vmcnt(8)
	s_waitcnt lgkmcnt(0)
	s_barrier
	s_waitcnt lgkmcnt(0)
	v_mfma_f32_16x16x32_bf16 v[80:83], v[148:151], v[200:203], v[80:83]
	v_mfma_f32_16x16x32_bf16 v[76:79], v[156:159], v[200:203], v[76:79]
	v_mfma_f32_16x16x32_bf16 v[64:67], v[148:151], v[220:223], v[64:67]
	v_mfma_f32_16x16x32_bf16 v[60:63], v[156:159], v[220:223], v[60:63]
	v_mfma_f32_16x16x32_bf16 v[48:51], v[148:151], v[228:231], v[48:51]
	v_mfma_f32_16x16x32_bf16 v[44:47], v[156:159], v[228:231], v[44:47]
	v_mfma_f32_16x16x32_bf16 v[32:35], v[148:151], v[236:239], v[32:35]
	v_mfma_f32_16x16x32_bf16 v[28:31], v[156:159], v[236:239], v[28:31]
	v_mfma_f32_16x16x32_bf16 v[80:83], v[152:155], v[204:207], v[80:83]
	v_mfma_f32_16x16x32_bf16 v[76:79], v[160:163], v[204:207], v[76:79]
	v_mfma_f32_16x16x32_bf16 v[64:67], v[152:155], v[224:227], v[64:67]
	v_mfma_f32_16x16x32_bf16 v[60:63], v[160:163], v[224:227], v[60:63]
	v_mfma_f32_16x16x32_bf16 v[48:51], v[152:155], v[232:235], v[48:51]
	v_mfma_f32_16x16x32_bf16 v[44:47], v[160:163], v[232:235], v[44:47]
	v_mfma_f32_16x16x32_bf16 v[32:35], v[152:155], v[240:243], v[32:35]
	v_mfma_f32_16x16x32_bf16 v[28:31], v[160:163], v[240:243], v[28:31]
	v_mfma_f32_16x16x32_bf16 v[72:75], v[172:175], v[200:203], v[72:75]
	v_mfma_f32_16x16x32_bf16 v[68:71], v[192:195], v[200:203], v[68:71]
	v_mfma_f32_16x16x32_bf16 v[56:59], v[172:175], v[220:223], v[56:59]
	v_mfma_f32_16x16x32_bf16 v[52:55], v[192:195], v[220:223], v[52:55]
	v_mfma_f32_16x16x32_bf16 v[40:43], v[172:175], v[228:231], v[40:43]
	v_mfma_f32_16x16x32_bf16 v[36:39], v[192:195], v[228:231], v[36:39]
	v_mfma_f32_16x16x32_bf16 v[24:27], v[172:175], v[236:239], v[24:27]
	v_mfma_f32_16x16x32_bf16 v[20:23], v[192:195], v[236:239], v[20:23]
	v_mfma_f32_16x16x32_bf16 v[72:75], v[176:179], v[204:207], v[72:75]
	v_mfma_f32_16x16x32_bf16 v[68:71], v[196:199], v[204:207], v[68:71]
	v_mfma_f32_16x16x32_bf16 v[56:59], v[176:179], v[224:227], v[56:59]
	v_mfma_f32_16x16x32_bf16 v[52:55], v[196:199], v[224:227], v[52:55]
	v_mfma_f32_16x16x32_bf16 v[40:43], v[176:179], v[232:235], v[40:43]
	v_mfma_f32_16x16x32_bf16 v[36:39], v[196:199], v[232:235], v[36:39]
	v_mfma_f32_16x16x32_bf16 v[24:27], v[176:179], v[240:243], v[24:27]
	v_mfma_f32_16x16x32_bf16 v[20:23], v[196:199], v[240:243], v[20:23]
	s_barrier
	s_add_i32 s60, s60, 2
	s_add_u32 s18, s18, 0x100
	s_addc_u32 s19, s19, 0
	s_add_u32 s23, s23, 0x100
	s_addc_u32 s35, s35, 0
	s_cmp_gt_u32 s60, 5
	s_cbranch_scc0 .LBB0_699
	s_and_b64 vcc, exec, s[6:7]
	s_cbranch_vccz .LBB0_702
	s_barrier

; #define PG8_STAGE(bufoff, gbase, voff) do { _Pragma("unroll") for (int _i = 0; _i < 2; ++_i) \
;         __builtin_amdgcn_global_load_lds((const unsigned*)((const char*)(gbase) + (voff)[_i]), (PG8_LAS unsigned*)(lds + (bufoff) + ldsw + _i * 8192), 16, 0, 0); } while (0)
; #define PG8_LDA(dst, b, h) do { _Pragma("unroll") for (int m = 0; m < 4; ++m) _Pragma("unroll") for (int k = 0; k < 2; ++k) dst[m][k] = *(const PG8_LAS bf16x8*)(lds + PG8_SA(b, h) + aoff + m * 2048 + k * 1024); } while (0)
; #define PG8_LDB(dst, b, h) do { _Pragma("unroll") for (int n = 0; n < 2; ++n) _Pragma("unroll") for (int k = 0; k < 2; ++k) dst[n][k] = *(const PG8_LAS bf16x8*)(lds + PG8_SB(b, h) + boff + n * 2048 + k * 1024); } while (0)
; #define PG8_MMA(ai, bj, At, Bt) do { __builtin_amdgcn_s_setprio(1); _Pragma("unroll") for (int m = 0; m < 4; ++m) _Pragma("unroll") for (int n = 0; n < 2; ++n) _Pragma("unroll") for (int k = 0; k < 2; ++k) \
;         acc[ai][bj][m][n] = __builtin_amdgcn_mfma_f32_16x16x32_bf16(Bt[n][k], At[m][k], acc[ai][bj][m][n], 0, 0, 0); __builtin_amdgcn_s_setprio(0); } while (0)
; #define PG8_WAIT_V(n) asm volatile("s_waitcnt vmcnt(" #n ")" ::: "memory")
; #define PG8_WAIT_L(n) asm volatile("s_waitcnt lgkmcnt(" #n ")" ::: "memory")
; template <class Epi, class Sched, bool ALIGN_EPI = false, bool SP2 = false>
; __device__ __forceinline__ void gemm_phase(PG8_LAS unsigned char* lds, const Gemm g, const Sched& S, const Epi& E) {
;     ...
;             const bool last = (t == nt - 2);
;             const char* a1 = cA + (size_t)(t + 1) * kstep;
;             const char* a2 = last ? nA : cA + (size_t)(t + 2) * kstep; const char* b2 = last ? nB : cB + (size_t)(t + 2) * kstep;
;             const char* a3 = a2 + kstep; const char* b3 = b2 + kstep;
;             if (last && has_next) S.a_ready(nxt);
;             if constexpr (SP2) {
;             PG8_LDB(B0, 0, 0); PG8_LDB(B1, 0, 1); PG8_SCHED; PG8_LDA(At, 0, 0); PG8_STAGE(PG8_SA(1, 1), a1 + hstep, voffA);
;             PG8_WAIT_V(8); PG8_WAIT_L(0); PG8_BAR; PG8_MMA(0, 0, At, B0); PG8_MMA(0, 1, At, B1); PG8_BAR; PG8_SCHED;
;             PG8_LDA(At, 0, 1); PG8_STAGE(PG8_SB(0, 0), b2, voffB); PG8_STAGE(PG8_SB(0, 1), b2 + hstep, voffB); PG8_STAGE(PG8_SA(0, 0), a2, voffA);
;             PG8_WAIT_V(8); PG8_WAIT_L(0); PG8_BAR; PG8_MMA(1, 0, At, B0); PG8_MMA(1, 1, At, B1); PG8_BAR; PG8_SCHED;
.LBB0_774:
	s_add_u32 s0, s54, 0xfffc0080
	s_addc_u32 s1, s55, -1
	s_add_i32 s61, 0, 0x10000
	s_cmp_eq_u32 s60, 12
	s_cselect_b32 s57, s17, s1
	s_cselect_b32 s56, s75, s0
	s_cselect_b32 s1, s15, s35
	s_cselect_b32 s0, s22, s23
	s_add_i32 s84, 0, 0x14000
	v_add_u32_e32 v160, s61, v205
	v_add_u32_e32 v186, s84, v205
	ds_read_b128 v[148:151], v160
	ds_read_b128 v[152:155], v160 offset:1024
	ds_read_b128 v[156:159], v160 offset:2048
	ds_read_b128 v[160:163], v160 offset:3072
	ds_read_b128 v[164:167], v186
	ds_read_b128 v[168:171], v186 offset:1024
	ds_read_b128 v[180:183], v186 offset:2048
	ds_read_b128 v[190:193], v186 offset:3072
	v_lshl_add_u64 v[186:187], s[54:55], 0, v[176:177]
	s_add_i32 m0, s62, 0xc000
	ds_read_b128 v[194:197], v207
	ds_read_b128 v[198:201], v207 offset:1024
	ds_read_b128 v[220:223], v207 offset:2048
	ds_read_b128 v[224:227], v207 offset:3072
	ds_read_b128 v[228:231], v207 offset:4096
	ds_read_b128 v[232:235], v207 offset:5120
	ds_read_b128 v[236:239], v207 offset:6144
	ds_read_b128 v[240:243], v207 offset:7168
	global_load_lds_dwordx4 v[186:187], off
	v_lshl_add_u64 v[186:187], s[54:55], 0, v[178:179]
	s_add_i32 m0, s62, 0xe000
	s_nop 0
	global_load_lds_dwordx4 v[186:187], off
	s_waitcnt vmcnt(8)
	s_waitcnt lgkmcnt(0)
	s_barrier
	s_waitcnt lgkmcnt(0)
	v_mfma_f32_16x16x32_bf16 v[144:147], v[148:151], v[194:197], v[144:147]
	v_mfma_f32_16x16x32_bf16 v[140:143], v[156:159], v[194:197], v[140:143]
	v_mfma_f32_16x16x32_bf16 v[128:131], v[148:151], v[220:223], v[128:131]
	v_mfma_f32_16x16x32_bf16 v[124:127], v[156:159], v[220:223], v[124:127]
	v_mfma_f32_16x16x32_bf16 v[112:115], v[148:151], v[228:231], v[112:115]
	v_mfma_f32_16x16x32_bf16 v[108:111], v[156:159], v[228:231], v[108:111]
	v_mfma_f32_16x16x32_bf16 v[96:99], v[148:151], v[236:239], v[96:99]
	v_mfma_f32_16x16x32_bf16 v[92:95], v[156:159], v[236:239], v[92:95]
	v_mfma_f32_16x16x32_bf16 v[144:147], v[152:155], v[198:201], v[144:147]
	v_mfma_f32_16x16x32_bf16 v[140:143], v[160:163], v[198:201], v[140:143]
	v_mfma_f32_16x16x32_bf16 v[128:131], v[152:155], v[224:227], v[128:131]
	v_mfma_f32_16x16x32_bf16 v[124:127], v[160:163], v[224:227], v[124:127]
	v_mfma_f32_16x16x32_bf16 v[112:115], v[152:155], v[232:235], v[112:115]
	v_mfma_f32_16x16x32_bf16 v[108:111], v[160:163], v[232:235], v[108:111]
	v_mfma_f32_16x16x32_bf16 v[96:99], v[152:155], v[240:243], v[96:99]
	v_mfma_f32_16x16x32_bf16 v[92:95], v[160:163], v[240:243], v[92:95]
	v_mfma_f32_16x16x32_bf16 v[136:139], v[164:167], v[194:197], v[136:139]
	v_mfma_f32_16x16x32_bf16 v[132:135], v[180:183], v[194:197], v[132:135]
	v_mfma_f32_16x16x32_bf16 v[120:123], v[164:167], v[220:223], v[120:123]
	v_mfma_f32_16x16x32_bf16 v[116:119], v[180:183], v[220:223], v[116:119]
	v_mfma_f32_16x16x32_bf16 v[104:107], v[164:167], v[228:231], v[104:107]
	v_mfma_f32_16x16x32_bf16 v[100:103], v[180:183], v[228:231], v[100:103]
	v_mfma_f32_16x16x32_bf16 v[88:91], v[164:167], v[236:239], v[88:91]
	v_mfma_f32_16x16x32_bf16 v[84:87], v[180:183], v[236:239], v[84:87]
	v_mfma_f32_16x16x32_bf16 v[136:139], v[168:171], v[198:201], v[136:139]
	v_mfma_f32_16x16x32_bf16 v[132:135], v[190:193], v[198:201], v[132:135]
	v_mfma_f32_16x16x32_bf16 v[120:123], v[168:171], v[224:227], v[120:123]
	v_mfma_f32_16x16x32_bf16 v[116:119], v[190:193], v[224:227], v[116:119]
	v_mfma_f32_16x16x32_bf16 v[104:107], v[168:171], v[232:235], v[104:107]
	v_mfma_f32_16x16x32_bf16 v[100:103], v[190:193], v[232:235], v[100:103]
	v_mfma_f32_16x16x32_bf16 v[88:91], v[168:171], v[240:243], v[88:91]
	v_mfma_f32_16x16x32_bf16 v[84:87], v[190:193], v[240:243], v[84:87]
	s_barrier
	s_add_i32 s61, s61, s59
	v_lshl_add_u64 v[186:187], s[0:1], 0, v[0:1]
	s_mov_b32 m0, s61
	ds_read_b128 v[194:197], v207 offset:16384
	ds_read_b128 v[198:201], v207 offset:17408
	ds_read_b128 v[220:223], v207 offset:18432
	ds_read_b128 v[224:227], v207 offset:19456
	ds_read_b128 v[228:231], v207 offset:20480
	ds_read_b128 v[232:235], v207 offset:21504
	ds_read_b128 v[236:239], v207 offset:22528
	ds_read_b128 v[240:243], v207 offset:23552
	global_load_lds_dwordx4 v[186:187], off
	s_add_i32 m0, s61, 0x2000
	s_add_u32 s64, s0, 0x40000
	v_lshl_add_u64 v[202:203], s[0:1], 0, v[2:3]
	s_addc_u32 s65, s1, 0
	s_add_i32 s61, s84, s59
	global_load_lds_dwordx4 v[202:203], off
	v_lshl_add_u64 v[208:209], s[64:65], 0, v[0:1]
	s_mov_b32 m0, s61
	v_lshl_add_u64 v[210:211], s[56:57], 0, v[172:173]
	global_load_lds_dwordx4 v[208:209], off
	v_lshl_add_u64 v[208:209], s[64:65], 0, v[2:3]
	s_add_i32 m0, s61, 0x2000
	s_nop 0
	global_load_lds_dwordx4 v[208:209], off
	v_lshl_add_u64 v[208:209], s[56:57], 0, v[174:175]
	s_mov_b32 m0, s62
	s_nop 0
	global_load_lds_dwordx4 v[208:209], off
	s_mov_b32 m0, s63
	s_nop 0
	global_load_lds_dwordx4 v[210:211], off
	s_waitcnt vmcnt(8)
	s_waitcnt lgkmcnt(0)
	s_barrier
; #define PG8_STAGE(bufoff, gbase, voff) do { _Pragma("unroll") for (int _i = 0; _i < 2; ++_i) \
;         __builtin_amdgcn_global_load_lds((const unsigned*)((const char*)(gbase) + (voff)[_i]), (PG8_LAS unsigned*)(lds + (bufoff) + ldsw + _i * 8192), 16, 0, 0); } while (0)
; #define PG8_LDA(dst, b, h) do { _Pragma("unroll") for (int m = 0; m < 4; ++m) _Pragma("unroll") for (int k = 0; k < 2; ++k) dst[m][k] = *(const PG8_LAS bf16x8*)(lds + PG8_SA(b, h) + aoff + m * 2048 + k * 1024); } while (0)
; #define PG8_LDB(dst, b, h) do { _Pragma("unroll") for (int n = 0; n < 2; ++n) _Pragma("unroll") for (int k = 0; k < 2; ++k) dst[n][k] = *(const PG8_LAS bf16x8*)(lds + PG8_SB(b, h) + boff + n * 2048 + k * 1024); } while (0)
; #define PG8_MMA(ai, bj, At, Bt) do { __builtin_amdgcn_s_setprio(1); _Pragma("unroll") for (int m = 0; m < 4; ++m) _Pragma("unroll") for (int n = 0; n < 2; ++n) _Pragma("unroll") for (int k = 0; k < 2; ++k) \
;         acc[ai][bj][m][n] = __builtin_amdgcn_mfma_f32_16x16x32_bf16(Bt[n][k], At[m][k], acc[ai][bj][m][n], 0, 0, 0); __builtin_amdgcn_s_setprio(0); } while (0)
; #define PG8_WAIT_V(n) asm volatile("s_waitcnt vmcnt(" #n ")" ::: "memory")
; #define PG8_WAIT_L(n) asm volatile("s_waitcnt lgkmcnt(" #n ")" ::: "memory")
; #define PG8_BAR __builtin_amdgcn_s_barrier()
; #define PG8_SCHED __builtin_amdgcn_sched_barrier(0)
; template <class Epi, class Sched, bool ALIGN_EPI = false, bool SP2 = false>
; __device__ __forceinline__ void gemm_phase(PG8_LAS unsigned char* lds, const Gemm g, const Sched& S, const Epi& E) {
;     ...
;             PG8_WAIT_V(8); PG8_WAIT_L(0); PG8_BAR; PG8_MMA(1, 0, At, B0); PG8_MMA(1, 1, At, B1); PG8_BAR; PG8_SCHED;
;             PG8_LDB(B0, 1, 0); PG8_LDB(B1, 1, 1); PG8_SCHED; PG8_LDA(At, 1, 0); PG8_STAGE(PG8_SA(0, 1), a2 + hstep, voffA);
;             PG8_WAIT_V(8); PG8_WAIT_L(0); PG8_BAR; PG8_MMA(0, 0, At, B0); PG8_MMA(0, 1, At, B1); PG8_BAR; PG8_SCHED;
	s_waitcnt lgkmcnt(0)
	v_mfma_f32_16x16x32_bf16 v[80:83], v[148:151], v[194:197], v[80:83]
	v_mfma_f32_16x16x32_bf16 v[76:79], v[156:159], v[194:197], v[76:79]
	v_mfma_f32_16x16x32_bf16 v[64:67], v[148:151], v[220:223], v[64:67]
	v_mfma_f32_16x16x32_bf16 v[60:63], v[156:159], v[220:223], v[60:63]
	v_mfma_f32_16x16x32_bf16 v[48:51], v[148:151], v[228:231], v[48:51]
	v_mfma_f32_16x16x32_bf16 v[44:47], v[156:159], v[228:231], v[44:47]
	v_mfma_f32_16x16x32_bf16 v[32:35], v[148:151], v[236:239], v[32:35]
	v_mfma_f32_16x16x32_bf16 v[28:31], v[156:159], v[236:239], v[28:31]
	v_mfma_f32_16x16x32_bf16 v[80:83], v[152:155], v[198:201], v[80:83]
	v_mfma_f32_16x16x32_bf16 v[76:79], v[160:163], v[198:201], v[76:79]
	v_mfma_f32_16x16x32_bf16 v[64:67], v[152:155], v[224:227], v[64:67]
	v_mfma_f32_16x16x32_bf16 v[60:63], v[160:163], v[224:227], v[60:63]
	v_mfma_f32_16x16x32_bf16 v[48:51], v[152:155], v[232:235], v[48:51]
	v_mfma_f32_16x16x32_bf16 v[44:47], v[160:163], v[232:235], v[44:47]
	v_mfma_f32_16x16x32_bf16 v[32:35], v[152:155], v[240:243], v[32:35]
	v_mfma_f32_16x16x32_bf16 v[28:31], v[160:163], v[240:243], v[28:31]
	v_mfma_f32_16x16x32_bf16 v[72:75], v[164:167], v[194:197], v[72:75]
	v_mfma_f32_16x16x32_bf16 v[68:71], v[180:183], v[194:197], v[68:71]
	v_mfma_f32_16x16x32_bf16 v[56:59], v[164:167], v[220:223], v[56:59]
	v_mfma_f32_16x16x32_bf16 v[52:55], v[180:183], v[220:223], v[52:55]
	v_mfma_f32_16x16x32_bf16 v[40:43], v[164:167], v[228:231], v[40:43]
	v_mfma_f32_16x16x32_bf16 v[36:39], v[180:183], v[228:231], v[36:39]
	v_mfma_f32_16x16x32_bf16 v[24:27], v[164:167], v[236:239], v[24:27]
	v_mfma_f32_16x16x32_bf16 v[20:23], v[180:183], v[236:239], v[20:23]
	v_mfma_f32_16x16x32_bf16 v[72:75], v[168:171], v[198:201], v[72:75]
	v_mfma_f32_16x16x32_bf16 v[68:71], v[190:193], v[198:201], v[68:71]
	v_mfma_f32_16x16x32_bf16 v[56:59], v[168:171], v[224:227], v[56:59]
	v_mfma_f32_16x16x32_bf16 v[52:55], v[190:193], v[224:227], v[52:55]
	v_mfma_f32_16x16x32_bf16 v[40:43], v[168:171], v[232:235], v[40:43]
	v_mfma_f32_16x16x32_bf16 v[36:39], v[190:193], v[232:235], v[36:39]
	v_mfma_f32_16x16x32_bf16 v[24:27], v[168:171], v[240:243], v[24:27]
	v_mfma_f32_16x16x32_bf16 v[20:23], v[190:193], v[240:243], v[20:23]
	s_barrier
	s_add_i32 s61, 0, 0x18000
	s_add_i32 s64, 0, 0x1c000
	v_add_u32_e32 v160, s61, v205
	v_add_u32_e32 v188, s64, v205
	ds_read_b128 v[148:151], v160
	ds_read_b128 v[152:155], v160 offset:1024
	ds_read_b128 v[156:159], v160 offset:2048
	ds_read_b128 v[160:163], v160 offset:3072
	ds_read_b128 v[164:167], v188
	ds_read_b128 v[168:171], v188 offset:1024
	ds_read_b128 v[180:183], v188 offset:2048
	ds_read_b128 v[190:193], v188 offset:3072
	s_add_u32 s56, s56, 0x40000
	s_addc_u32 s57, s57, 0
	s_mov_b32 m0, s66
	v_lshl_add_u64 v[244:245], s[56:57], 0, v[174:175]
	ds_read_b128 v[194:197], v207 offset:32768
	ds_read_b128 v[198:201], v207 offset:33792
	ds_read_b128 v[220:223], v207 offset:34816
	ds_read_b128 v[224:227], v207 offset:35840
	ds_read_b128 v[228:231], v207 offset:36864
	ds_read_b128 v[232:235], v207 offset:37888
	ds_read_b128 v[236:239], v207 offset:38912
	ds_read_b128 v[240:243], v207 offset:39936
	global_load_lds_dwordx4 v[244:245], off
	v_lshl_add_u64 v[244:245], s[56:57], 0, v[172:173]
	s_mov_b32 m0, s67
	s_nop 0
	global_load_lds_dwordx4 v[244:245], off
	s_waitcnt vmcnt(8)
	s_waitcnt lgkmcnt(0)
	s_barrier
	s_waitcnt lgkmcnt(0)
	v_mfma_f32_16x16x32_bf16 v[144:147], v[148:151], v[194:197], v[144:147]
	v_mfma_f32_16x16x32_bf16 v[140:143], v[156:159], v[194:197], v[140:143]
	v_mfma_f32_16x16x32_bf16 v[128:131], v[148:151], v[220:223], v[128:131]
	v_mfma_f32_16x16x32_bf16 v[124:127], v[156:159], v[220:223], v[124:127]
	v_mfma_f32_16x16x32_bf16 v[112:115], v[148:151], v[228:231], v[112:115]
	v_mfma_f32_16x16x32_bf16 v[108:111], v[156:159], v[228:231], v[108:111]
	v_mfma_f32_16x16x32_bf16 v[96:99], v[148:151], v[236:239], v[96:99]
	v_mfma_f32_16x16x32_bf16 v[92:95], v[156:159], v[236:239], v[92:95]
	v_mfma_f32_16x16x32_bf16 v[144:147], v[152:155], v[198:201], v[144:147]
	v_mfma_f32_16x16x32_bf16 v[140:143], v[160:163], v[198:201], v[140:143]
	v_mfma_f32_16x16x32_bf16 v[128:131], v[152:155], v[224:227], v[128:131]
	v_mfma_f32_16x16x32_bf16 v[124:127], v[160:163], v[224:227], v[124:127]
	v_mfma_f32_16x16x32_bf16 v[112:115], v[152:155], v[232:235], v[112:115]
	v_mfma_f32_16x16x32_bf16 v[108:111], v[160:163], v[232:235], v[108:111]
	v_mfma_f32_16x16x32_bf16 v[96:99], v[152:155], v[240:243], v[96:99]
	v_mfma_f32_16x16x32_bf16 v[92:95], v[160:163], v[240:243], v[92:95]
	v_mfma_f32_16x16x32_bf16 v[136:139], v[164:167], v[194:197], v[136:139]
	v_mfma_f32_16x16x32_bf16 v[132:135], v[180:183], v[194:197], v[132:135]
	v_mfma_f32_16x16x32_bf16 v[120:123], v[164:167], v[220:223], v[120:123]
	v_mfma_f32_16x16x32_bf16 v[116:119], v[180:183], v[220:223], v[116:119]
	v_mfma_f32_16x16x32_bf16 v[104:107], v[164:167], v[228:231], v[104:107]
	v_mfma_f32_16x16x32_bf16 v[100:103], v[180:183], v[228:231], v[100:103]
	v_mfma_f32_16x16x32_bf16 v[88:91], v[164:167], v[236:239], v[88:91]
	v_mfma_f32_16x16x32_bf16 v[84:87], v[180:183], v[236:239], v[84:87]
	v_mfma_f32_16x16x32_bf16 v[136:139], v[168:171], v[198:201], v[136:139]
	v_mfma_f32_16x16x32_bf16 v[132:135], v[190:193], v[198:201], v[132:135]
	v_mfma_f32_16x16x32_bf16 v[120:123], v[168:171], v[224:227], v[120:123]
	v_mfma_f32_16x16x32_bf16 v[116:119], v[190:193], v[224:227], v[116:119]
	v_mfma_f32_16x16x32_bf16 v[104:107], v[168:171], v[232:235], v[104:107]
	v_mfma_f32_16x16x32_bf16 v[100:103], v[190:193], v[232:235], v[100:103]
	v_mfma_f32_16x16x32_bf16 v[88:91], v[168:171], v[240:243], v[88:91]
	v_mfma_f32_16x16x32_bf16 v[84:87], v[190:193], v[240:243], v[84:87]
	s_barrier
; #define PG8_STAGE(bufoff, gbase, voff) do { _Pragma("unroll") for (int _i = 0; _i < 2; ++_i) \
;         __builtin_amdgcn_global_load_lds((const unsigned*)((const char*)(gbase) + (voff)[_i]), (PG8_LAS unsigned*)(lds + (bufoff) + ldsw + _i * 8192), 16, 0, 0); } while (0)
; #define PG8_LDA(dst, b, h) do { _Pragma("unroll") for (int m = 0; m < 4; ++m) _Pragma("unroll") for (int k = 0; k < 2; ++k) dst[m][k] = *(const PG8_LAS bf16x8*)(lds + PG8_SA(b, h) + aoff + m * 2048 + k * 1024); } while (0)
; #define PG8_MMA(ai, bj, At, Bt) do { __builtin_amdgcn_s_setprio(1); _Pragma("unroll") for (int m = 0; m < 4; ++m) _Pragma("unroll") for (int n = 0; n < 2; ++n) _Pragma("unroll") for (int k = 0; k < 2; ++k) \
;         acc[ai][bj][m][n] = __builtin_amdgcn_mfma_f32_16x16x32_bf16(Bt[n][k], At[m][k], acc[ai][bj][m][n], 0, 0, 0); __builtin_amdgcn_s_setprio(0); } while (0)
; #define PG8_WAIT_V(n) asm volatile("s_waitcnt vmcnt(" #n ")" ::: "memory")
; #define PG8_WAIT_L(n) asm volatile("s_waitcnt lgkmcnt(" #n ")" ::: "memory")
; #define PG8_BAR __builtin_amdgcn_s_barrier()
; #define PG8_SCHED __builtin_amdgcn_sched_barrier(0)
; template <class Epi, class Sched, bool ALIGN_EPI = false, bool SP2 = false>
; __device__ __forceinline__ void gemm_phase(PG8_LAS unsigned char* lds, const Gemm g, const Sched& S, const Epi& E) {
;     ...
;             PG8_LDA(At, 1, 1); PG8_STAGE(PG8_SB(1, 0), b3, voffB); PG8_STAGE(PG8_SB(1, 1), b3 + hstep, voffB); PG8_STAGE(PG8_SA(1, 0), a3, voffA);
;             PG8_WAIT_V(8); PG8_WAIT_L(0); PG8_BAR; PG8_MMA(1, 0, At, B0); PG8_MMA(1, 1, At, B1); PG8_BAR; PG8_SCHED;
	s_add_i32 s56, s61, s59
	v_lshl_add_u64 v[186:187], v[186:187], 0, s[20:21]
	s_mov_b32 m0, s56
	ds_read_b128 v[194:197], v207 offset:49152
	ds_read_b128 v[198:201], v207 offset:50176
	ds_read_b128 v[220:223], v207 offset:51200
	ds_read_b128 v[224:227], v207 offset:52224
	ds_read_b128 v[228:231], v207 offset:53248
	ds_read_b128 v[232:235], v207 offset:54272
	ds_read_b128 v[236:239], v207 offset:55296
	ds_read_b128 v[240:243], v207 offset:56320
	global_load_lds_dwordx4 v[186:187], off
	s_add_i32 m0, s56, 0x2000
	s_add_u32 s0, s0, 0x40080
	v_lshl_add_u64 v[186:187], v[202:203], 0, s[20:21]
	s_addc_u32 s1, s1, 0
	s_add_i32 s56, s64, s59
	global_load_lds_dwordx4 v[186:187], off
	v_lshl_add_u64 v[186:187], s[0:1], 0, v[0:1]
	s_mov_b32 m0, s56
	s_nop 0
	global_load_lds_dwordx4 v[186:187], off
	v_lshl_add_u64 v[186:187], s[0:1], 0, v[2:3]
	s_add_i32 m0, s56, 0x2000
	s_nop 0
	global_load_lds_dwordx4 v[186:187], off
	v_lshl_add_u64 v[186:187], v[208:209], 0, s[20:21]
	s_mov_b32 m0, s72
	s_nop 0
	global_load_lds_dwordx4 v[186:187], off
	v_lshl_add_u64 v[186:187], v[210:211], 0, s[20:21]
	s_mov_b32 m0, s73
	s_nop 0
	global_load_lds_dwordx4 v[186:187], off
	s_waitcnt vmcnt(8)
	s_waitcnt lgkmcnt(0)
	s_barrier
	s_waitcnt lgkmcnt(0)
	v_mfma_f32_16x16x32_bf16 v[80:83], v[148:151], v[194:197], v[80:83]
	v_mfma_f32_16x16x32_bf16 v[76:79], v[156:159], v[194:197], v[76:79]
	v_mfma_f32_16x16x32_bf16 v[64:67], v[148:151], v[220:223], v[64:67]
	v_mfma_f32_16x16x32_bf16 v[60:63], v[156:159], v[220:223], v[60:63]
	v_mfma_f32_16x16x32_bf16 v[48:51], v[148:151], v[228:231], v[48:51]
	v_mfma_f32_16x16x32_bf16 v[44:47], v[156:159], v[228:231], v[44:47]
	v_mfma_f32_16x16x32_bf16 v[32:35], v[148:151], v[236:239], v[32:35]
	v_mfma_f32_16x16x32_bf16 v[28:31], v[156:159], v[236:239], v[28:31]
	v_mfma_f32_16x16x32_bf16 v[80:83], v[152:155], v[198:201], v[80:83]
	v_mfma_f32_16x16x32_bf16 v[76:79], v[160:163], v[198:201], v[76:79]
	v_mfma_f32_16x16x32_bf16 v[64:67], v[152:155], v[224:227], v[64:67]
	v_mfma_f32_16x16x32_bf16 v[60:63], v[160:163], v[224:227], v[60:63]
	v_mfma_f32_16x16x32_bf16 v[48:51], v[152:155], v[232:235], v[48:51]
	v_mfma_f32_16x16x32_bf16 v[44:47], v[160:163], v[232:235], v[44:47]
	v_mfma_f32_16x16x32_bf16 v[32:35], v[152:155], v[240:243], v[32:35]
	v_mfma_f32_16x16x32_bf16 v[28:31], v[160:163], v[240:243], v[28:31]
	v_mfma_f32_16x16x32_bf16 v[72:75], v[164:167], v[194:197], v[72:75]
	v_mfma_f32_16x16x32_bf16 v[68:71], v[180:183], v[194:197], v[68:71]
	v_mfma_f32_16x16x32_bf16 v[56:59], v[164:167], v[220:223], v[56:59]
	v_mfma_f32_16x16x32_bf16 v[52:55], v[180:183], v[220:223], v[52:55]
	v_mfma_f32_16x16x32_bf16 v[40:43], v[164:167], v[228:231], v[40:43]
	v_mfma_f32_16x16x32_bf16 v[36:39], v[180:183], v[228:231], v[36:39]
	v_mfma_f32_16x16x32_bf16 v[24:27], v[164:167], v[236:239], v[24:27]
	v_mfma_f32_16x16x32_bf16 v[20:23], v[180:183], v[236:239], v[20:23]
	v_mfma_f32_16x16x32_bf16 v[72:75], v[168:171], v[198:201], v[72:75]
	v_mfma_f32_16x16x32_bf16 v[68:71], v[190:193], v[198:201], v[68:71]
	v_mfma_f32_16x16x32_bf16 v[56:59], v[168:171], v[224:227], v[56:59]
	v_mfma_f32_16x16x32_bf16 v[52:55], v[190:193], v[224:227], v[52:55]
	v_mfma_f32_16x16x32_bf16 v[40:43], v[168:171], v[232:235], v[40:43]
	v_mfma_f32_16x16x32_bf16 v[36:39], v[190:193], v[232:235], v[36:39]
	v_mfma_f32_16x16x32_bf16 v[24:27], v[168:171], v[240:243], v[24:27]
	v_mfma_f32_16x16x32_bf16 v[20:23], v[190:193], v[240:243], v[20:23]
	s_barrier
	s_add_i32 s60, s60, 2
	s_add_u32 s54, s54, 0x100
	s_addc_u32 s55, s55, 0
	s_add_u32 s23, s23, 0x100
	s_addc_u32 s35, s35, 0
	s_cmp_gt_u32 s60, 13
	s_cbranch_scc0 .LBB0_774
	v_mov_b64_e32 v[230:231], 0xff
	v_mov_b64_e32 v[228:229], 0x100
	s_and_b64 vcc, exec, s[12:13]
	s_cbranch_vccz .LBB0_777
	s_barrier

; #define PG8_STAGE(bufoff, gbase, voff) do { _Pragma("unroll") for (int _i = 0; _i < 2; ++_i) \
;         __builtin_amdgcn_global_load_lds((const unsigned*)((const char*)(gbase) + (voff)[_i]), (PG8_LAS unsigned*)(lds + (bufoff) + ldsw + _i * 8192), 16, 0, 0); } while (0)
; #define PG8_LDA(dst, b, h) do { _Pragma("unroll") for (int m = 0; m < 4; ++m) _Pragma("unroll") for (int k = 0; k < 2; ++k) dst[m][k] = *(const PG8_LAS bf16x8*)(lds + PG8_SA(b, h) + aoff + m * 2048 + k * 1024); } while (0)
; #define PG8_LDB(dst, b, h) do { _Pragma("unroll") for (int n = 0; n < 2; ++n) _Pragma("unroll") for (int k = 0; k < 2; ++k) dst[n][k] = *(const PG8_LAS bf16x8*)(lds + PG8_SB(b, h) + boff + n * 2048 + k * 1024); } while (0)
; #define PG8_MMA(ai, bj, At, Bt) do { __builtin_amdgcn_s_setprio(1); _Pragma("unroll") for (int m = 0; m < 4; ++m) _Pragma("unroll") for (int n = 0; n < 2; ++n) _Pragma("unroll") for (int k = 0; k < 2; ++k) \
;         acc[ai][bj][m][n] = __builtin_amdgcn_mfma_f32_16x16x32_bf16(Bt[n][k], At[m][k], acc[ai][bj][m][n], 0, 0, 0); __builtin_amdgcn_s_setprio(0); } while (0)
; #define PG8_WAIT_V(n) asm volatile("s_waitcnt vmcnt(" #n ")" ::: "memory")
; #define PG8_WAIT_L(n) asm volatile("s_waitcnt lgkmcnt(" #n ")" ::: "memory")
; template <class Epi, class Sched, bool ALIGN_EPI = false, bool SP2 = false>
; __device__ __forceinline__ void gemm_phase(PG8_LAS unsigned char* lds, const Gemm g, const Sched& S, const Epi& E) {
;     ...
;             const bool last = (t == nt - 2);
;             const char* a1 = cA + (size_t)(t + 1) * kstep;
;             const char* a2 = last ? nA : cA + (size_t)(t + 2) * kstep; const char* b2 = last ? nB : cB + (size_t)(t + 2) * kstep;
;             const char* a3 = a2 + kstep; const char* b3 = b2 + kstep;
;             if (last && has_next) S.a_ready(nxt);
;             if constexpr (SP2) {
;             PG8_LDB(B0, 0, 0); PG8_LDB(B1, 0, 1); PG8_SCHED; PG8_LDA(At, 0, 0); PG8_STAGE(PG8_SA(1, 1), a1 + hstep, voffA);
;             PG8_WAIT_V(8); PG8_WAIT_L(0); PG8_BAR; PG8_MMA(0, 0, At, B0); PG8_MMA(0, 1, At, B1); PG8_BAR; PG8_SCHED;
;             PG8_LDA(At, 0, 1); PG8_STAGE(PG8_SB(0, 0), b2, voffB); PG8_STAGE(PG8_SB(0, 1), b2 + hstep, voffB); PG8_STAGE(PG8_SA(0, 0), a2, voffA);
;             PG8_WAIT_V(8); PG8_WAIT_L(0); PG8_BAR; PG8_MMA(1, 0, At, B0); PG8_MMA(1, 1, At, B1); PG8_BAR; PG8_SCHED;
.LBB0_867:
	s_add_u32 s0, s24, 0xfffc0080
	s_addc_u32 s1, s25, -1
	s_add_i32 s61, 0, 0x10000
	s_cmp_eq_u32 s60, 12
	s_cselect_b32 s55, s15, s1
	s_cselect_b32 s54, s29, s0
	s_cselect_b32 s1, s13, s35
	s_cselect_b32 s0, s22, s23
	s_add_i32 s74, 0, 0x14000
	v_add_u32_e32 v172, s61, v161
	v_add_u32_e32 v186, s74, v161
	ds_read_b128 v[156:159], v172
	ds_read_b128 v[164:167], v172 offset:1024
	ds_read_b128 v[168:171], v172 offset:2048
	ds_read_b128 v[172:175], v172 offset:3072
	ds_read_b128 v[176:179], v186
	ds_read_b128 v[180:183], v186 offset:1024
	ds_read_b128 v[190:193], v186 offset:2048
	ds_read_b128 v[194:197], v186 offset:3072
	v_lshl_add_u64 v[186:187], s[24:25], 0, v[152:153]
	s_add_i32 m0, s58, 0xc000
	ds_read_b128 v[198:201], v163
	ds_read_b128 v[202:205], v163 offset:1024
	ds_read_b128 v[206:209], v163 offset:2048
	ds_read_b128 v[220:223], v163 offset:3072
	ds_read_b128 v[224:227], v163 offset:4096
	ds_read_b128 v[228:231], v163 offset:5120
	ds_read_b128 v[232:235], v163 offset:6144
	ds_read_b128 v[236:239], v163 offset:7168
	global_load_lds_dwordx4 v[186:187], off
	v_lshl_add_u64 v[186:187], s[24:25], 0, v[154:155]
	s_add_i32 m0, s58, 0xe000
	s_nop 0
	global_load_lds_dwordx4 v[186:187], off
	s_waitcnt vmcnt(8)
	s_waitcnt lgkmcnt(0)
	s_barrier
	s_waitcnt lgkmcnt(0)
	v_mfma_f32_16x16x32_bf16 v[144:147], v[156:159], v[198:201], v[144:147]
	v_mfma_f32_16x16x32_bf16 v[140:143], v[168:171], v[198:201], v[140:143]
	v_mfma_f32_16x16x32_bf16 v[128:131], v[156:159], v[206:209], v[128:131]
	v_mfma_f32_16x16x32_bf16 v[124:127], v[168:171], v[206:209], v[124:127]
	v_mfma_f32_16x16x32_bf16 v[112:115], v[156:159], v[224:227], v[112:115]
	v_mfma_f32_16x16x32_bf16 v[108:111], v[168:171], v[224:227], v[108:111]
	v_mfma_f32_16x16x32_bf16 v[96:99], v[156:159], v[232:235], v[96:99]
	v_mfma_f32_16x16x32_bf16 v[92:95], v[168:171], v[232:235], v[92:95]
	v_mfma_f32_16x16x32_bf16 v[144:147], v[164:167], v[202:205], v[144:147]
	v_mfma_f32_16x16x32_bf16 v[140:143], v[172:175], v[202:205], v[140:143]
	v_mfma_f32_16x16x32_bf16 v[128:131], v[164:167], v[220:223], v[128:131]
	v_mfma_f32_16x16x32_bf16 v[124:127], v[172:175], v[220:223], v[124:127]
	v_mfma_f32_16x16x32_bf16 v[112:115], v[164:167], v[228:231], v[112:115]
	v_mfma_f32_16x16x32_bf16 v[108:111], v[172:175], v[228:231], v[108:111]
	v_mfma_f32_16x16x32_bf16 v[96:99], v[164:167], v[236:239], v[96:99]
	v_mfma_f32_16x16x32_bf16 v[92:95], v[172:175], v[236:239], v[92:95]
	v_mfma_f32_16x16x32_bf16 v[136:139], v[176:179], v[198:201], v[136:139]
	v_mfma_f32_16x16x32_bf16 v[132:135], v[190:193], v[198:201], v[132:135]
	v_mfma_f32_16x16x32_bf16 v[120:123], v[176:179], v[206:209], v[120:123]
	v_mfma_f32_16x16x32_bf16 v[116:119], v[190:193], v[206:209], v[116:119]
	v_mfma_f32_16x16x32_bf16 v[104:107], v[176:179], v[224:227], v[104:107]
	v_mfma_f32_16x16x32_bf16 v[100:103], v[190:193], v[224:227], v[100:103]
	v_mfma_f32_16x16x32_bf16 v[88:91], v[176:179], v[232:235], v[88:91]
	v_mfma_f32_16x16x32_bf16 v[84:87], v[190:193], v[232:235], v[84:87]
	v_mfma_f32_16x16x32_bf16 v[136:139], v[180:183], v[202:205], v[136:139]
	v_mfma_f32_16x16x32_bf16 v[132:135], v[194:197], v[202:205], v[132:135]
	v_mfma_f32_16x16x32_bf16 v[120:123], v[180:183], v[220:223], v[120:123]
	v_mfma_f32_16x16x32_bf16 v[116:119], v[194:197], v[220:223], v[116:119]
	v_mfma_f32_16x16x32_bf16 v[104:107], v[180:183], v[228:231], v[104:107]
	v_mfma_f32_16x16x32_bf16 v[100:103], v[194:197], v[228:231], v[100:103]
	v_mfma_f32_16x16x32_bf16 v[88:91], v[180:183], v[236:239], v[88:91]
	v_mfma_f32_16x16x32_bf16 v[84:87], v[194:197], v[236:239], v[84:87]
	s_barrier
	s_add_i32 s61, s61, s57
	v_lshl_add_u64 v[186:187], s[0:1], 0, v[0:1]
	s_mov_b32 m0, s61
	ds_read_b128 v[198:201], v163 offset:16384
	ds_read_b128 v[202:205], v163 offset:17408
	ds_read_b128 v[206:209], v163 offset:18432
	ds_read_b128 v[220:223], v163 offset:19456
	ds_read_b128 v[224:227], v163 offset:20480
	ds_read_b128 v[228:231], v163 offset:21504
	ds_read_b128 v[232:235], v163 offset:22528
	ds_read_b128 v[236:239], v163 offset:23552
	global_load_lds_dwordx4 v[186:187], off
	s_add_i32 m0, s61, 0x2000
	s_add_u32 s64, s0, 0x40000
	v_lshl_add_u64 v[210:211], s[0:1], 0, v[2:3]
	s_addc_u32 s65, s1, 0
	s_add_i32 s61, s74, s57
	global_load_lds_dwordx4 v[210:211], off
	v_lshl_add_u64 v[240:241], s[64:65], 0, v[0:1]
	s_mov_b32 m0, s61
	v_lshl_add_u64 v[242:243], s[54:55], 0, v[148:149]
	global_load_lds_dwordx4 v[240:241], off
	v_lshl_add_u64 v[240:241], s[64:65], 0, v[2:3]
	s_add_i32 m0, s61, 0x2000
	s_nop 0
	global_load_lds_dwordx4 v[240:241], off
	v_lshl_add_u64 v[240:241], s[54:55], 0, v[150:151]
	s_mov_b32 m0, s58
	s_nop 0
	global_load_lds_dwordx4 v[240:241], off
	s_mov_b32 m0, s59
	s_nop 0
	global_load_lds_dwordx4 v[242:243], off
	s_waitcnt vmcnt(8)
	s_waitcnt lgkmcnt(0)
	s_barrier
; #define PG8_STAGE(bufoff, gbase, voff) do { _Pragma("unroll") for (int _i = 0; _i < 2; ++_i) \
;         __builtin_amdgcn_global_load_lds((const unsigned*)((const char*)(gbase) + (voff)[_i]), (PG8_LAS unsigned*)(lds + (bufoff) + ldsw + _i * 8192), 16, 0, 0); } while (0)
; #define PG8_LDA(dst, b, h) do { _Pragma("unroll") for (int m = 0; m < 4; ++m) _Pragma("unroll") for (int k = 0; k < 2; ++k) dst[m][k] = *(const PG8_LAS bf16x8*)(lds + PG8_SA(b, h) + aoff + m * 2048 + k * 1024); } while (0)
; #define PG8_LDB(dst, b, h) do { _Pragma("unroll") for (int n = 0; n < 2; ++n) _Pragma("unroll") for (int k = 0; k < 2; ++k) dst[n][k] = *(const PG8_LAS bf16x8*)(lds + PG8_SB(b, h) + boff + n * 2048 + k * 1024); } while (0)
; #define PG8_MMA(ai, bj, At, Bt) do { __builtin_amdgcn_s_setprio(1); _Pragma("unroll") for (int m = 0; m < 4; ++m) _Pragma("unroll") for (int n = 0; n < 2; ++n) _Pragma("unroll") for (int k = 0; k < 2; ++k) \
;         acc[ai][bj][m][n] = __builtin_amdgcn_mfma_f32_16x16x32_bf16(Bt[n][k], At[m][k], acc[ai][bj][m][n], 0, 0, 0); __builtin_amdgcn_s_setprio(0); } while (0)
; #define PG8_WAIT_V(n) asm volatile("s_waitcnt vmcnt(" #n ")" ::: "memory")
; #define PG8_WAIT_L(n) asm volatile("s_waitcnt lgkmcnt(" #n ")" ::: "memory")
; #define PG8_BAR __builtin_amdgcn_s_barrier()
; #define PG8_SCHED __builtin_amdgcn_sched_barrier(0)
; template <class Epi, class Sched, bool ALIGN_EPI = false, bool SP2 = false>
; __device__ __forceinline__ void gemm_phase(PG8_LAS unsigned char* lds, const Gemm g, const Sched& S, const Epi& E) {
;     ...
;             PG8_WAIT_V(8); PG8_WAIT_L(0); PG8_BAR; PG8_MMA(1, 0, At, B0); PG8_MMA(1, 1, At, B1); PG8_BAR; PG8_SCHED;
;             PG8_LDB(B0, 1, 0); PG8_LDB(B1, 1, 1); PG8_SCHED; PG8_LDA(At, 1, 0); PG8_STAGE(PG8_SA(0, 1), a2 + hstep, voffA);
;             PG8_WAIT_V(8); PG8_WAIT_L(0); PG8_BAR; PG8_MMA(0, 0, At, B0); PG8_MMA(0, 1, At, B1); PG8_BAR; PG8_SCHED;
	s_waitcnt lgkmcnt(0)
	v_mfma_f32_16x16x32_bf16 v[80:83], v[156:159], v[198:201], v[80:83]
	v_mfma_f32_16x16x32_bf16 v[76:79], v[168:171], v[198:201], v[76:79]
	v_mfma_f32_16x16x32_bf16 v[64:67], v[156:159], v[206:209], v[64:67]
	v_mfma_f32_16x16x32_bf16 v[60:63], v[168:171], v[206:209], v[60:63]
	v_mfma_f32_16x16x32_bf16 v[48:51], v[156:159], v[224:227], v[48:51]
	v_mfma_f32_16x16x32_bf16 v[44:47], v[168:171], v[224:227], v[44:47]
	v_mfma_f32_16x16x32_bf16 v[32:35], v[156:159], v[232:235], v[32:35]
	v_mfma_f32_16x16x32_bf16 v[28:31], v[168:171], v[232:235], v[28:31]
	v_mfma_f32_16x16x32_bf16 v[80:83], v[164:167], v[202:205], v[80:83]
	v_mfma_f32_16x16x32_bf16 v[76:79], v[172:175], v[202:205], v[76:79]
	v_mfma_f32_16x16x32_bf16 v[64:67], v[164:167], v[220:223], v[64:67]
	v_mfma_f32_16x16x32_bf16 v[60:63], v[172:175], v[220:223], v[60:63]
	v_mfma_f32_16x16x32_bf16 v[48:51], v[164:167], v[228:231], v[48:51]
	v_mfma_f32_16x16x32_bf16 v[44:47], v[172:175], v[228:231], v[44:47]
	v_mfma_f32_16x16x32_bf16 v[32:35], v[164:167], v[236:239], v[32:35]
	v_mfma_f32_16x16x32_bf16 v[28:31], v[172:175], v[236:239], v[28:31]
	v_mfma_f32_16x16x32_bf16 v[72:75], v[176:179], v[198:201], v[72:75]
	v_mfma_f32_16x16x32_bf16 v[68:71], v[190:193], v[198:201], v[68:71]
	v_mfma_f32_16x16x32_bf16 v[56:59], v[176:179], v[206:209], v[56:59]
	v_mfma_f32_16x16x32_bf16 v[52:55], v[190:193], v[206:209], v[52:55]
	v_mfma_f32_16x16x32_bf16 v[40:43], v[176:179], v[224:227], v[40:43]
	v_mfma_f32_16x16x32_bf16 v[36:39], v[190:193], v[224:227], v[36:39]
	v_mfma_f32_16x16x32_bf16 v[24:27], v[176:179], v[232:235], v[24:27]
	v_mfma_f32_16x16x32_bf16 v[20:23], v[190:193], v[232:235], v[20:23]
	v_mfma_f32_16x16x32_bf16 v[72:75], v[180:183], v[202:205], v[72:75]
	v_mfma_f32_16x16x32_bf16 v[68:71], v[194:197], v[202:205], v[68:71]
	v_mfma_f32_16x16x32_bf16 v[56:59], v[180:183], v[220:223], v[56:59]
	v_mfma_f32_16x16x32_bf16 v[52:55], v[194:197], v[220:223], v[52:55]
	v_mfma_f32_16x16x32_bf16 v[40:43], v[180:183], v[228:231], v[40:43]
	v_mfma_f32_16x16x32_bf16 v[36:39], v[194:197], v[228:231], v[36:39]
	v_mfma_f32_16x16x32_bf16 v[24:27], v[180:183], v[236:239], v[24:27]
	v_mfma_f32_16x16x32_bf16 v[20:23], v[194:197], v[236:239], v[20:23]
	s_barrier
	s_add_i32 s61, 0, 0x18000
	s_add_i32 s64, 0, 0x1c000
	v_add_u32_e32 v172, s61, v161
	v_add_u32_e32 v188, s64, v161
	ds_read_b128 v[156:159], v172
	ds_read_b128 v[164:167], v172 offset:1024
	ds_read_b128 v[168:171], v172 offset:2048
	ds_read_b128 v[172:175], v172 offset:3072
	ds_read_b128 v[176:179], v188
	ds_read_b128 v[180:183], v188 offset:1024
	ds_read_b128 v[190:193], v188 offset:2048
	ds_read_b128 v[194:197], v188 offset:3072
	s_add_u32 s54, s54, 0x40000
	s_addc_u32 s55, s55, 0
	s_mov_b32 m0, s62
	v_lshl_add_u64 v[244:245], s[54:55], 0, v[150:151]
	ds_read_b128 v[198:201], v163 offset:32768
	ds_read_b128 v[202:205], v163 offset:33792
	ds_read_b128 v[206:209], v163 offset:34816
	ds_read_b128 v[220:223], v163 offset:35840
	ds_read_b128 v[224:227], v163 offset:36864
	ds_read_b128 v[228:231], v163 offset:37888
	ds_read_b128 v[232:235], v163 offset:38912
	ds_read_b128 v[236:239], v163 offset:39936
	global_load_lds_dwordx4 v[244:245], off
	v_lshl_add_u64 v[244:245], s[54:55], 0, v[148:149]
	s_mov_b32 m0, s63
	s_nop 0
	global_load_lds_dwordx4 v[244:245], off
	s_waitcnt vmcnt(8)
	s_waitcnt lgkmcnt(0)
	s_barrier
	s_waitcnt lgkmcnt(0)
	v_mfma_f32_16x16x32_bf16 v[144:147], v[156:159], v[198:201], v[144:147]
	v_mfma_f32_16x16x32_bf16 v[140:143], v[168:171], v[198:201], v[140:143]
	v_mfma_f32_16x16x32_bf16 v[128:131], v[156:159], v[206:209], v[128:131]
	v_mfma_f32_16x16x32_bf16 v[124:127], v[168:171], v[206:209], v[124:127]
	v_mfma_f32_16x16x32_bf16 v[112:115], v[156:159], v[224:227], v[112:115]
	v_mfma_f32_16x16x32_bf16 v[108:111], v[168:171], v[224:227], v[108:111]
	v_mfma_f32_16x16x32_bf16 v[96:99], v[156:159], v[232:235], v[96:99]
	v_mfma_f32_16x16x32_bf16 v[92:95], v[168:171], v[232:235], v[92:95]
	v_mfma_f32_16x16x32_bf16 v[144:147], v[164:167], v[202:205], v[144:147]
	v_mfma_f32_16x16x32_bf16 v[140:143], v[172:175], v[202:205], v[140:143]
	v_mfma_f32_16x16x32_bf16 v[128:131], v[164:167], v[220:223], v[128:131]
	v_mfma_f32_16x16x32_bf16 v[124:127], v[172:175], v[220:223], v[124:127]
	v_mfma_f32_16x16x32_bf16 v[112:115], v[164:167], v[228:231], v[112:115]
	v_mfma_f32_16x16x32_bf16 v[108:111], v[172:175], v[228:231], v[108:111]
	v_mfma_f32_16x16x32_bf16 v[96:99], v[164:167], v[236:239], v[96:99]
	v_mfma_f32_16x16x32_bf16 v[92:95], v[172:175], v[236:239], v[92:95]
	v_mfma_f32_16x16x32_bf16 v[136:139], v[176:179], v[198:201], v[136:139]
	v_mfma_f32_16x16x32_bf16 v[132:135], v[190:193], v[198:201], v[132:135]
	v_mfma_f32_16x16x32_bf16 v[120:123], v[176:179], v[206:209], v[120:123]
	v_mfma_f32_16x16x32_bf16 v[116:119], v[190:193], v[206:209], v[116:119]
	v_mfma_f32_16x16x32_bf16 v[104:107], v[176:179], v[224:227], v[104:107]
	v_mfma_f32_16x16x32_bf16 v[100:103], v[190:193], v[224:227], v[100:103]
	v_mfma_f32_16x16x32_bf16 v[88:91], v[176:179], v[232:235], v[88:91]
	v_mfma_f32_16x16x32_bf16 v[84:87], v[190:193], v[232:235], v[84:87]
	v_mfma_f32_16x16x32_bf16 v[136:139], v[180:183], v[202:205], v[136:139]
	v_mfma_f32_16x16x32_bf16 v[132:135], v[194:197], v[202:205], v[132:135]
	v_mfma_f32_16x16x32_bf16 v[120:123], v[180:183], v[220:223], v[120:123]
	v_mfma_f32_16x16x32_bf16 v[116:119], v[194:197], v[220:223], v[116:119]
	v_mfma_f32_16x16x32_bf16 v[104:107], v[180:183], v[228:231], v[104:107]
	v_mfma_f32_16x16x32_bf16 v[100:103], v[194:197], v[228:231], v[100:103]
	v_mfma_f32_16x16x32_bf16 v[88:91], v[180:183], v[236:239], v[88:91]
	v_mfma_f32_16x16x32_bf16 v[84:87], v[194:197], v[236:239], v[84:87]
	s_barrier
; #define PG8_STAGE(bufoff, gbase, voff) do { _Pragma("unroll") for (int _i = 0; _i < 2; ++_i) \
;         __builtin_amdgcn_global_load_lds((const unsigned*)((const char*)(gbase) + (voff)[_i]), (PG8_LAS unsigned*)(lds + (bufoff) + ldsw + _i * 8192), 16, 0, 0); } while (0)
; #define PG8_LDA(dst, b, h) do { _Pragma("unroll") for (int m = 0; m < 4; ++m) _Pragma("unroll") for (int k = 0; k < 2; ++k) dst[m][k] = *(const PG8_LAS bf16x8*)(lds + PG8_SA(b, h) + aoff + m * 2048 + k * 1024); } while (0)
; #define PG8_MMA(ai, bj, At, Bt) do { __builtin_amdgcn_s_setprio(1); _Pragma("unroll") for (int m = 0; m < 4; ++m) _Pragma("unroll") for (int n = 0; n < 2; ++n) _Pragma("unroll") for (int k = 0; k < 2; ++k) \
;         acc[ai][bj][m][n] = __builtin_amdgcn_mfma_f32_16x16x32_bf16(Bt[n][k], At[m][k], acc[ai][bj][m][n], 0, 0, 0); __builtin_amdgcn_s_setprio(0); } while (0)
; #define PG8_WAIT_V(n) asm volatile("s_waitcnt vmcnt(" #n ")" ::: "memory")
; #define PG8_WAIT_L(n) asm volatile("s_waitcnt lgkmcnt(" #n ")" ::: "memory")
; #define PG8_BAR __builtin_amdgcn_s_barrier()
; #define PG8_SCHED __builtin_amdgcn_sched_barrier(0)
; template <class Epi, class Sched, bool ALIGN_EPI = false, bool SP2 = false>
; __device__ __forceinline__ void gemm_phase(PG8_LAS unsigned char* lds, const Gemm g, const Sched& S, const Epi& E) {
;     ...
;             PG8_LDA(At, 1, 1); PG8_STAGE(PG8_SB(1, 0), b3, voffB); PG8_STAGE(PG8_SB(1, 1), b3 + hstep, voffB); PG8_STAGE(PG8_SA(1, 0), a3, voffA);
;             PG8_WAIT_V(8); PG8_WAIT_L(0); PG8_BAR; PG8_MMA(1, 0, At, B0); PG8_MMA(1, 1, At, B1); PG8_BAR; PG8_SCHED;
	s_add_i32 s54, s61, s57
	v_lshl_add_u64 v[186:187], v[186:187], 0, s[20:21]
	s_mov_b32 m0, s54
	ds_read_b128 v[198:201], v163 offset:49152
	ds_read_b128 v[202:205], v163 offset:50176
	ds_read_b128 v[206:209], v163 offset:51200
	ds_read_b128 v[220:223], v163 offset:52224
	ds_read_b128 v[224:227], v163 offset:53248
	ds_read_b128 v[228:231], v163 offset:54272
	ds_read_b128 v[232:235], v163 offset:55296
	ds_read_b128 v[236:239], v163 offset:56320
	global_load_lds_dwordx4 v[186:187], off
	s_add_i32 m0, s54, 0x2000
	s_add_u32 s0, s0, 0x40080
	v_lshl_add_u64 v[186:187], v[210:211], 0, s[20:21]
	s_addc_u32 s1, s1, 0
	s_add_i32 s54, s64, s57
	global_load_lds_dwordx4 v[186:187], off
	v_lshl_add_u64 v[186:187], s[0:1], 0, v[0:1]
	s_mov_b32 m0, s54
	s_nop 0
	global_load_lds_dwordx4 v[186:187], off
	v_lshl_add_u64 v[186:187], s[0:1], 0, v[2:3]
	s_add_i32 m0, s54, 0x2000
	s_nop 0
	global_load_lds_dwordx4 v[186:187], off
	v_lshl_add_u64 v[186:187], v[240:241], 0, s[20:21]
	s_mov_b32 m0, s66
	s_nop 0
	global_load_lds_dwordx4 v[186:187], off
	v_lshl_add_u64 v[186:187], v[242:243], 0, s[20:21]
	s_mov_b32 m0, s67
	s_nop 0
	global_load_lds_dwordx4 v[186:187], off
	s_waitcnt vmcnt(8)
	s_waitcnt lgkmcnt(0)
	s_barrier
	s_waitcnt lgkmcnt(0)
	v_mfma_f32_16x16x32_bf16 v[80:83], v[156:159], v[198:201], v[80:83]
	v_mfma_f32_16x16x32_bf16 v[76:79], v[168:171], v[198:201], v[76:79]
	v_mfma_f32_16x16x32_bf16 v[64:67], v[156:159], v[206:209], v[64:67]
	v_mfma_f32_16x16x32_bf16 v[60:63], v[168:171], v[206:209], v[60:63]
	v_mfma_f32_16x16x32_bf16 v[48:51], v[156:159], v[224:227], v[48:51]
	v_mfma_f32_16x16x32_bf16 v[44:47], v[168:171], v[224:227], v[44:47]
	v_mfma_f32_16x16x32_bf16 v[32:35], v[156:159], v[232:235], v[32:35]
	v_mfma_f32_16x16x32_bf16 v[28:31], v[168:171], v[232:235], v[28:31]
	v_mfma_f32_16x16x32_bf16 v[80:83], v[164:167], v[202:205], v[80:83]
	v_mfma_f32_16x16x32_bf16 v[76:79], v[172:175], v[202:205], v[76:79]
	v_mfma_f32_16x16x32_bf16 v[64:67], v[164:167], v[220:223], v[64:67]
	v_mfma_f32_16x16x32_bf16 v[60:63], v[172:175], v[220:223], v[60:63]
	v_mfma_f32_16x16x32_bf16 v[48:51], v[164:167], v[228:231], v[48:51]
	v_mfma_f32_16x16x32_bf16 v[44:47], v[172:175], v[228:231], v[44:47]
	v_mfma_f32_16x16x32_bf16 v[32:35], v[164:167], v[236:239], v[32:35]
	v_mfma_f32_16x16x32_bf16 v[28:31], v[172:175], v[236:239], v[28:31]
	v_mfma_f32_16x16x32_bf16 v[72:75], v[176:179], v[198:201], v[72:75]
	v_mfma_f32_16x16x32_bf16 v[68:71], v[190:193], v[198:201], v[68:71]
	v_mfma_f32_16x16x32_bf16 v[56:59], v[176:179], v[206:209], v[56:59]
	v_mfma_f32_16x16x32_bf16 v[52:55], v[190:193], v[206:209], v[52:55]
	v_mfma_f32_16x16x32_bf16 v[40:43], v[176:179], v[224:227], v[40:43]
	v_mfma_f32_16x16x32_bf16 v[36:39], v[190:193], v[224:227], v[36:39]
	v_mfma_f32_16x16x32_bf16 v[24:27], v[176:179], v[232:235], v[24:27]
	v_mfma_f32_16x16x32_bf16 v[20:23], v[190:193], v[232:235], v[20:23]
	v_mfma_f32_16x16x32_bf16 v[72:75], v[180:183], v[202:205], v[72:75]
	v_mfma_f32_16x16x32_bf16 v[68:71], v[194:197], v[202:205], v[68:71]
	v_mfma_f32_16x16x32_bf16 v[56:59], v[180:183], v[220:223], v[56:59]
	v_mfma_f32_16x16x32_bf16 v[52:55], v[194:197], v[220:223], v[52:55]
	v_mfma_f32_16x16x32_bf16 v[40:43], v[180:183], v[228:231], v[40:43]
	v_mfma_f32_16x16x32_bf16 v[36:39], v[194:197], v[228:231], v[36:39]
	v_mfma_f32_16x16x32_bf16 v[24:27], v[180:183], v[236:239], v[24:27]
	v_mfma_f32_16x16x32_bf16 v[20:23], v[194:197], v[236:239], v[20:23]
	s_barrier
	s_add_i32 s60, s60, 2
	s_add_u32 s24, s24, 0x100
	s_addc_u32 s25, s25, 0
	s_add_u32 s23, s23, 0x100
	s_addc_u32 s35, s35, 0
	s_cmp_gt_u32 s60, 13
	s_cbranch_scc0 .LBB0_867
	s_and_b64 vcc, exec, s[10:11]
	s_cbranch_vccz .LBB0_870
	s_barrier

; #define PG8_STAGE(bufoff, gbase, voff) do { _Pragma("unroll") for (int _i = 0; _i < 2; ++_i) \
;         __builtin_amdgcn_global_load_lds((const unsigned*)((const char*)(gbase) + (voff)[_i]), (PG8_LAS unsigned*)(lds + (bufoff) + ldsw + _i * 8192), 16, 0, 0); } while (0)
; #define PG8_LDA(dst, b, h) do { _Pragma("unroll") for (int m = 0; m < 4; ++m) _Pragma("unroll") for (int k = 0; k < 2; ++k) dst[m][k] = *(const PG8_LAS bf16x8*)(lds + PG8_SA(b, h) + aoff + m * 2048 + k * 1024); } while (0)
; #define PG8_LDB(dst, b, h) do { _Pragma("unroll") for (int n = 0; n < 2; ++n) _Pragma("unroll") for (int k = 0; k < 2; ++k) dst[n][k] = *(const PG8_LAS bf16x8*)(lds + PG8_SB(b, h) + boff + n * 2048 + k * 1024); } while (0)
; #define PG8_MMA(ai, bj, At, Bt) do { __builtin_amdgcn_s_setprio(1); _Pragma("unroll") for (int m = 0; m < 4; ++m) _Pragma("unroll") for (int n = 0; n < 2; ++n) _Pragma("unroll") for (int k = 0; k < 2; ++k) \
;         acc[ai][bj][m][n] = __builtin_amdgcn_mfma_f32_16x16x32_bf16(Bt[n][k], At[m][k], acc[ai][bj][m][n], 0, 0, 0); __builtin_amdgcn_s_setprio(0); } while (0)
; #define PG8_WAIT_V(n) asm volatile("s_waitcnt vmcnt(" #n ")" ::: "memory")
; #define PG8_WAIT_L(n) asm volatile("s_waitcnt lgkmcnt(" #n ")" ::: "memory")
; template <class Epi, class Sched, bool ALIGN_EPI = false, bool SP2 = false>
; __device__ __forceinline__ void gemm_phase(PG8_LAS unsigned char* lds, const Gemm g, const Sched& S, const Epi& E) {
;     ...
;             const bool last = (t == nt - 2);
;             const char* a1 = cA + (size_t)(t + 1) * kstep;
;             const char* a2 = last ? nA : cA + (size_t)(t + 2) * kstep; const char* b2 = last ? nB : cB + (size_t)(t + 2) * kstep;
;             const char* a3 = a2 + kstep; const char* b3 = b2 + kstep;
;             if (last && has_next) S.a_ready(nxt);
;             if constexpr (SP2) {
;             PG8_LDB(B0, 0, 0); PG8_LDB(B1, 0, 1); PG8_SCHED; PG8_LDA(At, 0, 0); PG8_STAGE(PG8_SA(1, 1), a1 + hstep, voffA);
;             PG8_WAIT_V(8); PG8_WAIT_L(0); PG8_BAR; PG8_MMA(0, 0, At, B0); PG8_MMA(0, 1, At, B1); PG8_BAR; PG8_SCHED;
;             PG8_LDA(At, 0, 1); PG8_STAGE(PG8_SB(0, 0), b2, voffB); PG8_STAGE(PG8_SB(0, 1), b2 + hstep, voffB); PG8_STAGE(PG8_SA(0, 0), a2, voffA);
;             PG8_WAIT_V(8); PG8_WAIT_L(0); PG8_BAR; PG8_MMA(1, 0, At, B0); PG8_MMA(1, 1, At, B1); PG8_BAR; PG8_SCHED;
.LBB0_942:
	s_add_u32 s0, s10, 0xfff00080
	s_addc_u32 s1, s11, -1
	s_add_i32 s61, 0, 0x10000
	s_cmp_eq_u32 s60, 60
	s_cselect_b32 s13, s59, s1
	s_cselect_b32 s12, s62, s0
	s_cselect_b32 s1, s57, s35
	s_cselect_b32 s0, s22, s23
	s_add_i32 s63, 0, 0x14000
	v_add_u32_e32 v160, s61, v207
	v_add_u32_e32 v186, s63, v207
	ds_read_b128 v[148:151], v160
	ds_read_b128 v[152:155], v160 offset:1024
	ds_read_b128 v[156:159], v160 offset:2048
	ds_read_b128 v[160:163], v160 offset:3072
	ds_read_b128 v[164:167], v186
	ds_read_b128 v[168:171], v186 offset:1024
	ds_read_b128 v[172:175], v186 offset:2048
	ds_read_b128 v[190:193], v186 offset:3072
	v_lshl_add_u64 v[186:187], s[10:11], 0, v[180:181]
	s_add_i32 m0, s72, 0xc000
	ds_read_b128 v[194:197], v209
	ds_read_b128 v[198:201], v209 offset:1024
	ds_read_b128 v[202:205], v209 offset:2048
	ds_read_b128 v[220:223], v209 offset:3072
	ds_read_b128 v[224:227], v209 offset:4096
	ds_read_b128 v[228:231], v209 offset:5120
	ds_read_b128 v[232:235], v209 offset:6144
	ds_read_b128 v[236:239], v209 offset:7168
	global_load_lds_dwordx4 v[186:187], off
	v_lshl_add_u64 v[186:187], s[10:11], 0, v[182:183]
	s_add_i32 m0, s72, 0xe000
	s_nop 0
	global_load_lds_dwordx4 v[186:187], off
	s_waitcnt vmcnt(8)
	s_waitcnt lgkmcnt(0)
	s_barrier
	s_waitcnt lgkmcnt(0)
	v_mfma_f32_16x16x32_bf16 v[144:147], v[148:151], v[194:197], v[144:147]
	v_mfma_f32_16x16x32_bf16 v[140:143], v[156:159], v[194:197], v[140:143]
	v_mfma_f32_16x16x32_bf16 v[128:131], v[148:151], v[202:205], v[128:131]
	v_mfma_f32_16x16x32_bf16 v[124:127], v[156:159], v[202:205], v[124:127]
	v_mfma_f32_16x16x32_bf16 v[112:115], v[148:151], v[224:227], v[112:115]
	v_mfma_f32_16x16x32_bf16 v[108:111], v[156:159], v[224:227], v[108:111]
	v_mfma_f32_16x16x32_bf16 v[96:99], v[148:151], v[232:235], v[96:99]
	v_mfma_f32_16x16x32_bf16 v[92:95], v[156:159], v[232:235], v[92:95]
	v_mfma_f32_16x16x32_bf16 v[144:147], v[152:155], v[198:201], v[144:147]
	v_mfma_f32_16x16x32_bf16 v[140:143], v[160:163], v[198:201], v[140:143]
	v_mfma_f32_16x16x32_bf16 v[128:131], v[152:155], v[220:223], v[128:131]
	v_mfma_f32_16x16x32_bf16 v[124:127], v[160:163], v[220:223], v[124:127]
	v_mfma_f32_16x16x32_bf16 v[112:115], v[152:155], v[228:231], v[112:115]
	v_mfma_f32_16x16x32_bf16 v[108:111], v[160:163], v[228:231], v[108:111]
	v_mfma_f32_16x16x32_bf16 v[96:99], v[152:155], v[236:239], v[96:99]
	v_mfma_f32_16x16x32_bf16 v[92:95], v[160:163], v[236:239], v[92:95]
	v_mfma_f32_16x16x32_bf16 v[136:139], v[164:167], v[194:197], v[136:139]
	v_mfma_f32_16x16x32_bf16 v[132:135], v[172:175], v[194:197], v[132:135]
	v_mfma_f32_16x16x32_bf16 v[120:123], v[164:167], v[202:205], v[120:123]
	v_mfma_f32_16x16x32_bf16 v[116:119], v[172:175], v[202:205], v[116:119]
	v_mfma_f32_16x16x32_bf16 v[104:107], v[164:167], v[224:227], v[104:107]
	v_mfma_f32_16x16x32_bf16 v[100:103], v[172:175], v[224:227], v[100:103]
	v_mfma_f32_16x16x32_bf16 v[88:91], v[164:167], v[232:235], v[88:91]
	v_mfma_f32_16x16x32_bf16 v[84:87], v[172:175], v[232:235], v[84:87]
	v_mfma_f32_16x16x32_bf16 v[136:139], v[168:171], v[198:201], v[136:139]
	v_mfma_f32_16x16x32_bf16 v[132:135], v[190:193], v[198:201], v[132:135]
	v_mfma_f32_16x16x32_bf16 v[120:123], v[168:171], v[220:223], v[120:123]
	v_mfma_f32_16x16x32_bf16 v[116:119], v[190:193], v[220:223], v[116:119]
	v_mfma_f32_16x16x32_bf16 v[104:107], v[168:171], v[228:231], v[104:107]
	v_mfma_f32_16x16x32_bf16 v[100:103], v[190:193], v[228:231], v[100:103]
	v_mfma_f32_16x16x32_bf16 v[88:91], v[168:171], v[236:239], v[88:91]
	v_mfma_f32_16x16x32_bf16 v[84:87], v[190:193], v[236:239], v[84:87]
	s_barrier
	s_add_i32 s61, s61, s67
	v_lshl_add_u64 v[186:187], s[0:1], 0, v[0:1]
	s_mov_b32 m0, s61
	ds_read_b128 v[194:197], v209 offset:16384
	ds_read_b128 v[198:201], v209 offset:17408
	ds_read_b128 v[202:205], v209 offset:18432
	ds_read_b128 v[220:223], v209 offset:19456
	ds_read_b128 v[224:227], v209 offset:20480
	ds_read_b128 v[228:231], v209 offset:21504
	ds_read_b128 v[232:235], v209 offset:22528
	ds_read_b128 v[236:239], v209 offset:23552
	global_load_lds_dwordx4 v[186:187], off
	s_add_i32 m0, s61, 0x2000
	s_add_u32 s64, s0, 0x100000
	v_lshl_add_u64 v[210:211], s[0:1], 0, v[2:3]
	s_addc_u32 s65, s1, 0
	s_add_i32 s61, s63, s67
	global_load_lds_dwordx4 v[210:211], off
	v_lshl_add_u64 v[240:241], s[64:65], 0, v[0:1]
	s_mov_b32 m0, s61
	v_lshl_add_u64 v[242:243], s[12:13], 0, v[176:177]
	global_load_lds_dwordx4 v[240:241], off
	v_lshl_add_u64 v[240:241], s[64:65], 0, v[2:3]
	s_add_i32 m0, s61, 0x2000
	s_nop 0
	global_load_lds_dwordx4 v[240:241], off
	v_lshl_add_u64 v[240:241], s[12:13], 0, v[178:179]
	s_mov_b32 m0, s72
	s_nop 0
	global_load_lds_dwordx4 v[240:241], off
	s_mov_b32 m0, s73
	s_nop 0
	global_load_lds_dwordx4 v[242:243], off
	s_waitcnt vmcnt(8)
	s_waitcnt lgkmcnt(0)
	s_barrier
; #define PG8_STAGE(bufoff, gbase, voff) do { _Pragma("unroll") for (int _i = 0; _i < 2; ++_i) \
;         __builtin_amdgcn_global_load_lds((const unsigned*)((const char*)(gbase) + (voff)[_i]), (PG8_LAS unsigned*)(lds + (bufoff) + ldsw + _i * 8192), 16, 0, 0); } while (0)
; #define PG8_LDA(dst, b, h) do { _Pragma("unroll") for (int m = 0; m < 4; ++m) _Pragma("unroll") for (int k = 0; k < 2; ++k) dst[m][k] = *(const PG8_LAS bf16x8*)(lds + PG8_SA(b, h) + aoff + m * 2048 + k * 1024); } while (0)
; #define PG8_LDB(dst, b, h) do { _Pragma("unroll") for (int n = 0; n < 2; ++n) _Pragma("unroll") for (int k = 0; k < 2; ++k) dst[n][k] = *(const PG8_LAS bf16x8*)(lds + PG8_SB(b, h) + boff + n * 2048 + k * 1024); } while (0)
; #define PG8_MMA(ai, bj, At, Bt) do { __builtin_amdgcn_s_setprio(1); _Pragma("unroll") for (int m = 0; m < 4; ++m) _Pragma("unroll") for (int n = 0; n < 2; ++n) _Pragma("unroll") for (int k = 0; k < 2; ++k) \
;         acc[ai][bj][m][n] = __builtin_amdgcn_mfma_f32_16x16x32_bf16(Bt[n][k], At[m][k], acc[ai][bj][m][n], 0, 0, 0); __builtin_amdgcn_s_setprio(0); } while (0)
; #define PG8_WAIT_V(n) asm volatile("s_waitcnt vmcnt(" #n ")" ::: "memory")
; #define PG8_WAIT_L(n) asm volatile("s_waitcnt lgkmcnt(" #n ")" ::: "memory")
; #define PG8_BAR __builtin_amdgcn_s_barrier()
; #define PG8_SCHED __builtin_amdgcn_sched_barrier(0)
; template <class Epi, class Sched, bool ALIGN_EPI = false, bool SP2 = false>
; __device__ __forceinline__ void gemm_phase(PG8_LAS unsigned char* lds, const Gemm g, const Sched& S, const Epi& E) {
;     ...
;             PG8_WAIT_V(8); PG8_WAIT_L(0); PG8_BAR; PG8_MMA(1, 0, At, B0); PG8_MMA(1, 1, At, B1); PG8_BAR; PG8_SCHED;
;             PG8_LDB(B0, 1, 0); PG8_LDB(B1, 1, 1); PG8_SCHED; PG8_LDA(At, 1, 0); PG8_STAGE(PG8_SA(0, 1), a2 + hstep, voffA);
;             PG8_WAIT_V(8); PG8_WAIT_L(0); PG8_BAR; PG8_MMA(0, 0, At, B0); PG8_MMA(0, 1, At, B1); PG8_BAR; PG8_SCHED;
	s_waitcnt lgkmcnt(0)
	v_mfma_f32_16x16x32_bf16 v[80:83], v[148:151], v[194:197], v[80:83]
	v_mfma_f32_16x16x32_bf16 v[76:79], v[156:159], v[194:197], v[76:79]
	v_mfma_f32_16x16x32_bf16 v[64:67], v[148:151], v[202:205], v[64:67]
	v_mfma_f32_16x16x32_bf16 v[60:63], v[156:159], v[202:205], v[60:63]
	v_mfma_f32_16x16x32_bf16 v[48:51], v[148:151], v[224:227], v[48:51]
	v_mfma_f32_16x16x32_bf16 v[44:47], v[156:159], v[224:227], v[44:47]
	v_mfma_f32_16x16x32_bf16 v[32:35], v[148:151], v[232:235], v[32:35]
	v_mfma_f32_16x16x32_bf16 v[28:31], v[156:159], v[232:235], v[28:31]
	v_mfma_f32_16x16x32_bf16 v[80:83], v[152:155], v[198:201], v[80:83]
	v_mfma_f32_16x16x32_bf16 v[76:79], v[160:163], v[198:201], v[76:79]
	v_mfma_f32_16x16x32_bf16 v[64:67], v[152:155], v[220:223], v[64:67]
	v_mfma_f32_16x16x32_bf16 v[60:63], v[160:163], v[220:223], v[60:63]
	v_mfma_f32_16x16x32_bf16 v[48:51], v[152:155], v[228:231], v[48:51]
	v_mfma_f32_16x16x32_bf16 v[44:47], v[160:163], v[228:231], v[44:47]
	v_mfma_f32_16x16x32_bf16 v[32:35], v[152:155], v[236:239], v[32:35]
	v_mfma_f32_16x16x32_bf16 v[28:31], v[160:163], v[236:239], v[28:31]
	v_mfma_f32_16x16x32_bf16 v[72:75], v[164:167], v[194:197], v[72:75]
	v_mfma_f32_16x16x32_bf16 v[68:71], v[172:175], v[194:197], v[68:71]
	v_mfma_f32_16x16x32_bf16 v[56:59], v[164:167], v[202:205], v[56:59]
	v_mfma_f32_16x16x32_bf16 v[52:55], v[172:175], v[202:205], v[52:55]
	v_mfma_f32_16x16x32_bf16 v[40:43], v[164:167], v[224:227], v[40:43]
	v_mfma_f32_16x16x32_bf16 v[36:39], v[172:175], v[224:227], v[36:39]
	v_mfma_f32_16x16x32_bf16 v[24:27], v[164:167], v[232:235], v[24:27]
	v_mfma_f32_16x16x32_bf16 v[20:23], v[172:175], v[232:235], v[20:23]
	v_mfma_f32_16x16x32_bf16 v[72:75], v[168:171], v[198:201], v[72:75]
	v_mfma_f32_16x16x32_bf16 v[68:71], v[190:193], v[198:201], v[68:71]
	v_mfma_f32_16x16x32_bf16 v[56:59], v[168:171], v[220:223], v[56:59]
	v_mfma_f32_16x16x32_bf16 v[52:55], v[190:193], v[220:223], v[52:55]
	v_mfma_f32_16x16x32_bf16 v[40:43], v[168:171], v[228:231], v[40:43]
	v_mfma_f32_16x16x32_bf16 v[36:39], v[190:193], v[228:231], v[36:39]
	v_mfma_f32_16x16x32_bf16 v[24:27], v[168:171], v[236:239], v[24:27]
	v_mfma_f32_16x16x32_bf16 v[20:23], v[190:193], v[236:239], v[20:23]
	s_barrier
	s_add_i32 s61, 0, 0x18000
	s_add_i32 s63, 0, 0x1c000
	v_add_u32_e32 v160, s61, v207
	v_add_u32_e32 v188, s63, v207
	ds_read_b128 v[148:151], v160
	ds_read_b128 v[152:155], v160 offset:1024
	ds_read_b128 v[156:159], v160 offset:2048
	ds_read_b128 v[160:163], v160 offset:3072
	ds_read_b128 v[164:167], v188
	ds_read_b128 v[168:171], v188 offset:1024
	ds_read_b128 v[172:175], v188 offset:2048
	ds_read_b128 v[190:193], v188 offset:3072
	s_add_u32 s12, s12, 0x100000
	s_addc_u32 s13, s13, 0
	s_mov_b32 m0, s74
	v_lshl_add_u64 v[244:245], s[12:13], 0, v[178:179]
	ds_read_b128 v[194:197], v209 offset:32768
	ds_read_b128 v[198:201], v209 offset:33792
	ds_read_b128 v[202:205], v209 offset:34816
	ds_read_b128 v[220:223], v209 offset:35840
	ds_read_b128 v[224:227], v209 offset:36864
	ds_read_b128 v[228:231], v209 offset:37888
	ds_read_b128 v[232:235], v209 offset:38912
	ds_read_b128 v[236:239], v209 offset:39936
	global_load_lds_dwordx4 v[244:245], off
	v_lshl_add_u64 v[244:245], s[12:13], 0, v[176:177]
	s_mov_b32 m0, s75
	s_nop 0
	global_load_lds_dwordx4 v[244:245], off
	s_waitcnt vmcnt(8)
	s_waitcnt lgkmcnt(0)
	s_barrier
	s_waitcnt lgkmcnt(0)
	v_mfma_f32_16x16x32_bf16 v[144:147], v[148:151], v[194:197], v[144:147]
	v_mfma_f32_16x16x32_bf16 v[140:143], v[156:159], v[194:197], v[140:143]
	v_mfma_f32_16x16x32_bf16 v[128:131], v[148:151], v[202:205], v[128:131]
	v_mfma_f32_16x16x32_bf16 v[124:127], v[156:159], v[202:205], v[124:127]
	v_mfma_f32_16x16x32_bf16 v[112:115], v[148:151], v[224:227], v[112:115]
	v_mfma_f32_16x16x32_bf16 v[108:111], v[156:159], v[224:227], v[108:111]
	v_mfma_f32_16x16x32_bf16 v[96:99], v[148:151], v[232:235], v[96:99]
	v_mfma_f32_16x16x32_bf16 v[92:95], v[156:159], v[232:235], v[92:95]
	v_mfma_f32_16x16x32_bf16 v[144:147], v[152:155], v[198:201], v[144:147]
	v_mfma_f32_16x16x32_bf16 v[140:143], v[160:163], v[198:201], v[140:143]
	v_mfma_f32_16x16x32_bf16 v[128:131], v[152:155], v[220:223], v[128:131]
	v_mfma_f32_16x16x32_bf16 v[124:127], v[160:163], v[220:223], v[124:127]
	v_mfma_f32_16x16x32_bf16 v[112:115], v[152:155], v[228:231], v[112:115]
	v_mfma_f32_16x16x32_bf16 v[108:111], v[160:163], v[228:231], v[108:111]
	v_mfma_f32_16x16x32_bf16 v[96:99], v[152:155], v[236:239], v[96:99]
	v_mfma_f32_16x16x32_bf16 v[92:95], v[160:163], v[236:239], v[92:95]
	v_mfma_f32_16x16x32_bf16 v[136:139], v[164:167], v[194:197], v[136:139]
	v_mfma_f32_16x16x32_bf16 v[132:135], v[172:175], v[194:197], v[132:135]
	v_mfma_f32_16x16x32_bf16 v[120:123], v[164:167], v[202:205], v[120:123]
	v_mfma_f32_16x16x32_bf16 v[116:119], v[172:175], v[202:205], v[116:119]
	v_mfma_f32_16x16x32_bf16 v[104:107], v[164:167], v[224:227], v[104:107]
	v_mfma_f32_16x16x32_bf16 v[100:103], v[172:175], v[224:227], v[100:103]
	v_mfma_f32_16x16x32_bf16 v[88:91], v[164:167], v[232:235], v[88:91]
	v_mfma_f32_16x16x32_bf16 v[84:87], v[172:175], v[232:235], v[84:87]
	v_mfma_f32_16x16x32_bf16 v[136:139], v[168:171], v[198:201], v[136:139]
	v_mfma_f32_16x16x32_bf16 v[132:135], v[190:193], v[198:201], v[132:135]
	v_mfma_f32_16x16x32_bf16 v[120:123], v[168:171], v[220:223], v[120:123]
	v_mfma_f32_16x16x32_bf16 v[116:119], v[190:193], v[220:223], v[116:119]
	v_mfma_f32_16x16x32_bf16 v[104:107], v[168:171], v[228:231], v[104:107]
	v_mfma_f32_16x16x32_bf16 v[100:103], v[190:193], v[228:231], v[100:103]
	v_mfma_f32_16x16x32_bf16 v[88:91], v[168:171], v[236:239], v[88:91]
	v_mfma_f32_16x16x32_bf16 v[84:87], v[190:193], v[236:239], v[84:87]
	s_barrier
; #define PG8_STAGE(bufoff, gbase, voff) do { _Pragma("unroll") for (int _i = 0; _i < 2; ++_i) \
;         __builtin_amdgcn_global_load_lds((const unsigned*)((const char*)(gbase) + (voff)[_i]), (PG8_LAS unsigned*)(lds + (bufoff) + ldsw + _i * 8192), 16, 0, 0); } while (0)
; #define PG8_LDA(dst, b, h) do { _Pragma("unroll") for (int m = 0; m < 4; ++m) _Pragma("unroll") for (int k = 0; k < 2; ++k) dst[m][k] = *(const PG8_LAS bf16x8*)(lds + PG8_SA(b, h) + aoff + m * 2048 + k * 1024); } while (0)
; #define PG8_MMA(ai, bj, At, Bt) do { __builtin_amdgcn_s_setprio(1); _Pragma("unroll") for (int m = 0; m < 4; ++m) _Pragma("unroll") for (int n = 0; n < 2; ++n) _Pragma("unroll") for (int k = 0; k < 2; ++k) \
;         acc[ai][bj][m][n] = __builtin_amdgcn_mfma_f32_16x16x32_bf16(Bt[n][k], At[m][k], acc[ai][bj][m][n], 0, 0, 0); __builtin_amdgcn_s_setprio(0); } while (0)
; #define PG8_WAIT_V(n) asm volatile("s_waitcnt vmcnt(" #n ")" ::: "memory")
; #define PG8_WAIT_L(n) asm volatile("s_waitcnt lgkmcnt(" #n ")" ::: "memory")
; #define PG8_BAR __builtin_amdgcn_s_barrier()
; #define PG8_SCHED __builtin_amdgcn_sched_barrier(0)
; template <class Epi, class Sched, bool ALIGN_EPI = false, bool SP2 = false>
; __device__ __forceinline__ void gemm_phase(PG8_LAS unsigned char* lds, const Gemm g, const Sched& S, const Epi& E) {
;     ...
;             PG8_LDA(At, 1, 1); PG8_STAGE(PG8_SB(1, 0), b3, voffB); PG8_STAGE(PG8_SB(1, 1), b3 + hstep, voffB); PG8_STAGE(PG8_SA(1, 0), a3, voffA);
;             PG8_WAIT_V(8); PG8_WAIT_L(0); PG8_BAR; PG8_MMA(1, 0, At, B0); PG8_MMA(1, 1, At, B1); PG8_BAR; PG8_SCHED;
	s_add_i32 s12, s61, s67
	v_lshl_add_u64 v[186:187], v[186:187], 0, s[20:21]
	s_mov_b32 m0, s12
	ds_read_b128 v[194:197], v209 offset:49152
	ds_read_b128 v[198:201], v209 offset:50176
	ds_read_b128 v[202:205], v209 offset:51200
	ds_read_b128 v[220:223], v209 offset:52224
	ds_read_b128 v[224:227], v209 offset:53248
	ds_read_b128 v[228:231], v209 offset:54272
	ds_read_b128 v[232:235], v209 offset:55296
	ds_read_b128 v[236:239], v209 offset:56320
	global_load_lds_dwordx4 v[186:187], off
	s_add_i32 m0, s12, 0x2000
	s_add_u32 s0, s0, 0x100080
	v_lshl_add_u64 v[186:187], v[210:211], 0, s[20:21]
	s_addc_u32 s1, s1, 0
	s_add_i32 s12, s63, s67
	global_load_lds_dwordx4 v[186:187], off
	v_lshl_add_u64 v[186:187], s[0:1], 0, v[0:1]
	s_mov_b32 m0, s12
	s_nop 0
	global_load_lds_dwordx4 v[186:187], off
	v_lshl_add_u64 v[186:187], s[0:1], 0, v[2:3]
	s_add_i32 m0, s12, 0x2000
	s_nop 0
	global_load_lds_dwordx4 v[186:187], off
	v_lshl_add_u64 v[186:187], v[240:241], 0, s[20:21]
	s_mov_b32 m0, s93
	s_nop 0
	global_load_lds_dwordx4 v[186:187], off
	v_lshl_add_u64 v[186:187], v[242:243], 0, s[20:21]
	s_mov_b32 m0, s94
	s_nop 0
	global_load_lds_dwordx4 v[186:187], off
	s_waitcnt vmcnt(8)
	s_waitcnt lgkmcnt(0)
	s_barrier
	s_waitcnt lgkmcnt(0)
	v_mfma_f32_16x16x32_bf16 v[80:83], v[148:151], v[194:197], v[80:83]
	v_mfma_f32_16x16x32_bf16 v[76:79], v[156:159], v[194:197], v[76:79]
	v_mfma_f32_16x16x32_bf16 v[64:67], v[148:151], v[202:205], v[64:67]
	v_mfma_f32_16x16x32_bf16 v[60:63], v[156:159], v[202:205], v[60:63]
	v_mfma_f32_16x16x32_bf16 v[48:51], v[148:151], v[224:227], v[48:51]
	v_mfma_f32_16x16x32_bf16 v[44:47], v[156:159], v[224:227], v[44:47]
	v_mfma_f32_16x16x32_bf16 v[32:35], v[148:151], v[232:235], v[32:35]
	v_mfma_f32_16x16x32_bf16 v[28:31], v[156:159], v[232:235], v[28:31]
	v_mfma_f32_16x16x32_bf16 v[80:83], v[152:155], v[198:201], v[80:83]
	v_mfma_f32_16x16x32_bf16 v[76:79], v[160:163], v[198:201], v[76:79]
	v_mfma_f32_16x16x32_bf16 v[64:67], v[152:155], v[220:223], v[64:67]
	v_mfma_f32_16x16x32_bf16 v[60:63], v[160:163], v[220:223], v[60:63]
	v_mfma_f32_16x16x32_bf16 v[48:51], v[152:155], v[228:231], v[48:51]
	v_mfma_f32_16x16x32_bf16 v[44:47], v[160:163], v[228:231], v[44:47]
	v_mfma_f32_16x16x32_bf16 v[32:35], v[152:155], v[236:239], v[32:35]
	v_mfma_f32_16x16x32_bf16 v[28:31], v[160:163], v[236:239], v[28:31]
	v_mfma_f32_16x16x32_bf16 v[72:75], v[164:167], v[194:197], v[72:75]
	v_mfma_f32_16x16x32_bf16 v[68:71], v[172:175], v[194:197], v[68:71]
	v_mfma_f32_16x16x32_bf16 v[56:59], v[164:167], v[202:205], v[56:59]
	v_mfma_f32_16x16x32_bf16 v[52:55], v[172:175], v[202:205], v[52:55]
	v_mfma_f32_16x16x32_bf16 v[40:43], v[164:167], v[224:227], v[40:43]
	v_mfma_f32_16x16x32_bf16 v[36:39], v[172:175], v[224:227], v[36:39]
	v_mfma_f32_16x16x32_bf16 v[24:27], v[164:167], v[232:235], v[24:27]
	v_mfma_f32_16x16x32_bf16 v[20:23], v[172:175], v[232:235], v[20:23]
	v_mfma_f32_16x16x32_bf16 v[72:75], v[168:171], v[198:201], v[72:75]
	v_mfma_f32_16x16x32_bf16 v[68:71], v[190:193], v[198:201], v[68:71]
	v_mfma_f32_16x16x32_bf16 v[56:59], v[168:171], v[220:223], v[56:59]
	v_mfma_f32_16x16x32_bf16 v[52:55], v[190:193], v[220:223], v[52:55]
	v_mfma_f32_16x16x32_bf16 v[40:43], v[168:171], v[228:231], v[40:43]
	v_mfma_f32_16x16x32_bf16 v[36:39], v[190:193], v[228:231], v[36:39]
	v_mfma_f32_16x16x32_bf16 v[24:27], v[168:171], v[236:239], v[24:27]
	v_mfma_f32_16x16x32_bf16 v[20:23], v[190:193], v[236:239], v[20:23]
	s_barrier
	s_add_i32 s60, s60, 2
	s_add_u32 s10, s10, 0x100
	s_addc_u32 s11, s11, 0
	s_add_u32 s23, s23, 0x100
	s_addc_u32 s35, s35, 0
	s_cmp_gt_u32 s60, 61
	s_cbranch_scc0 .LBB0_942
	s_and_b64 vcc, exec, s[52:53]
	s_cbranch_vccz .LBB0_945
	s_barrier
